# v10 plus hoisted x loads in residual epilogues and pipelined retention state loads
# baseline (speedup 1.0000x reference)
; #define MFMA32(a, b, c) __builtin_amdgcn_mfma_f32_32x32x16_bf16((a), (b), (c), 0, 0, 0)
; DI int get_tid() { int t = threadIdx.x; asm volatile("" : "+v"(t)); return t; }
; DI void ret_attn_item(const Params& P, const WsPtrs& W, int layer, int item, unsigned char* smem) {
;   const int w = get_tid() >> 6, lane = get_tid() & 63;
;   int r = lane & 31, h = lane >> 5;
;   int bh = item >> 4, qb = item & 15, bl = bh >> 3, hh = bh & 7;
;   int q0 = qb * 256 + 32 * w;
;   size_t tokb = (size_t)bl * 4096;
;   float dl = log2f(1.f - exp2f(-5.f - (float)hh));
;   f32x16 o[4]; float l;
;   {
;     const u16* Qw = W.Y + (tokb + q0) * LDY + O_DQ + hh * 64;
;     bf16x8 qf[4];
; #pragma unroll
;     for (int ks = 0; ks < 4; ++ks) qf[ks] = *(const bf16x8*)(Qw + (size_t)r * LDY + 16 * ks + 8 * h);
;     const float nrel = (float)(q0 - qb * 256 + r);
; #pragma unroll
;     for (int dir = 0; dir < 2; ++dir) {
;       const u16* st = W.PF + ((size_t)((bh * 16 + qb) * 2 + dir)) * 8192;
;       const float sc = __builtin_amdgcn_exp2f(dl * (dir == 0 ? nrel + 1.f : 256.f - nrel));
; #pragma unroll
;       for (int dt = 0; dt < 4; ++dt) {
;         f32x16 tq;
; #pragma unroll
;         for (int e = 0; e < 16; ++e) tq[e] = 0.f;
; #pragma unroll
;         for (int ks = 0; ks < 4; ++ks) {
;           bf16x8 af = *(const bf16x8*)(st + (32 * dt + r) * 64 + 16 * ks + 8 * h);
;           tq = MFMA32(af, qf[ks], tq);
;         }
; #pragma unroll
;         for (int e = 0; e < 16; ++e) o[dt][e] = (dir == 0 ? 0.f : o[dt][e]) + sc * tq[e];
;       }
;     }
;   }
.LBB0_545:
	s_or_b64 exec, exec, s[4:5]
	s_waitcnt lgkmcnt(0)
	s_barrier
	ds_read_b32 v0, v1 offset:48
	v_readlane_b32 s2, v254, 24
	s_mov_b64 s[4:5], -1
	s_waitcnt lgkmcnt(0)
	v_readfirstlane_b32 s18, v0
	v_cmp_le_i32_e32 vcc, s2, v0
	s_cbranch_vccnz .LBB0_540
	v_readlane_b32 s2, v254, 28
	s_cmp_ge_i32 s18, s2
	s_cbranch_scc0 .LBB0_612
	v_readlane_b32 s2, v254, 22
	s_cmp_ge_i32 s18, s2
	s_cbranch_scc0 .LBB0_555
	v_readlane_b32 s2, v254, 25
	s_add_i32 s19, s18, s2
	v_readlane_b32 s2, v254, 23
	s_cmp_ge_i32 s18, s2
	s_cbranch_scc0 .LBB0_556
	v_readlane_b32 s4, v253, 10
	s_mov_b32 s10, s4
	v_readlane_b32 s2, v254, 9
	s_ashr_i32 s11, s10, 31
	s_sub_i32 s2, s19, s2
	s_lshl_b64 s[8:9], s[10:11], 14
	s_add_u32 s4, s62, s8
	s_addc_u32 s5, s63, s9
	s_add_u32 s6, s4, 0x7046100
	s_addc_u32 s7, s5, 0
	s_lshl_b64 s[12:13], s[10:11], 23
	s_mul_i32 s5, s10, 0x7e00000
	s_mul_hi_i32 s4, s10, 0x7e00000
	s_add_u32 s23, s6, s5
	s_addc_u32 s22, s7, s4
	s_mul_i32 s4, s10, 0x2800000
	s_lshl_b64 s[14:15], s[10:11], 25
	s_lshl_b64 s[16:17], s[10:11], 18
	s_mul_hi_i32 s5, s10, 0x2800000
	s_add_u32 s4, s23, s4
	s_addc_u32 s5, s22, s5
	s_add_u32 s14, s4, s14
	s_addc_u32 s15, s5, s15
	s_add_u32 s12, s14, s12
	s_addc_u32 s13, s15, s13
	s_add_u32 s12, s12, s16
	s_addc_u32 s13, s13, s17
	s_add_u32 s12, s12, s16
	s_addc_u32 s13, s13, s17
	s_add_u32 s14, s12, s16
	s_addc_u32 s15, s13, s17
	s_lshl_b64 s[12:13], s[10:11], 21
	s_add_u32 s24, s14, s12
	s_addc_u32 s25, s15, s13
	s_lshr_b32 s2, s2, 1
	s_and_b32 s20, s2, 0xffffff8
	v_mov_b32_e32 v0, v250
	s_or_b32 s11, s20, s81
	s_and_b32 s21, s19, 15
	s_lshl_b32 s2, s11, 4
	v_ashrrev_i32_e32 v8, 1, v0
	s_bfe_i32 s12, s11, 0x1c0000
	s_bfe_i32 s14, s11, 0x190003
	s_lshl_b32 s11, s21, 8
	v_and_b32_e32 v0, 0xffffffe0, v8
	s_waitcnt vmcnt(0)
	v_add_u32_e32 v126, s11, v0
	s_ashr_i32 s15, s14, 31
	s_lshl_b64 s[16:17], s[14:15], 12
	v_ashrrev_i32_e32 v127, 31, v126
	v_lshl_add_u64 v[2:3], s[16:17], 0, v[126:127]
	v_mov_b64_e32 v[4:5], s[6:7]
	v_readlane_b32 s26, v255, 48
	v_mov_b32_e32 v6, v250
	v_mad_u64_u32 v[4:5], s[16:17], v2, s33, v[4:5]
	v_readlane_b32 s27, v255, 49
	v_mad_i32_i24 v5, v3, s33, v5
	v_and_b32_e32 v7, 31, v6
	s_mov_b32 s27, s3
	v_lshl_add_u64 v[2:3], v[4:5], 0, s[26:27]
	s_mov_b64 s[16:17], 0x3000
	v_mul_u32_u24_e32 v0, 0x3300, v7
	v_lshl_add_u64 v[98:99], v[2:3], 0, s[16:17]
	v_lshlrev_b32_e32 v0, 1, v0
	v_lshl_add_u64 v[2:3], v[98:99], 0, v[0:1]
	v_lshrrev_b32_e32 v0, 1, v6
	v_and_b32_e32 v0, 16, v0
	v_lshl_add_u64 v[2:3], v[2:3], 0, v[0:1]
	s_movk_i32 s13, 0xffe0
	global_load_dwordx4 v[94:97], v[2:3], off
	global_load_dwordx4 v[90:93], v[2:3], off offset:32
	global_load_dwordx4 v[86:89], v[2:3], off offset:64
	global_load_dwordx4 v[82:85], v[2:3], off offset:96
	v_bfi_b32 v2, s13, v8, v6
	v_cvt_f32_i32_e32 v2, v2
	s_or_b32 s2, s2, s21
	s_lshl_b32 s16, s2, 1
	s_ashr_i32 s17, s16, 31
	v_add_f32_e32 v3, 1.0, v2
	v_lshl_add_u64 v[70:71], s[24:25], 0, v[0:1]
	s_lshl_b64 s[24:25], s[16:17], 14
	v_mul_f32_e32 v0, v222, v3
	v_exp_f32_e32 v100, v0
	v_lshl_add_u64 v[54:55], v[70:71], 0, s[24:25]
	v_lshlrev_b32_e32 v0, 7, v7
	v_lshl_add_u64 v[22:23], v[54:55], 0, v[0:1]
	v_sub_f32_e32 v74, 0x43800000, v2
	global_load_dwordx4 v[132:135], v[22:23], off
	global_load_dwordx4 v[136:139], v[22:23], off offset:32
	s_nop 0
	s_nop 0
	v_or_b32_e32 v110, 0x1000, v0
	v_mov_b32_e32 v111, v1
	v_lshl_add_u64 v[38:39], v[54:55], 0, v[110:111]
	global_load_dwordx4 v[140:143], v[38:39], off offset:32
	global_load_dwordx4 v[144:147], v[22:23], off offset:64
	v_or_b32_e32 v108, 0x2000, v0
	v_mov_b32_e32 v109, v1
	v_lshl_add_u64 v[56:57], v[54:55], 0, v[108:109]
	global_load_dwordx4 v[148:151], v[56:57], off offset:32
	v_or_b32_e32 v104, 0x3000, v0
	v_mov_b32_e32 v105, v1
	v_lshl_add_u64 v[72:73], v[54:55], 0, v[104:105]
	global_load_dwordx4 v[152:155], v[72:73], off offset:32
	s_or_b32 s16, s16, 1
	s_ashr_i32 s17, s16, 31
	s_lshl_b64 s[16:17], s[16:17], 14
	v_lshl_add_u64 v[106:107], v[70:71], 0, s[16:17]
	v_lshl_add_u64 v[116:117], v[106:107], 0, v[0:1]
	global_load_dwordx4 v[156:159], v[116:117], off offset:32
	global_load_dwordx4 v[160:163], v[22:23], off offset:96
	global_load_dwordx4 v[164:167], v[38:39], off
	global_load_dwordx4 v[168:171], v[38:39], off offset:64
	v_lshl_add_u64 v[104:105], v[106:107], 0, v[104:105]
	s_mul_i32 s16, s14, 0x6600000
	s_mul_hi_i32 s15, s14, 0x6600000
	s_add_u32 s13, s6, s16
	s_addc_u32 s14, s7, s15
	s_add_u32 s13, s13, s26
	s_mov_b32 s24, s26
	s_addc_u32 s14, s14, 0
	v_writelane_b32 v255, s24, 48
	s_add_u32 s17, s13, 0x3400
	s_waitcnt vmcnt(9)
	v_mfma_f32_32x32x16_bf16 v[2:17], v[132:135], v[94:97], 0
	global_load_dwordx4 v[172:175], v[38:39], off offset:96
	s_nop 0
	v_writelane_b32 v255, s25, 49
	s_addc_u32 s24, s14, 0
	s_ashr_i32 s13, s12, 31
	s_lshl_b64 s[12:13], s[12:13], 20
	s_add_u32 s14, s23, s12
	s_movk_i32 s12, 0xcd48
	s_waitcnt vmcnt(9)
	v_mfma_f32_32x32x16_bf16 v[2:17], v[136:139], v[90:93], v[2:17]
	global_load_dwordx4 v[176:179], v[56:57], off
	s_nop 0
	s_addc_u32 s22, s22, s13
	s_lshl_b32 s25, s21, 9
	s_mul_i32 s21, s21, 0x660000
	s_nop 0
	s_nop 0
	s_nop 0
	s_waitcnt vmcnt(8)
	v_mfma_f32_32x32x16_bf16 v[2:17], v[144:147], v[86:89], v[2:17]
	global_load_dwordx4 v[180:183], v[56:57], off offset:64
	s_nop 0
	s_waitcnt vmcnt(5)
	v_mfma_f32_32x32x16_bf16 v[2:17], v[160:163], v[82:85], v[2:17]
	global_load_dwordx4 v[184:187], v[56:57], off offset:96
	s_nop 0
	s_nop 10
	v_pk_fma_f32 v[2:3], v[100:101], v[2:3], 0 op_sel_hi:[0,1,0]
	s_waitcnt vmcnt(5)
; #define MFMA32(a, b, c) __builtin_amdgcn_mfma_f32_32x32x16_bf16((a), (b), (c), 0, 0, 0)
; DI void ret_attn_item(const Params& P, const WsPtrs& W, int layer, int item, unsigned char* smem) {
;     ...
;       for (int dt = 0; dt < 4; ++dt) {
;         f32x16 tq;
; #pragma unroll
;         for (int e = 0; e < 16; ++e) tq[e] = 0.f;
; #pragma unroll
;         for (int ks = 0; ks < 4; ++ks) {
;           bf16x8 af = *(const bf16x8*)(st + (32 * dt + r) * 64 + 16 * ks + 8 * h);
;           tq = MFMA32(af, qf[ks], tq);
;         }
; #pragma unroll
;         for (int e = 0; e < 16; ++e) o[dt][e] = (dir == 0 ? 0.f : o[dt][e]) + sc * tq[e];
;       }
	v_mfma_f32_32x32x16_bf16 v[18:33], v[164:167], v[94:97], 0
	global_load_dwordx4 v[132:135], v[72:73], off
	v_fma_f32 v4, v100, v4, 0
	v_fma_f32 v5, v100, v5, 0
	v_fma_f32 v6, v100, v6, 0
	v_fma_f32 v7, v100, v7, 0
	v_fma_f32 v8, v100, v8, 0
	v_fma_f32 v9, v100, v9, 0
	v_pk_fma_f32 v[10:11], v[100:101], v[10:11], 0 op_sel_hi:[0,1,0]
	v_pk_fma_f32 v[12:13], v[100:101], v[12:13], 0 op_sel_hi:[0,1,0]
	v_pk_fma_f32 v[14:15], v[100:101], v[14:15], 0 op_sel_hi:[0,1,0]
	v_mul_f32_e32 v16, v100, v16
	v_mfma_f32_32x32x16_bf16 v[18:33], v[140:143], v[90:93], v[18:33]
	global_load_dwordx4 v[136:139], v[72:73], off offset:64
	s_nop 0
	s_waitcnt vmcnt(6)
	v_mfma_f32_32x32x16_bf16 v[18:33], v[168:171], v[86:89], v[18:33]
	global_load_dwordx4 v[144:147], v[72:73], off offset:96
	s_nop 0
	s_waitcnt vmcnt(6)
	v_mfma_f32_32x32x16_bf16 v[18:33], v[172:175], v[82:85], v[18:33]
	global_load_dwordx4 v[160:163], v[116:117], off
	s_nop 0
	s_nop 10
	v_mul_f32_e32 v32, v100, v32
	s_waitcnt vmcnt(6)
	v_mfma_f32_32x32x16_bf16 v[34:49], v[176:179], v[94:97], 0
	global_load_dwordx4 v[164:167], v[116:117], off offset:64
	v_mfma_f32_32x32x16_bf16 v[34:49], v[148:151], v[90:93], v[34:49]
	global_load_dwordx4 v[140:143], v[116:117], off offset:96
	s_nop 0
	s_waitcnt vmcnt(7)
	v_mfma_f32_32x32x16_bf16 v[34:49], v[180:183], v[86:89], v[34:49]
	s_nop 0
	s_waitcnt vmcnt(6)
	v_mfma_f32_32x32x16_bf16 v[34:49], v[184:187], v[82:85], v[34:49]
	s_nop 0
	s_nop 10
	v_mul_f32_e32 v48, v100, v48
	s_waitcnt vmcnt(5)
	v_mfma_f32_32x32x16_bf16 v[50:65], v[132:135], v[94:97], 0
	v_mfma_f32_32x32x16_bf16 v[50:65], v[152:155], v[90:93], v[50:65]
	s_nop 0
	s_waitcnt vmcnt(4)
	v_mfma_f32_32x32x16_bf16 v[50:65], v[136:139], v[86:89], v[50:65]
	s_nop 0
	s_waitcnt vmcnt(3)
	v_mfma_f32_32x32x16_bf16 v[50:65], v[144:147], v[82:85], v[50:65]
	v_mul_f32_e32 v66, v222, v74
	v_exp_f32_e32 v102, v66
	s_nop 0
	v_mov_b32_e32 v101, v102
	v_pk_fma_f32 v[18:19], v[100:101], v[18:19], 0 op_sel_hi:[0,1,0]
	v_pk_fma_f32 v[20:21], v[100:101], v[20:21], 0 op_sel_hi:[0,1,0]
	v_pk_fma_f32 v[22:23], v[100:101], v[22:23], 0 op_sel_hi:[0,1,0]
	v_pk_fma_f32 v[24:25], v[100:101], v[24:25], 0 op_sel_hi:[0,1,0]
	v_pk_fma_f32 v[26:27], v[100:101], v[26:27], 0 op_sel_hi:[0,1,0]
	v_pk_fma_f32 v[28:29], v[100:101], v[28:29], 0 op_sel_hi:[0,1,0]
	v_pk_fma_f32 v[30:31], v[100:101], v[30:31], 0 op_sel_hi:[0,1,0]
	v_pk_fma_f32 v[34:35], v[100:101], v[34:35], 0 op_sel_hi:[0,1,0]
	v_pk_fma_f32 v[36:37], v[100:101], v[36:37], 0 op_sel_hi:[0,1,0]
	v_pk_fma_f32 v[38:39], v[100:101], v[38:39], 0 op_sel_hi:[0,1,0]
	v_pk_fma_f32 v[40:41], v[100:101], v[40:41], 0 op_sel_hi:[0,1,0]
	v_pk_fma_f32 v[42:43], v[100:101], v[42:43], 0 op_sel_hi:[0,1,0]
	v_pk_fma_f32 v[44:45], v[100:101], v[44:45], 0 op_sel_hi:[0,1,0]
	v_pk_fma_f32 v[46:47], v[100:101], v[46:47], 0 op_sel_hi:[0,1,0]
	v_pk_fma_f32 v[50:51], v[100:101], v[50:51], 0 op_sel_hi:[0,1,0]
	v_pk_fma_f32 v[52:53], v[100:101], v[52:53], 0 op_sel_hi:[0,1,0]
	v_mul_f32_e32 v64, v100, v64
	v_pk_fma_f32 v[54:55], v[100:101], v[54:55], 0 op_sel_hi:[0,1,0]
	v_pk_fma_f32 v[56:57], v[100:101], v[56:57], 0 op_sel_hi:[0,1,0]
	v_pk_fma_f32 v[58:59], v[100:101], v[58:59], 0 op_sel_hi:[0,1,0]
	v_pk_fma_f32 v[60:61], v[100:101], v[60:61], 0 op_sel_hi:[0,1,0]
	v_pk_fma_f32 v[62:63], v[100:101], v[62:63], 0 op_sel_hi:[0,1,0]
	s_waitcnt vmcnt(2)
	v_mfma_f32_32x32x16_bf16 v[66:81], v[160:163], v[94:97], 0
	v_mfma_f32_32x32x16_bf16 v[66:81], v[156:159], v[90:93], v[66:81]
	s_nop 0
	s_waitcnt vmcnt(1)
	v_mfma_f32_32x32x16_bf16 v[66:81], v[164:167], v[86:89], v[66:81]
	s_nop 0
	s_waitcnt vmcnt(0)
	v_mfma_f32_32x32x16_bf16 v[66:81], v[140:143], v[82:85], v[66:81]
	v_lshl_add_u64 v[114:115], v[106:107], 0, v[110:111]
	global_load_dwordx4 v[168:171], v[114:115], off offset:32
	global_load_dwordx4 v[172:175], v[114:115], off
	global_load_dwordx4 v[176:179], v[114:115], off offset:64
	global_load_dwordx4 v[148:151], v[114:115], off offset:96
	s_nop 0
	s_nop 9
	v_pk_fma_f32 v[2:3], v[102:103], v[66:67], v[2:3] op_sel_hi:[0,1,1]
	v_mul_f32_e32 v66, v102, v80
	v_mov_b32_e32 v80, v17
	v_pk_fma_f32 v[4:5], v[102:103], v[68:69], v[4:5] op_sel_hi:[0,1,1]
	v_pk_mul_f32 v[68:69], v[100:101], v[80:81]
	v_pk_fma_f32 v[14:15], v[102:103], v[78:79], v[14:15] op_sel_hi:[0,1,1]
	v_mov_b32_e32 v17, v68
	v_pk_add_f32 v[16:17], v[16:17], 0 op_sel_hi:[1,0]
	v_mov_b32_e32 v67, v69
	v_pk_add_f32 v[16:17], v[16:17], v[66:67]
	s_nop 0
	v_pk_fma_f32 v[12:13], v[102:103], v[76:77], v[12:13] op_sel_hi:[0,1,1]
	v_pk_fma_f32 v[10:11], v[102:103], v[74:75], v[10:11] op_sel_hi:[0,1,1]
	v_pk_fma_f32 v[8:9], v[102:103], v[72:73], v[8:9] op_sel_hi:[0,1,1]
	v_pk_fma_f32 v[6:7], v[102:103], v[70:71], v[6:7] op_sel_hi:[0,1,1]
	s_waitcnt vmcnt(2)
	v_mfma_f32_32x32x16_bf16 v[66:81], v[172:175], v[94:97], 0
	v_mfma_f32_32x32x16_bf16 v[66:81], v[168:171], v[90:93], v[66:81]
	s_nop 0
	s_waitcnt vmcnt(1)
	v_mfma_f32_32x32x16_bf16 v[66:81], v[176:179], v[86:89], v[66:81]
	s_nop 0
	s_waitcnt vmcnt(0)
; #define MFMA32(a, b, c) __builtin_amdgcn_mfma_f32_32x32x16_bf16((a), (b), (c), 0, 0, 0)
;     ...
; #pragma unroll
;   for (int i = 0; i < NKL; ++i) { int c = tid + NTHR * i; int row = c / KCH, kc = c % KCH; koff[i] = (u32)(row * ldk + 8 * kc) * 2u; klds[i] = row * KST + 8 * kc; }
;   const u32 voff = (u32)((tid >> 3) * 4096 + 8 * (tid & 7)) * 2u;
;   const int vlds = 64 * KST + (tid >> 3) * 72 + 8 * (tid & 7);
;   auto gload = [&](int k0) __attribute__((always_inline)) {
;     const char* kb = (const char*)Kg + (size_t)k0 * ldk * 2;
; #pragma unroll
;     for (int i = 0; i < NKL; ++i) rk[i] = *(const u32x4*)(kb + koff[i]);
;     const char* vb = (const char*)VTg + (size_t)k0 * 2;
; #pragma unroll
;     for (int i = 0; i < 2; ++i) rv[i] = *(const u32x4*)(vb + (size_t)i * 64 * 4096 * 2 + voff);
;   };
;   auto lstore = [&](int b) __attribute__((always_inline)) {
;     u16* St = S0 + b * STG;
; #pragma unroll
;     for (int i = 0; i < NKL; ++i) *(u32x4*)(St + klds[i]) = rk[i];
; #pragma unroll
;     for (int i = 0; i < 2; ++i) *(u32x4*)(St + vlds + i * 64 * 72) = rv[i];
;   };
;   gload(kt0 * 64);
;   __syncthreads();
;   lstore(0);
;   gload((kt0 + 1) * 64);
;   __syncthreads();
; DI void ret_attn_item(const Params& P, const WsPtrs& W, int layer, int item, unsigned char* smem) {
;     ...
;       for (int dt = 0; dt < 4; ++dt) {
;         f32x16 tq;
; #pragma unroll
;         for (int e = 0; e < 16; ++e) tq[e] = 0.f;
; #pragma unroll
;         for (int ks = 0; ks < 4; ++ks) {
;           bf16x8 af = *(const bf16x8*)(st + (32 * dt + r) * 64 + 16 * ks + 8 * h);
;           tq = MFMA32(af, qf[ks], tq);
;         }
; #pragma unroll
;         for (int e = 0; e < 16; ++e) o[dt][e] = (dir == 0 ? 0.f : o[dt][e]) + sc * tq[e];
;       }
;     }
	v_mfma_f32_32x32x16_bf16 v[66:81], v[148:151], v[82:85], v[66:81]
	v_lshl_add_u64 v[112:113], v[106:107], 0, v[108:109]
	global_load_dwordx4 v[180:183], v[112:113], off offset:32
	global_load_dwordx4 v[184:187], v[112:113], off
	global_load_dwordx4 v[132:135], v[112:113], off offset:64
	global_load_dwordx4 v[152:155], v[112:113], off offset:96
	global_load_dwordx4 v[136:139], v[104:105], off
	global_load_dwordx4 v[144:147], v[104:105], off offset:32
	global_load_dwordx4 v[160:163], v[104:105], off offset:64
	global_load_dwordx4 v[156:159], v[104:105], off offset:96
	s_nop 0
	s_nop 9
	v_pk_fma_f32 v[18:19], v[102:103], v[66:67], v[18:19] op_sel_hi:[0,1,1]
	v_mul_f32_e32 v66, v102, v80
	v_mov_b32_e32 v80, v33
	v_pk_fma_f32 v[20:21], v[102:103], v[68:69], v[20:21] op_sel_hi:[0,1,1]
	v_pk_mul_f32 v[68:69], v[100:101], v[80:81]
	v_pk_fma_f32 v[30:31], v[102:103], v[78:79], v[30:31] op_sel_hi:[0,1,1]
	v_mov_b32_e32 v33, v68
	v_pk_add_f32 v[32:33], v[32:33], 0 op_sel_hi:[1,0]
	v_mov_b32_e32 v67, v69
	v_pk_add_f32 v[32:33], v[32:33], v[66:67]
	s_nop 0
	v_pk_fma_f32 v[28:29], v[102:103], v[76:77], v[28:29] op_sel_hi:[0,1,1]
	v_pk_fma_f32 v[26:27], v[102:103], v[74:75], v[26:27] op_sel_hi:[0,1,1]
	v_pk_fma_f32 v[24:25], v[102:103], v[72:73], v[24:25] op_sel_hi:[0,1,1]
	v_pk_fma_f32 v[22:23], v[102:103], v[70:71], v[22:23] op_sel_hi:[0,1,1]
	s_waitcnt vmcnt(6)
	v_mfma_f32_32x32x16_bf16 v[66:81], v[184:187], v[94:97], 0
	v_mfma_f32_32x32x16_bf16 v[66:81], v[180:183], v[90:93], v[66:81]
	s_nop 0
	s_waitcnt vmcnt(5)
	v_mfma_f32_32x32x16_bf16 v[66:81], v[132:135], v[86:89], v[66:81]
	s_nop 0
	s_waitcnt vmcnt(4)
	v_mfma_f32_32x32x16_bf16 v[66:81], v[152:155], v[82:85], v[66:81]
	s_nop 11
	v_pk_fma_f32 v[34:35], v[102:103], v[66:67], v[34:35] op_sel_hi:[0,1,1]
	v_mul_f32_e32 v66, v102, v80
	v_mov_b32_e32 v80, v49
	v_pk_fma_f32 v[36:37], v[102:103], v[68:69], v[36:37] op_sel_hi:[0,1,1]
	v_pk_mul_f32 v[68:69], v[100:101], v[80:81]
	v_pk_fma_f32 v[46:47], v[102:103], v[78:79], v[46:47] op_sel_hi:[0,1,1]
	v_mov_b32_e32 v49, v68
	v_pk_add_f32 v[48:49], v[48:49], 0 op_sel_hi:[1,0]
	v_mov_b32_e32 v67, v69
	v_pk_add_f32 v[48:49], v[48:49], v[66:67]
	s_nop 0
	v_pk_fma_f32 v[44:45], v[102:103], v[76:77], v[44:45] op_sel_hi:[0,1,1]
	v_pk_fma_f32 v[42:43], v[102:103], v[74:75], v[42:43] op_sel_hi:[0,1,1]
	v_pk_fma_f32 v[40:41], v[102:103], v[72:73], v[40:41] op_sel_hi:[0,1,1]
	v_pk_fma_f32 v[38:39], v[102:103], v[70:71], v[38:39] op_sel_hi:[0,1,1]
	s_waitcnt vmcnt(3)
	v_mfma_f32_32x32x16_bf16 v[66:81], v[136:139], v[94:97], 0
	s_nop 0
	s_waitcnt vmcnt(2)
	v_mfma_f32_32x32x16_bf16 v[66:81], v[144:147], v[90:93], v[66:81]
	s_nop 0
	s_waitcnt vmcnt(1)
	v_mfma_f32_32x32x16_bf16 v[66:81], v[160:163], v[86:89], v[66:81]
	s_nop 0
	s_waitcnt vmcnt(0)
	v_mfma_f32_32x32x16_bf16 v[66:81], v[156:159], v[82:85], v[66:81]
	s_nop 11
	v_pk_fma_f32 v[50:51], v[102:103], v[66:67], v[50:51] op_sel_hi:[0,1,1]
	v_mul_f32_e32 v66, v102, v80
	v_mov_b32_e32 v80, v65
	v_pk_fma_f32 v[52:53], v[102:103], v[68:69], v[52:53] op_sel_hi:[0,1,1]
	v_pk_mul_f32 v[68:69], v[100:101], v[80:81]
	v_pk_fma_f32 v[62:63], v[102:103], v[78:79], v[62:63] op_sel_hi:[0,1,1]
	v_mov_b32_e32 v67, v69
	v_mov_b32_e32 v69, v250
	v_mov_b32_e32 v65, v68
	v_and_b32_e32 v83, 31, v69
	v_mul_u32_u24_e32 v0, 0x3300, v83
	v_pk_add_f32 v[64:65], v[64:65], 0 op_sel_hi:[1,0]
	v_bfe_u32 v68, v69, 5, 1
	v_lshlrev_b32_e32 v0, 1, v0
	v_pk_add_f32 v[64:65], v[64:65], v[66:67]
	v_lshl_add_u64 v[66:67], v[98:99], 0, v[0:1]
	v_lshlrev_b32_e32 v0, 4, v68
	v_lshl_add_u64 v[66:67], v[66:67], 0, v[0:1]
	v_ashrrev_i32_e32 v0, 31, v69
	v_lshrrev_b32_e32 v0, 29, v0
	v_add_u32_e32 v0, v69, v0
	v_pk_fma_f32 v[60:61], v[102:103], v[76:77], v[60:61] op_sel_hi:[0,1,1]
	v_pk_fma_f32 v[58:59], v[102:103], v[74:75], v[58:59] op_sel_hi:[0,1,1]
	v_pk_fma_f32 v[56:57], v[102:103], v[72:73], v[56:57] op_sel_hi:[0,1,1]
	v_pk_fma_f32 v[54:55], v[102:103], v[70:71], v[54:55] op_sel_hi:[0,1,1]
	global_load_dwordx4 v[98:101], v[66:67], off
	global_load_dwordx4 v[102:105], v[66:67], off offset:32
	global_load_dwordx4 v[106:109], v[66:67], off offset:64
	global_load_dwordx4 v[110:113], v[66:67], off offset:96
	v_ashrrev_i32_e32 v67, 3, v0
	v_and_b32_e32 v0, 0x1ffffff8, v0
	v_sub_u32_e32 v0, v69, v0
	v_mul_lo_u32 v66, v67, s56
	v_lshl_add_u32 v66, v0, 3, v66
	v_mad_u64_u32 v[128:129], s[12:13], v67, s12, v[66:67]
	s_add_u32 s12, s17, s21
	v_lshlrev_b32_e32 v0, 1, v66
	v_ashrrev_i32_e32 v87, 3, v69
	v_lshlrev_b32_e32 v66, 3, v69
	s_addc_u32 s13, s24, 0
	v_and_b32_e32 v82, 56, v66
	v_lshlrev_b32_e32 v66, 13, v87
	global_load_dwordx4 v[70:73], v0, s[12:13]
	s_add_u32 s12, s14, s25
	v_lshl_or_b32 v66, v82, 1, v66
	s_addc_u32 s13, s22, 0
	v_mov_b32_e32 v67, v1
	v_lshl_add_u64 v[78:79], s[12:13], 0, v[66:67]
	s_mov_b32 s14, 0x80000
	v_add_co_u32_e32 v84, vcc, s14, v78
	global_load_dwordx4 v[74:77], v66, s[12:13]
	s_nop 0
	v_addc_co_u32_e32 v85, vcc, 0, v79, vcc
	global_load_dwordx4 v[78:81], v[84:85], off
	s_movk_i32 s21, 0x48
	v_mad_u64_u32 v[130:131], s[22:23], v87, s21, v[82:83]
	s_or_b32 s21, s25, 0x80
	v_lshl_add_u32 v69, v128, 1, 64
	s_mulk_i32 s21, 0x3300
	s_barrier
	s_add_u32 s22, s17, s21
	s_addc_u32 s23, s24, 0
	s_mul_hi_i32 s17, s10, 0x7e04000
	s_mul_i32 s10, s10, 0x7e04000
	v_lshlrev_b32_e32 v86, 3, v68
	s_mov_b32 s14, 0
	v_lshlrev_b32_e32 v134, 1, v86
	s_waitcnt vmcnt(2)
	ds_write_b128 v69, v[70:73]
	v_lshl_add_u32 v69, v130, 1, 64
	s_waitcnt vmcnt(1)
	ds_write_b128 v69, v[74:77] offset:9216
	s_waitcnt vmcnt(0)
	ds_write_b128 v69, v[78:81] offset:18432
	global_load_dwordx4 v[114:117], v0, s[22:23]
	global_load_dwordx4 v[118:121], v66, s[12:13] offset:128
	global_load_dwordx4 v[122:125], v[84:85], off offset:128
	v_readlane_b32 s12, v255, 25
	s_or_b32 s12, s12, s20
	s_bfe_i32 s13, s12, 0x1001b
	s_bfe_i32 s12, s12, 0x1c0000
	s_lshl_b64 s[12:13], s[12:13], 20
	s_add_u32 s10, s10, s12
	v_readlane_b32 s12, v254, 29
	s_addc_u32 s13, s17, s13
	s_add_i32 s12, s12, s18
	s_and_b32 s17, s12, 15
	s_lshl_b32 s12, s17, 9
	s_or_b32 s12, s10, s12
	v_readlane_b32 s10, v255, 42
	v_or_b32_e32 v69, v83, v126
	v_lshl_add_u64 v[126:127], s[12:13], 0, v[66:67]
	s_add_u32 s10, s10, s16
	v_readlane_b32 s12, v255, 43
	s_addc_u32 s12, s12, s15
	s_mul_i32 s17, s17, 0x660000
	s_add_u32 s10, s10, s17
	v_cvt_f32_i32_e32 v129, v69
	s_addc_u32 s12, s12, 0
	s_add_u32 s8, s10, s8
	v_mul_u32_u24_e32 v69, 0x48, v83
	s_addc_u32 s9, s12, s9
	v_lshl_add_u64 v[132:133], s[8:9], 0, v[0:1]
	v_lshl_or_b32 v0, v68, 2, s11
	v_lshlrev_b32_e32 v131, 1, v69
	s_mov_b32 s8, 0
	s_waitcnt lgkmcnt(0)
	s_barrier
	s_branch .LBB0_551

; DI u32 pack2(float a, float b) { f2_t v = {a, b}; bf2_t r = __builtin_convertvector(v, bf2_t); return __builtin_bit_cast(u32, r); }
; DI float shx(float v, int k) { return __int_as_float(__builtin_amdgcn_ds_bpermute((lane_id_l() ^ k) << 2, __float_as_int(v))); }
; DI void resid_store8(const f32x4v (&acc)[2][2][4][2], const float* xin, float* xout, u16* xb, float* ssp, int m0, int n0, bool wr_norm = true) {
;     ...
; #pragma unroll
;   for (int bj = 0; bj < 2; ++bj)
; #pragma unroll
;     for (int n = 0; n < 2; ++n) {
;       const int row = m0 + bj * 128 + wc * 32 + n * 16 + fr;
; #pragma unroll
;       for (int ai = 0; ai < 2; ++ai) {
;         float ss = 0.f;
;         const int cb = n0 + ai * 128 + wr * 64;
; #pragma unroll
;         for (int m = 0; m < 4; ++m) {
;           const size_t off = (size_t)row * 1024 + cb + m * 16 + fq * 4;
;           f32x4 v = *(const f32x4*)(xin + off);
;           f32x4v a = acc[ai][bj][m][n];
;           v.x += a.x; v.y += a.y; v.z += a.z; v.w += a.w;
;           *(f32x4*)(xout + off) = v;
;           ss += v.x * v.x + v.y * v.y + v.z * v.z + v.w * v.w;
;           if (wr_norm) { u32x2 o2; o2.x = pack2(v.x, v.y); o2.y = pack2(v.z, v.w); *(u32x2*)(xb + off) = o2; }
;         }
;         ss += shx(ss, 16);
;         ss += shx(ss, 32);
;         if (wr_norm && fq == 0) ssp[(size_t)row * 16 + (cb >> 6)] = ss;
;       }
.LBB0_835:
	s_or_b64 exec, exec, s[14:15]
	v_mov_b32_e32 v0, v250
	s_nop 0
	v_lshrrev_b32_e32 v131, 1, v0
	v_and_b32_e32 v130, 15, v0
	v_and_b32_e32 v131, 0x60, v131
	v_bfe_u32 v146, v0, 4, 2
	v_or3_b32 v132, v130, v131, s12
	v_ashrrev_i32_e32 v0, 2, v0
	v_and_b32_e32 v0, 0xffffffc0, v0
	v_ashrrev_i32_e32 v133, 31, v132
	v_add_u32_e32 v130, s10, v0
	v_lshlrev_b32_e32 v0, 2, v146
	v_lshlrev_b64 v[134:135], 10, v[132:133]
	v_or_b32_e32 v134, v134, v0
	v_ashrrev_i32_e32 v131, 31, v130
	v_lshl_add_u64 v[140:141], v[134:135], 0, v[130:131]
	v_readlane_b32 s10, v255, 11
	v_lshlrev_b64 v[142:143], 2, v[140:141]
	v_readlane_b32 s11, v255, 12
	v_cmp_eq_u32_e32 vcc, 0, v146
	s_nop 0
	v_lshl_add_u64 v[144:145], s[10:11], 0, v[142:143]
	global_load_dwordx4 v[136:139], v[144:145], off
	global_load_dwordx4 v[148:151], v[144:145], off offset:64
	global_load_dwordx4 v[152:155], v[144:145], off offset:128
	global_load_dwordx4 v[156:159], v[144:145], off offset:192
	s_mul_i32 s11, s6, 0x5800000
	s_mul_hi_i32 s10, s6, 0x5800000
	s_add_u32 s11, s62, s11
	s_addc_u32 s12, s63, s10
	s_add_u32 s10, s11, s25
	s_addc_u32 s11, s12, s26
	v_readlane_b32 s12, v254, 60
	v_readlane_b32 s13, v254, 61
	v_lshl_add_u64 v[140:141], v[140:141], 1, s[10:11]
	s_lshl_b64 s[6:7], s[6:7], 18
	v_lshl_add_u64 v[142:143], s[12:13], 0, v[142:143]
	s_add_u32 s8, s10, s8
	s_addc_u32 s9, s11, s9
	s_add_u32 s6, s8, s6
	s_addc_u32 s7, s9, s7
	s_waitcnt vmcnt(3)
	v_pk_add_f32 v[128:129], v[128:129], v[138:139]
	v_pk_add_f32 v[126:127], v[126:127], v[136:137]
	v_cvt_pk_bf16_f32 v137, v128, v129
	v_cvt_pk_bf16_f32 v136, v126, v127
	global_store_dwordx4 v[142:143], v[126:129], off
	global_store_dwordx2 v[140:141], v[136:137], off
	s_nop 0
	v_pk_mul_f32 v[126:127], v[126:127], v[126:127]
	v_pk_mul_f32 v[128:129], v[128:129], v[128:129]
	v_add_f32_e32 v126, v126, v127
	v_add_f32_e32 v126, v128, v126
	v_add_f32_e32 v126, v129, v126
	s_waitcnt vmcnt(4)
	v_pk_add_f32 v[124:125], v[124:125], v[150:151]
	v_pk_add_f32 v[122:123], v[122:123], v[148:149]
	v_cvt_pk_bf16_f32 v137, v124, v125
	v_cvt_pk_bf16_f32 v136, v122, v123
	global_store_dwordx4 v[142:143], v[122:125], off offset:64
	global_store_dwordx2 v[140:141], v[136:137], off offset:32
	s_nop 0
	v_pk_mul_f32 v[122:123], v[122:123], v[122:123]
	v_pk_mul_f32 v[124:125], v[124:125], v[124:125]
	v_add_f32_e32 v122, v122, v123
	v_add_f32_e32 v122, v124, v122
	v_add_f32_e32 v122, v125, v122
	v_add_f32_e32 v122, v126, v122
	s_waitcnt vmcnt(5)
	v_pk_add_f32 v[120:121], v[120:121], v[154:155]
	v_pk_add_f32 v[118:119], v[118:119], v[152:153]
	v_cvt_pk_bf16_f32 v137, v120, v121
	v_cvt_pk_bf16_f32 v136, v118, v119
	global_store_dwordx4 v[142:143], v[118:121], off offset:128
	global_store_dwordx2 v[140:141], v[136:137], off offset:64
	s_nop 0
	v_pk_mul_f32 v[118:119], v[118:119], v[118:119]
	v_pk_mul_f32 v[120:121], v[120:121], v[120:121]
	v_add_f32_e32 v118, v118, v119
	v_add_f32_e32 v118, v120, v118
	v_add_f32_e32 v118, v121, v118
	v_add_f32_e32 v122, v122, v118
	v_mov_b32_e32 v144, v229
	v_mov_b32_e32 v145, v229
	s_waitcnt vmcnt(6)
	v_pk_add_f32 v[114:115], v[114:115], v[156:157]
	v_pk_add_f32 v[116:117], v[116:117], v[158:159]
	v_pk_mul_f32 v[120:121], v[114:115], v[114:115]
	global_store_dwordx4 v[142:143], v[114:117], off offset:192
	v_pk_mul_f32 v[118:119], v[116:117], v[116:117]
	s_nop 0
	v_cvt_pk_bf16_f32 v114, v114, v115
	v_cvt_pk_bf16_f32 v115, v116, v117
	v_add_f32_e32 v116, v120, v121
	global_store_dwordx2 v[140:141], v[114:115], off offset:96
	v_add_f32_e32 v114, v118, v116
	v_add_f32_e32 v114, v119, v114
	v_lshlrev_b32_e32 v115, 2, v144
	v_xor_b32_e32 v115, 64, v115
	v_add_f32_e32 v114, v122, v114
	ds_bpermute_b32 v115, v115, v114
	s_waitcnt lgkmcnt(0)
	v_add_f32_e32 v116, v114, v115
	v_lshlrev_b32_e32 v117, 2, v145
	v_xor_b32_e32 v114, 0x80, v117
	ds_bpermute_b32 v117, v114, v116
	v_lshlrev_b64 v[114:115], 6, v[132:133]
	v_lshl_add_u64 v[118:119], s[6:7], 0, v[114:115]
	v_ashrrev_i32_e32 v114, 6, v130
	s_and_saveexec_b64 s[8:9], vcc
	s_cbranch_execz .LBB0_837
	v_ashrrev_i32_e32 v115, 31, v114
	v_lshl_add_u64 v[120:121], v[114:115], 2, v[118:119]
	s_waitcnt lgkmcnt(0)
	v_add_f32_e32 v115, v116, v117
	global_store_dword v[120:121], v115, off
.LBB0_837:
	s_or_b64 exec, exec, s[8:9]
	v_add_u32_e32 v116, 0x80, v130
	s_waitcnt lgkmcnt(0)
	v_ashrrev_i32_e32 v117, 31, v116
	v_lshl_add_u64 v[124:125], v[134:135], 0, v[116:117]
	v_readlane_b32 s8, v255, 11
	v_lshlrev_b64 v[126:127], 2, v[124:125]
	v_readlane_b32 s9, v255, 12
	v_lshl_add_u64 v[124:125], v[124:125], 1, s[10:11]
	v_mov_b32_e32 v115, v229
	v_lshl_add_u64 v[128:129], s[8:9], 0, v[126:127]
	global_load_dwordx4 v[120:123], v[128:129], off
	global_load_dwordx4 v[148:151], v[128:129], off offset:64
	global_load_dwordx4 v[152:155], v[128:129], off offset:128
	global_load_dwordx4 v[156:159], v[128:129], off offset:192
	v_readlane_b32 s8, v254, 60
	v_readlane_b32 s9, v254, 61
	s_waitcnt vmcnt(3)
	v_pk_add_f32 v[112:113], v[112:113], v[122:123]
	v_pk_add_f32 v[110:111], v[110:111], v[120:121]
	v_lshl_add_u64 v[126:127], s[8:9], 0, v[126:127]
	v_cvt_pk_bf16_f32 v120, v110, v111
	v_cvt_pk_bf16_f32 v121, v112, v113
	global_store_dwordx4 v[126:127], v[110:113], off
	global_store_dwordx2 v[124:125], v[120:121], off
	s_nop 0
	v_pk_mul_f32 v[110:111], v[110:111], v[110:111]
	v_pk_mul_f32 v[112:113], v[112:113], v[112:113]
	v_add_f32_e32 v110, v110, v111
	v_add_f32_e32 v110, v112, v110
	v_add_f32_e32 v110, v113, v110
	s_waitcnt vmcnt(4)
; DI u32 pack2(float a, float b) { f2_t v = {a, b}; bf2_t r = __builtin_convertvector(v, bf2_t); return __builtin_bit_cast(u32, r); }
; DI float shx(float v, int k) { return __int_as_float(__builtin_amdgcn_ds_bpermute((lane_id_l() ^ k) << 2, __float_as_int(v))); }
; DI void resid_store8(const f32x4v (&acc)[2][2][4][2], const float* xin, float* xout, u16* xb, float* ssp, int m0, int n0, bool wr_norm = true) {
;     ...
; #pragma unroll
;   for (int bj = 0; bj < 2; ++bj)
; #pragma unroll
;     for (int n = 0; n < 2; ++n) {
;       const int row = m0 + bj * 128 + wc * 32 + n * 16 + fr;
; #pragma unroll
;       for (int ai = 0; ai < 2; ++ai) {
;         float ss = 0.f;
;         const int cb = n0 + ai * 128 + wr * 64;
; #pragma unroll
;         for (int m = 0; m < 4; ++m) {
;           const size_t off = (size_t)row * 1024 + cb + m * 16 + fq * 4;
;           f32x4 v = *(const f32x4*)(xin + off);
;           f32x4v a = acc[ai][bj][m][n];
;           v.x += a.x; v.y += a.y; v.z += a.z; v.w += a.w;
;           *(f32x4*)(xout + off) = v;
;           ss += v.x * v.x + v.y * v.y + v.z * v.z + v.w * v.w;
;           if (wr_norm) { u32x2 o2; o2.x = pack2(v.x, v.y); o2.y = pack2(v.z, v.w); *(u32x2*)(xb + off) = o2; }
;         }
;         ss += shx(ss, 16);
;         ss += shx(ss, 32);
;         if (wr_norm && fq == 0) ssp[(size_t)row * 16 + (cb >> 6)] = ss;
;       }
	v_pk_add_f32 v[108:109], v[108:109], v[150:151]
	v_pk_add_f32 v[106:107], v[106:107], v[148:149]
	v_cvt_pk_bf16_f32 v121, v108, v109
	v_cvt_pk_bf16_f32 v120, v106, v107
	global_store_dwordx4 v[126:127], v[106:109], off offset:64
	global_store_dwordx2 v[124:125], v[120:121], off offset:32
	s_nop 0
	v_pk_mul_f32 v[106:107], v[106:107], v[106:107]
	v_pk_mul_f32 v[108:109], v[108:109], v[108:109]
	v_add_f32_e32 v106, v106, v107
	v_add_f32_e32 v106, v108, v106
	v_add_f32_e32 v106, v109, v106
	v_add_f32_e32 v106, v110, v106
	s_waitcnt vmcnt(5)
	v_pk_add_f32 v[104:105], v[104:105], v[154:155]
	v_pk_add_f32 v[102:103], v[102:103], v[152:153]
	v_cvt_pk_bf16_f32 v121, v104, v105
	v_cvt_pk_bf16_f32 v120, v102, v103
	global_store_dwordx4 v[126:127], v[102:105], off offset:128
	global_store_dwordx2 v[124:125], v[120:121], off offset:64
	s_nop 0
	v_pk_mul_f32 v[102:103], v[102:103], v[102:103]
	v_pk_mul_f32 v[104:105], v[104:105], v[104:105]
	v_add_f32_e32 v102, v102, v103
	v_add_f32_e32 v102, v104, v102
	v_add_f32_e32 v102, v105, v102
	v_add_f32_e32 v106, v106, v102
	s_waitcnt vmcnt(6)
	v_pk_add_f32 v[98:99], v[98:99], v[156:157]
	v_pk_add_f32 v[100:101], v[100:101], v[158:159]
	v_pk_mul_f32 v[104:105], v[98:99], v[98:99]
	global_store_dwordx4 v[126:127], v[98:101], off offset:192
	v_pk_mul_f32 v[102:103], v[100:101], v[100:101]
	s_nop 0
	v_cvt_pk_bf16_f32 v98, v98, v99
	v_cvt_pk_bf16_f32 v99, v100, v101
	v_add_f32_e32 v100, v104, v105
	global_store_dwordx2 v[124:125], v[98:99], off offset:96
	v_add_f32_e32 v98, v102, v100
	v_add_f32_e32 v98, v103, v98
	v_lshlrev_b32_e32 v99, 2, v115
	v_xor_b32_e32 v99, 64, v99
	v_add_f32_e32 v98, v106, v98
	ds_bpermute_b32 v99, v99, v98
	v_mov_b32_e32 v100, v229
	s_nop 0
	v_lshlrev_b32_e32 v101, 2, v100
	s_waitcnt lgkmcnt(0)
	v_add_f32_e32 v100, v98, v99
	v_xor_b32_e32 v98, 0x80, v101
	ds_bpermute_b32 v101, v98, v100
	v_ashrrev_i32_e32 v98, 6, v116
	s_and_saveexec_b64 s[8:9], vcc
	s_cbranch_execz .LBB0_839
	v_ashrrev_i32_e32 v99, 31, v98
	v_lshl_add_u64 v[102:103], v[98:99], 2, v[118:119]
	s_waitcnt lgkmcnt(0)
	v_add_f32_e32 v99, v100, v101
	global_store_dword v[102:103], v99, off
.LBB0_839:
	s_or_b64 exec, exec, s[8:9]
	v_or_b32_e32 v106, 16, v132
	v_ashrrev_i32_e32 v107, 31, v106
	s_waitcnt lgkmcnt(0)
	v_lshlrev_b64 v[100:101], 10, v[106:107]
	v_or_b32_e32 v100, v100, v0
	v_lshl_add_u64 v[108:109], v[100:101], 0, v[130:131]
	v_readlane_b32 s8, v255, 11
	v_lshlrev_b64 v[110:111], 2, v[108:109]
	v_readlane_b32 s9, v255, 12
	v_lshl_add_u64 v[108:109], v[108:109], 1, s[10:11]
	v_mov_b32_e32 v99, v229
	v_lshl_add_u64 v[112:113], s[8:9], 0, v[110:111]
	global_load_dwordx4 v[102:105], v[112:113], off
	global_load_dwordx4 v[148:151], v[112:113], off offset:64
	global_load_dwordx4 v[152:155], v[112:113], off offset:128
	global_load_dwordx4 v[156:159], v[112:113], off offset:192
	v_readlane_b32 s8, v254, 60
	v_readlane_b32 s9, v254, 61
	s_waitcnt vmcnt(3)
	v_pk_add_f32 v[96:97], v[96:97], v[104:105]
	v_pk_add_f32 v[94:95], v[94:95], v[102:103]
	v_lshl_add_u64 v[110:111], s[8:9], 0, v[110:111]
	v_cvt_pk_bf16_f32 v102, v94, v95
	v_cvt_pk_bf16_f32 v103, v96, v97
	global_store_dwordx4 v[110:111], v[94:97], off
	global_store_dwordx2 v[108:109], v[102:103], off
	s_nop 0
	v_pk_mul_f32 v[94:95], v[94:95], v[94:95]
	v_pk_mul_f32 v[96:97], v[96:97], v[96:97]
	v_add_f32_e32 v94, v94, v95
	v_add_f32_e32 v94, v96, v94
	v_add_f32_e32 v94, v97, v94
	s_waitcnt vmcnt(4)
	v_pk_add_f32 v[92:93], v[92:93], v[150:151]
	v_pk_add_f32 v[90:91], v[90:91], v[148:149]
	v_cvt_pk_bf16_f32 v103, v92, v93
	v_cvt_pk_bf16_f32 v102, v90, v91
	global_store_dwordx4 v[110:111], v[90:93], off offset:64
	global_store_dwordx2 v[108:109], v[102:103], off offset:32
	s_nop 0
	v_pk_mul_f32 v[90:91], v[90:91], v[90:91]
	v_pk_mul_f32 v[92:93], v[92:93], v[92:93]
	v_add_f32_e32 v90, v90, v91
	v_add_f32_e32 v90, v92, v90
	v_add_f32_e32 v90, v93, v90
	v_add_f32_e32 v90, v94, v90
	s_waitcnt vmcnt(5)
	v_pk_add_f32 v[88:89], v[88:89], v[154:155]
	v_pk_add_f32 v[86:87], v[86:87], v[152:153]
	v_cvt_pk_bf16_f32 v103, v88, v89
	v_cvt_pk_bf16_f32 v102, v86, v87
	global_store_dwordx4 v[110:111], v[86:89], off offset:128
	global_store_dwordx2 v[108:109], v[102:103], off offset:64
	s_nop 0
	v_pk_mul_f32 v[86:87], v[86:87], v[86:87]
	v_pk_mul_f32 v[88:89], v[88:89], v[88:89]
	v_add_f32_e32 v86, v86, v87
	v_add_f32_e32 v86, v88, v86
	v_add_f32_e32 v86, v89, v86
	v_add_f32_e32 v90, v90, v86
	s_waitcnt vmcnt(6)
	v_pk_add_f32 v[82:83], v[82:83], v[156:157]
	v_pk_add_f32 v[84:85], v[84:85], v[158:159]
	v_pk_mul_f32 v[88:89], v[82:83], v[82:83]
	global_store_dwordx4 v[110:111], v[82:85], off offset:192
	v_pk_mul_f32 v[86:87], v[84:85], v[84:85]
	s_nop 0
	v_cvt_pk_bf16_f32 v82, v82, v83
	v_cvt_pk_bf16_f32 v83, v84, v85
	v_add_f32_e32 v84, v88, v89
	global_store_dwordx2 v[108:109], v[82:83], off offset:96
	v_add_f32_e32 v82, v86, v84
	v_add_f32_e32 v82, v87, v82
	v_lshlrev_b32_e32 v83, 2, v99
	v_xor_b32_e32 v83, 64, v83
	v_add_f32_e32 v82, v90, v82
	ds_bpermute_b32 v83, v83, v82
	v_mov_b32_e32 v84, v229
	s_nop 0
	v_lshlrev_b32_e32 v85, 2, v84
	s_waitcnt lgkmcnt(0)
	v_add_f32_e32 v84, v82, v83
	v_xor_b32_e32 v82, 0x80, v85
	ds_bpermute_b32 v85, v82, v84
	v_lshlrev_b64 v[82:83], 6, v[106:107]
	v_lshl_add_u64 v[82:83], s[6:7], 0, v[82:83]
	s_and_saveexec_b64 s[8:9], vcc
	s_cbranch_execz .LBB0_841
	v_ashrrev_i32_e32 v115, 31, v114
	v_lshl_add_u64 v[86:87], v[114:115], 2, v[82:83]
	s_waitcnt lgkmcnt(0)
	v_add_f32_e32 v84, v84, v85
	global_store_dword v[86:87], v84, off
; DI u32 pack2(float a, float b) { f2_t v = {a, b}; bf2_t r = __builtin_convertvector(v, bf2_t); return __builtin_bit_cast(u32, r); }
; DI float shx(float v, int k) { return __int_as_float(__builtin_amdgcn_ds_bpermute((lane_id_l() ^ k) << 2, __float_as_int(v))); }
; DI void resid_store8(const f32x4v (&acc)[2][2][4][2], const float* xin, float* xout, u16* xb, float* ssp, int m0, int n0, bool wr_norm = true) {
;     ...
; #pragma unroll
;   for (int bj = 0; bj < 2; ++bj)
; #pragma unroll
;     for (int n = 0; n < 2; ++n) {
;       const int row = m0 + bj * 128 + wc * 32 + n * 16 + fr;
; #pragma unroll
;       for (int ai = 0; ai < 2; ++ai) {
;         float ss = 0.f;
;         const int cb = n0 + ai * 128 + wr * 64;
; #pragma unroll
;         for (int m = 0; m < 4; ++m) {
;           const size_t off = (size_t)row * 1024 + cb + m * 16 + fq * 4;
;           f32x4 v = *(const f32x4*)(xin + off);
;           f32x4v a = acc[ai][bj][m][n];
;           v.x += a.x; v.y += a.y; v.z += a.z; v.w += a.w;
;           *(f32x4*)(xout + off) = v;
;           ss += v.x * v.x + v.y * v.y + v.z * v.z + v.w * v.w;
;           if (wr_norm) { u32x2 o2; o2.x = pack2(v.x, v.y); o2.y = pack2(v.z, v.w); *(u32x2*)(xb + off) = o2; }
;         }
;         ss += shx(ss, 16);
;         ss += shx(ss, 32);
;         if (wr_norm && fq == 0) ssp[(size_t)row * 16 + (cb >> 6)] = ss;
;       }
.LBB0_841:
	s_or_b64 exec, exec, s[8:9]
	v_lshl_add_u64 v[88:89], v[100:101], 0, v[116:117]
	v_readlane_b32 s8, v255, 11
	v_lshlrev_b64 v[90:91], 2, v[88:89]
	v_readlane_b32 s9, v255, 12
	v_lshl_add_u64 v[88:89], v[88:89], 1, s[10:11]
	s_nop 0
	v_lshl_add_u64 v[92:93], s[8:9], 0, v[90:91]
	s_waitcnt lgkmcnt(0)
	global_load_dwordx4 v[84:87], v[92:93], off
	global_load_dwordx4 v[148:151], v[92:93], off offset:64
	global_load_dwordx4 v[152:155], v[92:93], off offset:128
	global_load_dwordx4 v[156:159], v[92:93], off offset:192
	v_readlane_b32 s8, v254, 60
	v_readlane_b32 s9, v254, 61
	s_waitcnt vmcnt(3)
	v_pk_add_f32 v[80:81], v[80:81], v[86:87]
	v_pk_add_f32 v[78:79], v[78:79], v[84:85]
	v_lshl_add_u64 v[90:91], s[8:9], 0, v[90:91]
	v_cvt_pk_bf16_f32 v84, v78, v79
	v_cvt_pk_bf16_f32 v85, v80, v81
	global_store_dwordx4 v[90:91], v[78:81], off
	global_store_dwordx2 v[88:89], v[84:85], off
	s_nop 0
	v_pk_mul_f32 v[78:79], v[78:79], v[78:79]
	v_pk_mul_f32 v[80:81], v[80:81], v[80:81]
	v_add_f32_e32 v78, v78, v79
	v_add_f32_e32 v78, v80, v78
	v_add_f32_e32 v78, v81, v78
	s_waitcnt vmcnt(4)
	v_pk_add_f32 v[76:77], v[76:77], v[150:151]
	v_pk_add_f32 v[74:75], v[74:75], v[148:149]
	v_cvt_pk_bf16_f32 v85, v76, v77
	v_cvt_pk_bf16_f32 v84, v74, v75
	global_store_dwordx4 v[90:91], v[74:77], off offset:64
	global_store_dwordx2 v[88:89], v[84:85], off offset:32
	s_nop 0
	v_pk_mul_f32 v[74:75], v[74:75], v[74:75]
	v_pk_mul_f32 v[76:77], v[76:77], v[76:77]
	v_add_f32_e32 v74, v74, v75
	v_add_f32_e32 v74, v76, v74
	v_add_f32_e32 v74, v77, v74
	v_add_f32_e32 v74, v78, v74
	s_waitcnt vmcnt(5)
	v_pk_add_f32 v[72:73], v[72:73], v[154:155]
	v_pk_add_f32 v[70:71], v[70:71], v[152:153]
	v_cvt_pk_bf16_f32 v85, v72, v73
	v_cvt_pk_bf16_f32 v84, v70, v71
	global_store_dwordx4 v[90:91], v[70:73], off offset:128
	global_store_dwordx2 v[88:89], v[84:85], off offset:64
	s_nop 0
	v_pk_mul_f32 v[70:71], v[70:71], v[70:71]
	v_pk_mul_f32 v[72:73], v[72:73], v[72:73]
	v_add_f32_e32 v70, v70, v71
	v_add_f32_e32 v70, v72, v70
	v_add_f32_e32 v70, v73, v70
	v_add_f32_e32 v74, v74, v70
	v_mov_b32_e32 v92, v229
	s_waitcnt vmcnt(6)
	v_pk_add_f32 v[66:67], v[66:67], v[156:157]
	v_pk_add_f32 v[68:69], v[68:69], v[158:159]
	v_pk_mul_f32 v[72:73], v[66:67], v[66:67]
	global_store_dwordx4 v[90:91], v[66:69], off offset:192
	v_pk_mul_f32 v[70:71], v[68:69], v[68:69]
	s_nop 0
	v_cvt_pk_bf16_f32 v66, v66, v67
	v_cvt_pk_bf16_f32 v67, v68, v69
	v_add_f32_e32 v68, v72, v73
	global_store_dwordx2 v[88:89], v[66:67], off offset:96
	v_add_f32_e32 v66, v70, v68
	v_add_f32_e32 v66, v71, v66
	v_lshlrev_b32_e32 v67, 2, v92
	v_xor_b32_e32 v67, 64, v67
	v_add_f32_e32 v66, v74, v66
	ds_bpermute_b32 v67, v67, v66
	v_mov_b32_e32 v68, v229
	s_waitcnt lgkmcnt(0)
	v_add_f32_e32 v66, v66, v67
	v_lshlrev_b32_e32 v68, 2, v68
	v_xor_b32_e32 v67, 0x80, v68
	ds_bpermute_b32 v67, v67, v66
	s_and_saveexec_b64 s[8:9], vcc
	s_cbranch_execz .LBB0_843
	v_ashrrev_i32_e32 v99, 31, v98
	v_lshl_add_u64 v[68:69], v[98:99], 2, v[82:83]
	s_waitcnt lgkmcnt(0)
	v_add_f32_e32 v66, v66, v67
	global_store_dword v[68:69], v66, off
.LBB0_843:
	s_or_b64 exec, exec, s[8:9]
	v_or_b32_e32 v72, 0x80, v132
	v_ashrrev_i32_e32 v73, 31, v72
	s_waitcnt lgkmcnt(0)
	v_lshlrev_b64 v[66:67], 10, v[72:73]
	v_or_b32_e32 v66, v66, v0
	v_lshl_add_u64 v[74:75], v[66:67], 0, v[130:131]
	v_readlane_b32 s8, v255, 11
	v_lshlrev_b64 v[76:77], 2, v[74:75]
	v_readlane_b32 s9, v255, 12
	v_lshl_add_u64 v[74:75], v[74:75], 1, s[10:11]
	s_nop 0
	v_lshl_add_u64 v[78:79], s[8:9], 0, v[76:77]
	global_load_dwordx4 v[68:71], v[78:79], off
	global_load_dwordx4 v[148:151], v[78:79], off offset:64
	global_load_dwordx4 v[152:155], v[78:79], off offset:128
	global_load_dwordx4 v[156:159], v[78:79], off offset:192
	v_readlane_b32 s8, v254, 60
	v_readlane_b32 s9, v254, 61
	s_waitcnt vmcnt(3)
	v_pk_add_f32 v[64:65], v[64:65], v[70:71]
	v_pk_add_f32 v[62:63], v[62:63], v[68:69]
	v_lshl_add_u64 v[76:77], s[8:9], 0, v[76:77]
	v_cvt_pk_bf16_f32 v68, v62, v63
	v_cvt_pk_bf16_f32 v69, v64, v65
	global_store_dwordx4 v[76:77], v[62:65], off
	global_store_dwordx2 v[74:75], v[68:69], off
	s_nop 0
	v_pk_mul_f32 v[62:63], v[62:63], v[62:63]
	v_pk_mul_f32 v[64:65], v[64:65], v[64:65]
	v_add_f32_e32 v62, v62, v63
	v_add_f32_e32 v62, v64, v62
	v_add_f32_e32 v62, v65, v62
	s_waitcnt vmcnt(4)
	v_pk_add_f32 v[60:61], v[60:61], v[150:151]
	v_pk_add_f32 v[58:59], v[58:59], v[148:149]
	v_cvt_pk_bf16_f32 v69, v60, v61
	v_cvt_pk_bf16_f32 v68, v58, v59
	global_store_dwordx4 v[76:77], v[58:61], off offset:64
	global_store_dwordx2 v[74:75], v[68:69], off offset:32
	s_nop 0
	v_pk_mul_f32 v[58:59], v[58:59], v[58:59]
	v_pk_mul_f32 v[60:61], v[60:61], v[60:61]
	v_add_f32_e32 v58, v58, v59
	v_add_f32_e32 v58, v60, v58
	v_add_f32_e32 v58, v61, v58
	v_add_f32_e32 v58, v62, v58
	s_waitcnt vmcnt(5)
	v_pk_add_f32 v[56:57], v[56:57], v[154:155]
	v_pk_add_f32 v[54:55], v[54:55], v[152:153]
	v_cvt_pk_bf16_f32 v69, v56, v57
	v_cvt_pk_bf16_f32 v68, v54, v55
	global_store_dwordx4 v[76:77], v[54:57], off offset:128
	global_store_dwordx2 v[74:75], v[68:69], off offset:64
	s_nop 0
	v_pk_mul_f32 v[54:55], v[54:55], v[54:55]
	v_pk_mul_f32 v[56:57], v[56:57], v[56:57]
	v_add_f32_e32 v54, v54, v55
	v_add_f32_e32 v54, v56, v54
	v_add_f32_e32 v54, v57, v54
	v_add_f32_e32 v58, v58, v54
	v_mov_b32_e32 v78, v229
	s_waitcnt vmcnt(6)
	v_pk_add_f32 v[50:51], v[50:51], v[156:157]
	v_pk_add_f32 v[52:53], v[52:53], v[158:159]
	v_pk_mul_f32 v[56:57], v[50:51], v[50:51]
	global_store_dwordx4 v[76:77], v[50:53], off offset:192
	v_pk_mul_f32 v[54:55], v[52:53], v[52:53]
	s_nop 0
	v_cvt_pk_bf16_f32 v50, v50, v51
	v_cvt_pk_bf16_f32 v51, v52, v53
	v_add_f32_e32 v52, v56, v57
	global_store_dwordx2 v[74:75], v[50:51], off offset:96
	v_add_f32_e32 v50, v54, v52
	v_add_f32_e32 v50, v55, v50
	v_lshlrev_b32_e32 v51, 2, v78
	v_xor_b32_e32 v51, 64, v51
	v_add_f32_e32 v50, v58, v50
	ds_bpermute_b32 v51, v51, v50
	v_mov_b32_e32 v52, v229
	s_nop 0
	v_lshlrev_b32_e32 v53, 2, v52
	s_waitcnt lgkmcnt(0)
	v_add_f32_e32 v52, v50, v51
	v_xor_b32_e32 v50, 0x80, v53
	ds_bpermute_b32 v53, v50, v52
	v_lshlrev_b64 v[50:51], 6, v[72:73]
	v_lshl_add_u64 v[50:51], s[6:7], 0, v[50:51]
	s_and_saveexec_b64 s[8:9], vcc
	s_cbranch_execz .LBB0_845
	v_ashrrev_i32_e32 v115, 31, v114
	v_lshl_add_u64 v[54:55], v[114:115], 2, v[50:51]
	s_waitcnt lgkmcnt(0)
	v_add_f32_e32 v52, v52, v53
	global_store_dword v[54:55], v52, off
; DI u32 pack2(float a, float b) { f2_t v = {a, b}; bf2_t r = __builtin_convertvector(v, bf2_t); return __builtin_bit_cast(u32, r); }
; DI float shx(float v, int k) { return __int_as_float(__builtin_amdgcn_ds_bpermute((lane_id_l() ^ k) << 2, __float_as_int(v))); }
; DI void resid_store8(const f32x4v (&acc)[2][2][4][2], const float* xin, float* xout, u16* xb, float* ssp, int m0, int n0, bool wr_norm = true) {
;     ...
; #pragma unroll
;   for (int bj = 0; bj < 2; ++bj)
; #pragma unroll
;     for (int n = 0; n < 2; ++n) {
;       const int row = m0 + bj * 128 + wc * 32 + n * 16 + fr;
; #pragma unroll
;       for (int ai = 0; ai < 2; ++ai) {
;         float ss = 0.f;
;         const int cb = n0 + ai * 128 + wr * 64;
; #pragma unroll
;         for (int m = 0; m < 4; ++m) {
;           const size_t off = (size_t)row * 1024 + cb + m * 16 + fq * 4;
;           f32x4 v = *(const f32x4*)(xin + off);
;           f32x4v a = acc[ai][bj][m][n];
;           v.x += a.x; v.y += a.y; v.z += a.z; v.w += a.w;
;           *(f32x4*)(xout + off) = v;
;           ss += v.x * v.x + v.y * v.y + v.z * v.z + v.w * v.w;
;           if (wr_norm) { u32x2 o2; o2.x = pack2(v.x, v.y); o2.y = pack2(v.z, v.w); *(u32x2*)(xb + off) = o2; }
;         }
;         ss += shx(ss, 16);
;         ss += shx(ss, 32);
;         if (wr_norm && fq == 0) ssp[(size_t)row * 16 + (cb >> 6)] = ss;
;       }
.LBB0_845:
	s_or_b64 exec, exec, s[8:9]
	v_lshl_add_u64 v[56:57], v[66:67], 0, v[116:117]
	v_readlane_b32 s8, v255, 11
	v_lshlrev_b64 v[58:59], 2, v[56:57]
	v_readlane_b32 s9, v255, 12
	v_lshl_add_u64 v[56:57], v[56:57], 1, s[10:11]
	s_nop 0
	v_lshl_add_u64 v[60:61], s[8:9], 0, v[58:59]
	s_waitcnt lgkmcnt(0)
	global_load_dwordx4 v[52:55], v[60:61], off
	global_load_dwordx4 v[148:151], v[60:61], off offset:64
	global_load_dwordx4 v[152:155], v[60:61], off offset:128
	global_load_dwordx4 v[156:159], v[60:61], off offset:192
	v_readlane_b32 s8, v254, 60
	v_readlane_b32 s9, v254, 61
	s_waitcnt vmcnt(3)
	v_pk_add_f32 v[48:49], v[48:49], v[54:55]
	v_pk_add_f32 v[46:47], v[46:47], v[52:53]
	v_lshl_add_u64 v[58:59], s[8:9], 0, v[58:59]
	v_cvt_pk_bf16_f32 v52, v46, v47
	v_cvt_pk_bf16_f32 v53, v48, v49
	global_store_dwordx4 v[58:59], v[46:49], off
	global_store_dwordx2 v[56:57], v[52:53], off
	s_nop 0
	v_pk_mul_f32 v[46:47], v[46:47], v[46:47]
	v_pk_mul_f32 v[48:49], v[48:49], v[48:49]
	v_add_f32_e32 v46, v46, v47
	v_add_f32_e32 v46, v48, v46
	v_add_f32_e32 v46, v49, v46
	s_waitcnt vmcnt(4)
	v_pk_add_f32 v[44:45], v[44:45], v[150:151]
	v_pk_add_f32 v[42:43], v[42:43], v[148:149]
	v_cvt_pk_bf16_f32 v53, v44, v45
	v_cvt_pk_bf16_f32 v52, v42, v43
	global_store_dwordx4 v[58:59], v[42:45], off offset:64
	global_store_dwordx2 v[56:57], v[52:53], off offset:32
	s_nop 0
	v_pk_mul_f32 v[42:43], v[42:43], v[42:43]
	v_pk_mul_f32 v[44:45], v[44:45], v[44:45]
	v_add_f32_e32 v42, v42, v43
	v_add_f32_e32 v42, v44, v42
	v_add_f32_e32 v42, v45, v42
	v_add_f32_e32 v42, v46, v42
	s_waitcnt vmcnt(5)
	v_pk_add_f32 v[40:41], v[40:41], v[154:155]
	v_pk_add_f32 v[38:39], v[38:39], v[152:153]
	v_cvt_pk_bf16_f32 v53, v40, v41
	v_cvt_pk_bf16_f32 v52, v38, v39
	global_store_dwordx4 v[58:59], v[38:41], off offset:128
	global_store_dwordx2 v[56:57], v[52:53], off offset:64
	s_nop 0
	v_pk_mul_f32 v[38:39], v[38:39], v[38:39]
	v_pk_mul_f32 v[40:41], v[40:41], v[40:41]
	v_add_f32_e32 v38, v38, v39
	v_add_f32_e32 v38, v40, v38
	v_add_f32_e32 v38, v41, v38
	v_add_f32_e32 v42, v42, v38
	v_mov_b32_e32 v60, v229
	s_waitcnt vmcnt(6)
	v_pk_add_f32 v[34:35], v[34:35], v[156:157]
	v_pk_add_f32 v[36:37], v[36:37], v[158:159]
	v_pk_mul_f32 v[40:41], v[34:35], v[34:35]
	global_store_dwordx4 v[58:59], v[34:37], off offset:192
	v_pk_mul_f32 v[38:39], v[36:37], v[36:37]
	s_nop 0
	v_cvt_pk_bf16_f32 v34, v34, v35
	v_cvt_pk_bf16_f32 v35, v36, v37
	v_add_f32_e32 v36, v40, v41
	global_store_dwordx2 v[56:57], v[34:35], off offset:96
	v_add_f32_e32 v34, v38, v36
	v_add_f32_e32 v34, v39, v34
	v_lshlrev_b32_e32 v35, 2, v60
	v_xor_b32_e32 v35, 64, v35
	v_add_f32_e32 v34, v42, v34
	ds_bpermute_b32 v35, v35, v34
	v_mov_b32_e32 v36, v229
	s_waitcnt lgkmcnt(0)
	v_add_f32_e32 v34, v34, v35
	v_lshlrev_b32_e32 v36, 2, v36
	v_xor_b32_e32 v35, 0x80, v36
	ds_bpermute_b32 v35, v35, v34
	s_and_saveexec_b64 s[8:9], vcc
	s_cbranch_execz .LBB0_847
	v_ashrrev_i32_e32 v99, 31, v98
	v_lshl_add_u64 v[36:37], v[98:99], 2, v[50:51]
	s_waitcnt lgkmcnt(0)
	v_add_f32_e32 v34, v34, v35
	global_store_dword v[36:37], v34, off
; DI u32 pack2(float a, float b) { f2_t v = {a, b}; bf2_t r = __builtin_convertvector(v, bf2_t); return __builtin_bit_cast(u32, r); }
; DI float shx(float v, int k) { return __int_as_float(__builtin_amdgcn_ds_bpermute((lane_id_l() ^ k) << 2, __float_as_int(v))); }
; DI void resid_store8(const f32x4v (&acc)[2][2][4][2], const float* xin, float* xout, u16* xb, float* ssp, int m0, int n0, bool wr_norm = true) {
;     ...
; #pragma unroll
;   for (int bj = 0; bj < 2; ++bj)
; #pragma unroll
;     for (int n = 0; n < 2; ++n) {
;       const int row = m0 + bj * 128 + wc * 32 + n * 16 + fr;
; #pragma unroll
;       for (int ai = 0; ai < 2; ++ai) {
;         float ss = 0.f;
;         const int cb = n0 + ai * 128 + wr * 64;
; #pragma unroll
;         for (int m = 0; m < 4; ++m) {
;           const size_t off = (size_t)row * 1024 + cb + m * 16 + fq * 4;
;           f32x4 v = *(const f32x4*)(xin + off);
;           f32x4v a = acc[ai][bj][m][n];
;           v.x += a.x; v.y += a.y; v.z += a.z; v.w += a.w;
;           *(f32x4*)(xout + off) = v;
;           ss += v.x * v.x + v.y * v.y + v.z * v.z + v.w * v.w;
;           if (wr_norm) { u32x2 o2; o2.x = pack2(v.x, v.y); o2.y = pack2(v.z, v.w); *(u32x2*)(xb + off) = o2; }
;         }
;         ss += shx(ss, 16);
;         ss += shx(ss, 32);
;         if (wr_norm && fq == 0) ssp[(size_t)row * 16 + (cb >> 6)] = ss;
;       }
.LBB0_847:
	s_or_b64 exec, exec, s[8:9]
	v_or_b32_e32 v40, 0x90, v132
	v_ashrrev_i32_e32 v41, 31, v40
	s_waitcnt lgkmcnt(0)
	v_lshlrev_b64 v[34:35], 10, v[40:41]
	v_or_b32_e32 v34, v34, v0
	v_lshl_add_u64 v[42:43], v[34:35], 0, v[130:131]
	v_readlane_b32 s8, v255, 11
	v_lshlrev_b64 v[44:45], 2, v[42:43]
	v_readlane_b32 s9, v255, 12
	v_lshl_add_u64 v[42:43], v[42:43], 1, s[10:11]
	v_mov_b32_e32 v0, v229
	v_lshl_add_u64 v[46:47], s[8:9], 0, v[44:45]
	global_load_dwordx4 v[36:39], v[46:47], off
	global_load_dwordx4 v[148:151], v[46:47], off offset:64
	global_load_dwordx4 v[152:155], v[46:47], off offset:128
	global_load_dwordx4 v[156:159], v[46:47], off offset:192
	v_readlane_b32 s8, v254, 60
	v_readlane_b32 s9, v254, 61
	s_waitcnt vmcnt(3)
	v_pk_add_f32 v[32:33], v[32:33], v[38:39]
	v_pk_add_f32 v[30:31], v[30:31], v[36:37]
	v_lshl_add_u64 v[44:45], s[8:9], 0, v[44:45]
	v_cvt_pk_bf16_f32 v36, v30, v31
	v_cvt_pk_bf16_f32 v37, v32, v33
	global_store_dwordx4 v[44:45], v[30:33], off
	global_store_dwordx2 v[42:43], v[36:37], off
	s_nop 0
	v_pk_mul_f32 v[30:31], v[30:31], v[30:31]
	v_pk_mul_f32 v[32:33], v[32:33], v[32:33]
	v_add_f32_e32 v30, v30, v31
	v_add_f32_e32 v30, v32, v30
	v_add_f32_e32 v30, v33, v30
	s_waitcnt vmcnt(4)
	v_pk_add_f32 v[28:29], v[28:29], v[150:151]
	v_pk_add_f32 v[26:27], v[26:27], v[148:149]
	v_cvt_pk_bf16_f32 v37, v28, v29
	v_cvt_pk_bf16_f32 v36, v26, v27
	global_store_dwordx4 v[44:45], v[26:29], off offset:64
	global_store_dwordx2 v[42:43], v[36:37], off offset:32
	s_nop 0
	v_pk_mul_f32 v[26:27], v[26:27], v[26:27]
	v_pk_mul_f32 v[28:29], v[28:29], v[28:29]
	v_add_f32_e32 v26, v26, v27
	v_add_f32_e32 v26, v28, v26
	v_add_f32_e32 v26, v29, v26
	v_add_f32_e32 v26, v30, v26
	s_waitcnt vmcnt(5)
	v_pk_add_f32 v[24:25], v[24:25], v[154:155]
	v_pk_add_f32 v[22:23], v[22:23], v[152:153]
	v_cvt_pk_bf16_f32 v37, v24, v25
	v_cvt_pk_bf16_f32 v36, v22, v23
	global_store_dwordx4 v[44:45], v[22:25], off offset:128
	global_store_dwordx2 v[42:43], v[36:37], off offset:64
	s_nop 0
	v_pk_mul_f32 v[22:23], v[22:23], v[22:23]
	v_pk_mul_f32 v[24:25], v[24:25], v[24:25]
	v_add_f32_e32 v22, v22, v23
	v_add_f32_e32 v22, v24, v22
	v_add_f32_e32 v22, v25, v22
	v_add_f32_e32 v26, v26, v22
	s_waitcnt vmcnt(6)
	v_pk_add_f32 v[18:19], v[18:19], v[156:157]
	v_pk_add_f32 v[20:21], v[20:21], v[158:159]
	v_pk_mul_f32 v[24:25], v[18:19], v[18:19]
	global_store_dwordx4 v[44:45], v[18:21], off offset:192
	v_pk_mul_f32 v[22:23], v[20:21], v[20:21]
	s_nop 0
	v_cvt_pk_bf16_f32 v18, v18, v19
	v_cvt_pk_bf16_f32 v19, v20, v21
	v_add_f32_e32 v20, v24, v25
	global_store_dwordx2 v[42:43], v[18:19], off offset:96
	v_add_f32_e32 v18, v22, v20
	v_lshlrev_b32_e32 v0, 2, v0
	v_add_f32_e32 v18, v23, v18
	v_xor_b32_e32 v0, 64, v0
	v_add_f32_e32 v18, v26, v18
	ds_bpermute_b32 v0, v0, v18
	v_mov_b32_e32 v19, v229
	s_waitcnt lgkmcnt(0)
	v_add_f32_e32 v0, v18, v0
	v_lshlrev_b32_e32 v19, 2, v19
	v_xor_b32_e32 v18, 0x80, v19
	ds_bpermute_b32 v20, v18, v0
	v_lshlrev_b64 v[18:19], 6, v[40:41]
	v_lshl_add_u64 v[18:19], s[6:7], 0, v[18:19]
	s_and_saveexec_b64 s[6:7], vcc
	s_cbranch_execz .LBB0_849
	v_ashrrev_i32_e32 v115, 31, v114
	v_lshl_add_u64 v[22:23], v[114:115], 2, v[18:19]
	s_waitcnt lgkmcnt(0)
	v_add_f32_e32 v0, v0, v20
	global_store_dword v[22:23], v0, off
.LBB0_849:
	s_or_b64 exec, exec, s[6:7]
	v_lshl_add_u64 v[24:25], v[34:35], 0, v[116:117]
	v_readlane_b32 s6, v255, 11
	v_lshlrev_b64 v[26:27], 2, v[24:25]
	v_readlane_b32 s7, v255, 12
	v_lshl_add_u64 v[24:25], v[24:25], 1, s[10:11]
	v_mov_b32_e32 v0, v229
	v_lshl_add_u64 v[28:29], s[6:7], 0, v[26:27]
	s_waitcnt lgkmcnt(0)
	global_load_dwordx4 v[20:23], v[28:29], off
	global_load_dwordx4 v[148:151], v[28:29], off offset:64
	global_load_dwordx4 v[152:155], v[28:29], off offset:128
	global_load_dwordx4 v[156:159], v[28:29], off offset:192
	v_readlane_b32 s6, v254, 60
	v_readlane_b32 s7, v254, 61
	s_waitcnt vmcnt(3)
	v_pk_add_f32 v[16:17], v[16:17], v[22:23]
	v_pk_add_f32 v[14:15], v[14:15], v[20:21]
	v_lshl_add_u64 v[26:27], s[6:7], 0, v[26:27]
	v_cvt_pk_bf16_f32 v20, v14, v15
	v_cvt_pk_bf16_f32 v21, v16, v17
	global_store_dwordx4 v[26:27], v[14:17], off
	global_store_dwordx2 v[24:25], v[20:21], off
	s_nop 0
	v_pk_mul_f32 v[14:15], v[14:15], v[14:15]
	v_pk_mul_f32 v[16:17], v[16:17], v[16:17]
	v_add_f32_e32 v14, v14, v15
	v_add_f32_e32 v14, v16, v14
	v_add_f32_e32 v14, v17, v14
	s_waitcnt vmcnt(4)
	v_pk_add_f32 v[12:13], v[12:13], v[150:151]
	v_pk_add_f32 v[10:11], v[10:11], v[148:149]
	v_cvt_pk_bf16_f32 v21, v12, v13
	v_cvt_pk_bf16_f32 v20, v10, v11
	global_store_dwordx4 v[26:27], v[10:13], off offset:64
	global_store_dwordx2 v[24:25], v[20:21], off offset:32
	s_nop 0
	v_pk_mul_f32 v[10:11], v[10:11], v[10:11]
	v_pk_mul_f32 v[12:13], v[12:13], v[12:13]
	v_add_f32_e32 v10, v10, v11
	v_add_f32_e32 v10, v12, v10
	v_add_f32_e32 v10, v13, v10
	v_add_f32_e32 v10, v14, v10
	s_waitcnt vmcnt(5)
	v_pk_add_f32 v[8:9], v[8:9], v[154:155]
	v_pk_add_f32 v[6:7], v[6:7], v[152:153]
	v_cvt_pk_bf16_f32 v21, v8, v9
	v_cvt_pk_bf16_f32 v20, v6, v7
	global_store_dwordx4 v[26:27], v[6:9], off offset:128
	global_store_dwordx2 v[24:25], v[20:21], off offset:64
	s_nop 0
	v_pk_mul_f32 v[6:7], v[6:7], v[6:7]
	v_pk_mul_f32 v[8:9], v[8:9], v[8:9]
	v_add_f32_e32 v6, v6, v7
	v_add_f32_e32 v6, v8, v6
	v_add_f32_e32 v6, v9, v6
	v_add_f32_e32 v10, v10, v6
	s_waitcnt vmcnt(6)
	v_pk_add_f32 v[2:3], v[2:3], v[156:157]
	v_pk_add_f32 v[4:5], v[4:5], v[158:159]
	v_pk_mul_f32 v[8:9], v[2:3], v[2:3]
	global_store_dwordx4 v[26:27], v[2:5], off offset:192
	v_pk_mul_f32 v[6:7], v[4:5], v[4:5]
	s_nop 0
	v_cvt_pk_bf16_f32 v2, v2, v3
	v_cvt_pk_bf16_f32 v3, v4, v5
	v_add_f32_e32 v4, v8, v9
	global_store_dwordx2 v[24:25], v[2:3], off offset:96
	v_add_f32_e32 v2, v6, v4
	v_lshlrev_b32_e32 v0, 2, v0
	v_add_f32_e32 v2, v7, v2
	v_xor_b32_e32 v0, 64, v0
	v_add_f32_e32 v2, v10, v2
	ds_bpermute_b32 v0, v0, v2
	v_mov_b32_e32 v3, v229
	s_waitcnt lgkmcnt(0)
	v_add_f32_e32 v0, v2, v0
	v_lshlrev_b32_e32 v3, 2, v3
	v_xor_b32_e32 v2, 0x80, v3
	ds_bpermute_b32 v2, v2, v0
	s_and_saveexec_b64 s[6:7], vcc
	s_cbranch_execz .LBB0_828
	v_ashrrev_i32_e32 v99, 31, v98
	v_lshl_add_u64 v[4:5], v[98:99], 2, v[18:19]
	s_waitcnt lgkmcnt(0)
	v_add_f32_e32 v0, v0, v2
	global_store_dword v[4:5], v0, off
	s_branch .LBB0_828

; DI u32 pack2(float a, float b) { f2_t v = {a, b}; bf2_t r = __builtin_convertvector(v, bf2_t); return __builtin_bit_cast(u32, r); }
; DI float shx(float v, int k) { return __int_as_float(__builtin_amdgcn_ds_bpermute((lane_id_l() ^ k) << 2, __float_as_int(v))); }
; DI void resid_store8(const f32x4v (&acc)[2][2][4][2], const float* xin, float* xout, u16* xb, float* ssp, int m0, int n0, bool wr_norm = true) {
;     ...
; #pragma unroll
;   for (int bj = 0; bj < 2; ++bj)
; #pragma unroll
;     for (int n = 0; n < 2; ++n) {
;       const int row = m0 + bj * 128 + wc * 32 + n * 16 + fr;
; #pragma unroll
;       for (int ai = 0; ai < 2; ++ai) {
;         float ss = 0.f;
;         const int cb = n0 + ai * 128 + wr * 64;
; #pragma unroll
;         for (int m = 0; m < 4; ++m) {
;           const size_t off = (size_t)row * 1024 + cb + m * 16 + fq * 4;
;           f32x4 v = *(const f32x4*)(xin + off);
;           f32x4v a = acc[ai][bj][m][n];
;           v.x += a.x; v.y += a.y; v.z += a.z; v.w += a.w;
;           *(f32x4*)(xout + off) = v;
;           ss += v.x * v.x + v.y * v.y + v.z * v.z + v.w * v.w;
;           if (wr_norm) { u32x2 o2; o2.x = pack2(v.x, v.y); o2.y = pack2(v.z, v.w); *(u32x2*)(xb + off) = o2; }
;         }
;         ss += shx(ss, 16);
;         ss += shx(ss, 32);
;         if (wr_norm && fq == 0) ssp[(size_t)row * 16 + (cb >> 6)] = ss;
;       }
.LBB0_983:
	s_or_b64 exec, exec, s[12:13]
	v_mov_b32_e32 v0, v250
	v_mov_b32_e32 v145, v229
	v_lshrrev_b32_e32 v131, 1, v0
	v_and_b32_e32 v130, 15, v0
	v_and_b32_e32 v131, 0x60, v131
	v_bfe_u32 v144, v0, 4, 2
	v_or3_b32 v132, v130, v131, s10
	v_ashrrev_i32_e32 v0, 2, v0
	v_and_b32_e32 v0, 0xffffffc0, v0
	v_ashrrev_i32_e32 v133, 31, v132
	v_add_u32_e32 v130, s6, v0
	v_lshlrev_b32_e32 v0, 2, v144
	v_lshlrev_b64 v[134:135], 10, v[132:133]
	v_or_b32_e32 v134, v134, v0
	v_ashrrev_i32_e32 v131, 31, v130
	v_readlane_b32 s6, v254, 60
	v_lshl_add_u64 v[140:141], v[134:135], 0, v[130:131]
	v_readlane_b32 s7, v254, 61
	s_lshl_b64 s[10:11], s[8:9], 23
	v_mov_b32_e32 v146, v229
	v_lshl_add_u64 v[142:143], v[140:141], 2, s[6:7]
	global_load_dwordx4 v[136:139], v[142:143], off
	global_load_dwordx4 v[148:151], v[142:143], off offset:64
	global_load_dwordx4 v[152:155], v[142:143], off offset:128
	global_load_dwordx4 v[156:159], v[142:143], off offset:192
	s_mul_i32 s7, s8, 0xc600000
	s_mul_hi_i32 s6, s8, 0xc600000
	s_add_u32 s7, s62, s7
	s_addc_u32 s12, s63, s6
	s_add_u32 s6, s7, s53
	s_addc_u32 s7, s12, s70
	v_lshl_add_u64 v[140:141], v[140:141], 1, s[6:7]
	s_lshl_b64 s[8:9], s[8:9], 18
	s_add_u32 s10, s6, s10
	s_addc_u32 s11, s7, s11
	s_add_u32 s10, s10, s8
	s_addc_u32 s11, s11, s9
	s_add_u32 s8, s10, s8
	s_addc_u32 s9, s11, s9
	v_cmp_eq_u32_e32 vcc, 0, v144
	s_waitcnt vmcnt(3)
	v_pk_add_f32 v[128:129], v[128:129], v[138:139]
	v_pk_add_f32 v[126:127], v[126:127], v[136:137]
	v_cvt_pk_bf16_f32 v137, v128, v129
	v_cvt_pk_bf16_f32 v136, v126, v127
	global_store_dwordx4 v[142:143], v[126:129], off
	global_store_dwordx2 v[140:141], v[136:137], off
	s_nop 0
	v_pk_mul_f32 v[126:127], v[126:127], v[126:127]
	v_pk_mul_f32 v[128:129], v[128:129], v[128:129]
	v_add_f32_e32 v126, v126, v127
	v_add_f32_e32 v126, v128, v126
	v_add_f32_e32 v126, v129, v126
	s_waitcnt vmcnt(4)
	v_pk_add_f32 v[124:125], v[124:125], v[150:151]
	v_pk_add_f32 v[122:123], v[122:123], v[148:149]
	v_cvt_pk_bf16_f32 v137, v124, v125
	v_cvt_pk_bf16_f32 v136, v122, v123
	global_store_dwordx4 v[142:143], v[122:125], off offset:64
	global_store_dwordx2 v[140:141], v[136:137], off offset:32
	s_nop 0
	v_pk_mul_f32 v[122:123], v[122:123], v[122:123]
	v_pk_mul_f32 v[124:125], v[124:125], v[124:125]
	v_add_f32_e32 v122, v122, v123
	v_add_f32_e32 v122, v124, v122
	v_add_f32_e32 v122, v125, v122
	v_add_f32_e32 v122, v126, v122
	s_waitcnt vmcnt(5)
	v_pk_add_f32 v[120:121], v[120:121], v[154:155]
	v_pk_add_f32 v[118:119], v[118:119], v[152:153]
	v_cvt_pk_bf16_f32 v137, v120, v121
	v_cvt_pk_bf16_f32 v136, v118, v119
	global_store_dwordx4 v[142:143], v[118:121], off offset:128
	global_store_dwordx2 v[140:141], v[136:137], off offset:64
	s_nop 0
	v_pk_mul_f32 v[118:119], v[118:119], v[118:119]
	v_pk_mul_f32 v[120:121], v[120:121], v[120:121]
	v_add_f32_e32 v118, v118, v119
	v_add_f32_e32 v118, v120, v118
	v_add_f32_e32 v118, v121, v118
	v_add_f32_e32 v122, v122, v118
	s_waitcnt vmcnt(6)
	v_pk_add_f32 v[114:115], v[114:115], v[156:157]
	v_pk_add_f32 v[116:117], v[116:117], v[158:159]
	v_pk_mul_f32 v[120:121], v[114:115], v[114:115]
	global_store_dwordx4 v[142:143], v[114:117], off offset:192
	v_pk_mul_f32 v[118:119], v[116:117], v[116:117]
	s_nop 0
	v_cvt_pk_bf16_f32 v114, v114, v115
	v_cvt_pk_bf16_f32 v115, v116, v117
	v_add_f32_e32 v116, v120, v121
	global_store_dwordx2 v[140:141], v[114:115], off offset:96
	v_add_f32_e32 v114, v118, v116
	v_add_f32_e32 v114, v119, v114
	v_lshlrev_b32_e32 v115, 2, v145
	v_xor_b32_e32 v115, 64, v115
	v_add_f32_e32 v114, v122, v114
	ds_bpermute_b32 v115, v115, v114
	s_waitcnt lgkmcnt(0)
	v_add_f32_e32 v116, v114, v115
	v_lshlrev_b32_e32 v117, 2, v146
	v_xor_b32_e32 v114, 0x80, v117
	ds_bpermute_b32 v117, v114, v116
	v_lshlrev_b64 v[114:115], 6, v[132:133]
	v_lshl_add_u64 v[118:119], s[8:9], 0, v[114:115]
	v_ashrrev_i32_e32 v114, 6, v130
	s_and_saveexec_b64 s[10:11], vcc
	s_cbranch_execz .LBB0_985
	v_ashrrev_i32_e32 v115, 31, v114
	v_lshl_add_u64 v[120:121], v[114:115], 2, v[118:119]
	s_waitcnt lgkmcnt(0)
	v_add_f32_e32 v115, v116, v117
	global_store_dword v[120:121], v115, off
.LBB0_985:
	s_or_b64 exec, exec, s[10:11]
	v_add_u32_e32 v116, 0x80, v130
	s_waitcnt lgkmcnt(0)
	v_ashrrev_i32_e32 v117, 31, v116
	v_readlane_b32 s10, v254, 60
	v_lshl_add_u64 v[124:125], v[134:135], 0, v[116:117]
	v_readlane_b32 s11, v254, 61
	s_nop 1
	v_lshl_add_u64 v[126:127], v[124:125], 2, s[10:11]
	global_load_dwordx4 v[120:123], v[126:127], off
	global_load_dwordx4 v[148:151], v[126:127], off offset:64
	global_load_dwordx4 v[152:155], v[126:127], off offset:128
	global_load_dwordx4 v[156:159], v[126:127], off offset:192
	v_lshl_add_u64 v[124:125], v[124:125], 1, s[6:7]
	s_waitcnt vmcnt(3)
	v_pk_add_f32 v[112:113], v[112:113], v[122:123]
	v_pk_add_f32 v[110:111], v[110:111], v[120:121]
	global_store_dwordx4 v[126:127], v[110:113], off
	v_pk_mul_f32 v[122:123], v[110:111], v[110:111]
	v_pk_mul_f32 v[120:121], v[112:113], v[112:113]
	v_cvt_pk_bf16_f32 v110, v110, v111
	v_cvt_pk_bf16_f32 v111, v112, v113
	global_store_dwordx2 v[124:125], v[110:111], off
	s_nop 0
	v_add_f32_e32 v115, v122, v123
	v_add_f32_e32 v115, v120, v115
	v_add_f32_e32 v115, v121, v115
	s_waitcnt vmcnt(4)
	v_pk_add_f32 v[108:109], v[108:109], v[150:151]
	v_pk_add_f32 v[106:107], v[106:107], v[148:149]
	global_store_dwordx4 v[126:127], v[106:109], off offset:64
	v_pk_mul_f32 v[112:113], v[106:107], v[106:107]
	v_pk_mul_f32 v[110:111], v[108:109], v[108:109]
	v_cvt_pk_bf16_f32 v106, v106, v107
	v_cvt_pk_bf16_f32 v107, v108, v109
	global_store_dwordx2 v[124:125], v[106:107], off offset:32
	s_nop 0
	v_add_f32_e32 v112, v112, v113
	v_add_f32_e32 v110, v110, v112
	v_add_f32_e32 v110, v111, v110
	v_add_f32_e32 v110, v115, v110
	s_waitcnt vmcnt(5)
; DI u32 pack2(float a, float b) { f2_t v = {a, b}; bf2_t r = __builtin_convertvector(v, bf2_t); return __builtin_bit_cast(u32, r); }
; DI float shx(float v, int k) { return __int_as_float(__builtin_amdgcn_ds_bpermute((lane_id_l() ^ k) << 2, __float_as_int(v))); }
; DI void resid_store8(const f32x4v (&acc)[2][2][4][2], const float* xin, float* xout, u16* xb, float* ssp, int m0, int n0, bool wr_norm = true) {
;     ...
; #pragma unroll
;   for (int bj = 0; bj < 2; ++bj)
; #pragma unroll
;     for (int n = 0; n < 2; ++n) {
;       const int row = m0 + bj * 128 + wc * 32 + n * 16 + fr;
; #pragma unroll
;       for (int ai = 0; ai < 2; ++ai) {
;         float ss = 0.f;
;         const int cb = n0 + ai * 128 + wr * 64;
; #pragma unroll
;         for (int m = 0; m < 4; ++m) {
;           const size_t off = (size_t)row * 1024 + cb + m * 16 + fq * 4;
;           f32x4 v = *(const f32x4*)(xin + off);
;           f32x4v a = acc[ai][bj][m][n];
;           v.x += a.x; v.y += a.y; v.z += a.z; v.w += a.w;
;           *(f32x4*)(xout + off) = v;
;           ss += v.x * v.x + v.y * v.y + v.z * v.z + v.w * v.w;
;           if (wr_norm) { u32x2 o2; o2.x = pack2(v.x, v.y); o2.y = pack2(v.z, v.w); *(u32x2*)(xb + off) = o2; }
;         }
;         ss += shx(ss, 16);
;         ss += shx(ss, 32);
;         if (wr_norm && fq == 0) ssp[(size_t)row * 16 + (cb >> 6)] = ss;
;       }
	v_pk_add_f32 v[104:105], v[104:105], v[154:155]
	v_pk_add_f32 v[102:103], v[102:103], v[152:153]
	global_store_dwordx4 v[126:127], v[102:105], off offset:128
	v_pk_mul_f32 v[108:109], v[102:103], v[102:103]
	v_pk_mul_f32 v[106:107], v[104:105], v[104:105]
	v_cvt_pk_bf16_f32 v102, v102, v103
	v_cvt_pk_bf16_f32 v103, v104, v105
	global_store_dwordx2 v[124:125], v[102:103], off offset:64
	s_nop 0
	v_add_f32_e32 v108, v108, v109
	v_add_f32_e32 v106, v106, v108
	v_add_f32_e32 v106, v107, v106
	v_add_f32_e32 v106, v110, v106
	s_waitcnt vmcnt(6)
	v_pk_add_f32 v[100:101], v[100:101], v[158:159]
	v_pk_add_f32 v[98:99], v[98:99], v[156:157]
	global_store_dwordx4 v[126:127], v[98:101], off offset:192
	v_pk_mul_f32 v[104:105], v[98:99], v[98:99]
	v_pk_mul_f32 v[102:103], v[100:101], v[100:101]
	v_cvt_pk_bf16_f32 v98, v98, v99
	v_cvt_pk_bf16_f32 v99, v100, v101
	v_add_f32_e32 v104, v104, v105
	global_store_dwordx2 v[124:125], v[98:99], off offset:96
	v_mov_b32_e32 v98, v229
	v_add_f32_e32 v102, v102, v104
	v_add_f32_e32 v102, v103, v102
	v_lshlrev_b32_e32 v98, 2, v98
	v_add_f32_e32 v102, v106, v102
	v_xor_b32_e32 v98, 64, v98
	ds_bpermute_b32 v98, v98, v102
	s_waitcnt lgkmcnt(0)
	v_add_f32_e32 v100, v102, v98
	v_mov_b32_e32 v98, v229
	s_nop 0
	v_lshlrev_b32_e32 v98, 2, v98
	v_xor_b32_e32 v98, 0x80, v98
	ds_bpermute_b32 v101, v98, v100
	v_ashrrev_i32_e32 v98, 6, v116
	s_and_saveexec_b64 s[10:11], vcc
	s_cbranch_execz .LBB0_987
	v_ashrrev_i32_e32 v99, 31, v98
	v_lshl_add_u64 v[102:103], v[98:99], 2, v[118:119]
	s_waitcnt lgkmcnt(0)
	v_add_f32_e32 v99, v100, v101
	global_store_dword v[102:103], v99, off
.LBB0_987:
	s_or_b64 exec, exec, s[10:11]
	v_or_b32_e32 v100, 16, v132
	s_waitcnt lgkmcnt(0)
	v_ashrrev_i32_e32 v101, 31, v100
	v_lshlrev_b64 v[102:103], 10, v[100:101]
	v_or_b32_e32 v102, v102, v0
	v_readlane_b32 s10, v254, 60
	v_lshl_add_u64 v[108:109], v[102:103], 0, v[130:131]
	v_readlane_b32 s11, v254, 61
	v_lshlrev_b64 v[100:101], 6, v[100:101]
	v_lshl_add_u64 v[100:101], s[8:9], 0, v[100:101]
	v_lshl_add_u64 v[110:111], v[108:109], 2, s[10:11]
	global_load_dwordx4 v[104:107], v[110:111], off
	global_load_dwordx4 v[148:151], v[110:111], off offset:64
	global_load_dwordx4 v[152:155], v[110:111], off offset:128
	global_load_dwordx4 v[156:159], v[110:111], off offset:192
	v_lshl_add_u64 v[108:109], v[108:109], 1, s[6:7]
	s_waitcnt vmcnt(3)
	v_pk_add_f32 v[96:97], v[96:97], v[106:107]
	v_pk_add_f32 v[94:95], v[94:95], v[104:105]
	global_store_dwordx4 v[110:111], v[94:97], off
	v_pk_mul_f32 v[106:107], v[94:95], v[94:95]
	v_pk_mul_f32 v[104:105], v[96:97], v[96:97]
	v_cvt_pk_bf16_f32 v94, v94, v95
	v_cvt_pk_bf16_f32 v95, v96, v97
	global_store_dwordx2 v[108:109], v[94:95], off
	s_nop 0
	v_add_f32_e32 v99, v106, v107
	v_add_f32_e32 v99, v104, v99
	v_add_f32_e32 v99, v105, v99
	s_waitcnt vmcnt(4)
	v_pk_add_f32 v[92:93], v[92:93], v[150:151]
	v_pk_add_f32 v[90:91], v[90:91], v[148:149]
	global_store_dwordx4 v[110:111], v[90:93], off offset:64
	v_pk_mul_f32 v[96:97], v[90:91], v[90:91]
	v_pk_mul_f32 v[94:95], v[92:93], v[92:93]
	v_cvt_pk_bf16_f32 v90, v90, v91
	v_cvt_pk_bf16_f32 v91, v92, v93
	global_store_dwordx2 v[108:109], v[90:91], off offset:32
	s_nop 0
	v_add_f32_e32 v96, v96, v97
	v_add_f32_e32 v94, v94, v96
	v_add_f32_e32 v94, v95, v94
	v_add_f32_e32 v94, v99, v94
	s_waitcnt vmcnt(5)
	v_pk_add_f32 v[88:89], v[88:89], v[154:155]
	v_pk_add_f32 v[86:87], v[86:87], v[152:153]
	global_store_dwordx4 v[110:111], v[86:89], off offset:128
	v_pk_mul_f32 v[92:93], v[86:87], v[86:87]
	v_pk_mul_f32 v[90:91], v[88:89], v[88:89]
	v_cvt_pk_bf16_f32 v86, v86, v87
	v_cvt_pk_bf16_f32 v87, v88, v89
	global_store_dwordx2 v[108:109], v[86:87], off offset:64
	s_nop 0
	v_add_f32_e32 v92, v92, v93
	v_add_f32_e32 v90, v90, v92
	v_add_f32_e32 v90, v91, v90
	v_add_f32_e32 v90, v94, v90
	s_waitcnt vmcnt(6)
	v_pk_add_f32 v[84:85], v[84:85], v[158:159]
	v_pk_add_f32 v[82:83], v[82:83], v[156:157]
	global_store_dwordx4 v[110:111], v[82:85], off offset:192
	v_pk_mul_f32 v[88:89], v[82:83], v[82:83]
	v_pk_mul_f32 v[86:87], v[84:85], v[84:85]
	v_cvt_pk_bf16_f32 v82, v82, v83
	v_cvt_pk_bf16_f32 v83, v84, v85
	v_add_f32_e32 v88, v88, v89
	global_store_dwordx2 v[108:109], v[82:83], off offset:96
	v_mov_b32_e32 v82, v229
	v_add_f32_e32 v86, v86, v88
	v_add_f32_e32 v86, v87, v86
	v_lshlrev_b32_e32 v82, 2, v82
	v_add_f32_e32 v86, v90, v86
	v_xor_b32_e32 v82, 64, v82
	ds_bpermute_b32 v82, v82, v86
	v_mov_b32_e32 v83, v229
	s_waitcnt lgkmcnt(0)
	v_add_f32_e32 v82, v86, v82
	v_lshlrev_b32_e32 v83, 2, v83
	v_xor_b32_e32 v83, 0x80, v83
	ds_bpermute_b32 v83, v83, v82
	s_and_saveexec_b64 s[10:11], vcc
	s_cbranch_execz .LBB0_989
	v_ashrrev_i32_e32 v115, 31, v114
	v_lshl_add_u64 v[84:85], v[114:115], 2, v[100:101]
	s_waitcnt lgkmcnt(0)
	v_add_f32_e32 v82, v82, v83
	global_store_dword v[84:85], v82, off
; DI u32 pack2(float a, float b) { f2_t v = {a, b}; bf2_t r = __builtin_convertvector(v, bf2_t); return __builtin_bit_cast(u32, r); }
; DI float shx(float v, int k) { return __int_as_float(__builtin_amdgcn_ds_bpermute((lane_id_l() ^ k) << 2, __float_as_int(v))); }
; DI void resid_store8(const f32x4v (&acc)[2][2][4][2], const float* xin, float* xout, u16* xb, float* ssp, int m0, int n0, bool wr_norm = true) {
;     ...
; #pragma unroll
;   for (int bj = 0; bj < 2; ++bj)
; #pragma unroll
;     for (int n = 0; n < 2; ++n) {
;       const int row = m0 + bj * 128 + wc * 32 + n * 16 + fr;
; #pragma unroll
;       for (int ai = 0; ai < 2; ++ai) {
;         float ss = 0.f;
;         const int cb = n0 + ai * 128 + wr * 64;
; #pragma unroll
;         for (int m = 0; m < 4; ++m) {
;           const size_t off = (size_t)row * 1024 + cb + m * 16 + fq * 4;
;           f32x4 v = *(const f32x4*)(xin + off);
;           f32x4v a = acc[ai][bj][m][n];
;           v.x += a.x; v.y += a.y; v.z += a.z; v.w += a.w;
;           *(f32x4*)(xout + off) = v;
;           ss += v.x * v.x + v.y * v.y + v.z * v.z + v.w * v.w;
;           if (wr_norm) { u32x2 o2; o2.x = pack2(v.x, v.y); o2.y = pack2(v.z, v.w); *(u32x2*)(xb + off) = o2; }
;         }
;         ss += shx(ss, 16);
;         ss += shx(ss, 32);
;         if (wr_norm && fq == 0) ssp[(size_t)row * 16 + (cb >> 6)] = ss;
;       }
.LBB0_989:
	s_or_b64 exec, exec, s[10:11]
	v_readlane_b32 s10, v254, 60
	v_lshl_add_u64 v[86:87], v[102:103], 0, v[116:117]
	v_readlane_b32 s11, v254, 61
	s_nop 1
	v_lshl_add_u64 v[88:89], v[86:87], 2, s[10:11]
	s_waitcnt lgkmcnt(0)
	global_load_dwordx4 v[82:85], v[88:89], off
	global_load_dwordx4 v[148:151], v[88:89], off offset:64
	global_load_dwordx4 v[152:155], v[88:89], off offset:128
	global_load_dwordx4 v[156:159], v[88:89], off offset:192
	v_lshl_add_u64 v[86:87], v[86:87], 1, s[6:7]
	s_waitcnt vmcnt(3)
	v_pk_add_f32 v[80:81], v[80:81], v[84:85]
	v_pk_add_f32 v[78:79], v[78:79], v[82:83]
	global_store_dwordx4 v[88:89], v[78:81], off
	v_pk_mul_f32 v[84:85], v[78:79], v[78:79]
	v_pk_mul_f32 v[82:83], v[80:81], v[80:81]
	v_cvt_pk_bf16_f32 v78, v78, v79
	v_cvt_pk_bf16_f32 v79, v80, v81
	global_store_dwordx2 v[86:87], v[78:79], off
	s_nop 0
	v_add_f32_e32 v84, v84, v85
	v_add_f32_e32 v82, v82, v84
	v_add_f32_e32 v82, v83, v82
	s_waitcnt vmcnt(4)
	v_pk_add_f32 v[76:77], v[76:77], v[150:151]
	v_pk_add_f32 v[74:75], v[74:75], v[148:149]
	global_store_dwordx4 v[88:89], v[74:77], off offset:64
	v_pk_mul_f32 v[80:81], v[74:75], v[74:75]
	v_pk_mul_f32 v[78:79], v[76:77], v[76:77]
	v_cvt_pk_bf16_f32 v74, v74, v75
	v_cvt_pk_bf16_f32 v75, v76, v77
	global_store_dwordx2 v[86:87], v[74:75], off offset:32
	s_nop 0
	v_add_f32_e32 v80, v80, v81
	v_add_f32_e32 v78, v78, v80
	v_add_f32_e32 v78, v79, v78
	v_add_f32_e32 v78, v82, v78
	s_waitcnt vmcnt(5)
	v_pk_add_f32 v[72:73], v[72:73], v[154:155]
	v_pk_add_f32 v[70:71], v[70:71], v[152:153]
	global_store_dwordx4 v[88:89], v[70:73], off offset:128
	v_pk_mul_f32 v[76:77], v[70:71], v[70:71]
	v_pk_mul_f32 v[74:75], v[72:73], v[72:73]
	v_cvt_pk_bf16_f32 v70, v70, v71
	v_cvt_pk_bf16_f32 v71, v72, v73
	global_store_dwordx2 v[86:87], v[70:71], off offset:64
	s_nop 0
	v_add_f32_e32 v76, v76, v77
	v_add_f32_e32 v74, v74, v76
	v_add_f32_e32 v74, v75, v74
	v_add_f32_e32 v74, v78, v74
	s_waitcnt vmcnt(6)
	v_pk_add_f32 v[68:69], v[68:69], v[158:159]
	v_pk_add_f32 v[66:67], v[66:67], v[156:157]
	global_store_dwordx4 v[88:89], v[66:69], off offset:192
	v_pk_mul_f32 v[72:73], v[66:67], v[66:67]
	v_pk_mul_f32 v[70:71], v[68:69], v[68:69]
	v_cvt_pk_bf16_f32 v66, v66, v67
	v_cvt_pk_bf16_f32 v67, v68, v69
	v_add_f32_e32 v72, v72, v73
	global_store_dwordx2 v[86:87], v[66:67], off offset:96
	v_mov_b32_e32 v66, v229
	v_add_f32_e32 v70, v70, v72
	v_add_f32_e32 v70, v71, v70
	v_lshlrev_b32_e32 v66, 2, v66
	v_add_f32_e32 v70, v74, v70
	v_xor_b32_e32 v66, 64, v66
	ds_bpermute_b32 v66, v66, v70
	v_mov_b32_e32 v67, v229
	s_waitcnt lgkmcnt(0)
	v_add_f32_e32 v66, v70, v66
	v_lshlrev_b32_e32 v67, 2, v67
	v_xor_b32_e32 v67, 0x80, v67
	ds_bpermute_b32 v67, v67, v66
	s_and_saveexec_b64 s[10:11], vcc
	s_cbranch_execz .LBB0_991
	v_ashrrev_i32_e32 v99, 31, v98
	v_lshl_add_u64 v[68:69], v[98:99], 2, v[100:101]
	s_waitcnt lgkmcnt(0)
	v_add_f32_e32 v66, v66, v67
	global_store_dword v[68:69], v66, off
.LBB0_991:
	s_or_b64 exec, exec, s[10:11]
	v_or_b32_e32 v66, 0x80, v132
	s_waitcnt lgkmcnt(0)
	v_ashrrev_i32_e32 v67, 31, v66
	v_lshlrev_b64 v[68:69], 10, v[66:67]
	v_or_b32_e32 v68, v68, v0
	v_readlane_b32 s10, v254, 60
	v_lshl_add_u64 v[74:75], v[68:69], 0, v[130:131]
	v_readlane_b32 s11, v254, 61
	v_lshlrev_b64 v[66:67], 6, v[66:67]
	v_lshl_add_u64 v[66:67], s[8:9], 0, v[66:67]
	v_lshl_add_u64 v[76:77], v[74:75], 2, s[10:11]
	global_load_dwordx4 v[70:73], v[76:77], off
	global_load_dwordx4 v[148:151], v[76:77], off offset:64
	global_load_dwordx4 v[152:155], v[76:77], off offset:128
	global_load_dwordx4 v[156:159], v[76:77], off offset:192
	v_lshl_add_u64 v[74:75], v[74:75], 1, s[6:7]
	s_waitcnt vmcnt(3)
	v_pk_add_f32 v[64:65], v[64:65], v[72:73]
	v_pk_add_f32 v[62:63], v[62:63], v[70:71]
	global_store_dwordx4 v[76:77], v[62:65], off
	v_pk_mul_f32 v[72:73], v[62:63], v[62:63]
	v_pk_mul_f32 v[70:71], v[64:65], v[64:65]
	v_cvt_pk_bf16_f32 v62, v62, v63
	v_cvt_pk_bf16_f32 v63, v64, v65
	global_store_dwordx2 v[74:75], v[62:63], off
	s_nop 0
	v_add_f32_e32 v72, v72, v73
	v_add_f32_e32 v70, v70, v72
	v_add_f32_e32 v70, v71, v70
	s_waitcnt vmcnt(4)
	v_pk_add_f32 v[60:61], v[60:61], v[150:151]
	v_pk_add_f32 v[58:59], v[58:59], v[148:149]
	global_store_dwordx4 v[76:77], v[58:61], off offset:64
	v_pk_mul_f32 v[64:65], v[58:59], v[58:59]
	v_pk_mul_f32 v[62:63], v[60:61], v[60:61]
	v_cvt_pk_bf16_f32 v58, v58, v59
	v_cvt_pk_bf16_f32 v59, v60, v61
	global_store_dwordx2 v[74:75], v[58:59], off offset:32
	s_nop 0
	v_add_f32_e32 v64, v64, v65
	v_add_f32_e32 v62, v62, v64
	v_add_f32_e32 v62, v63, v62
	v_add_f32_e32 v62, v70, v62
	s_waitcnt vmcnt(5)
	v_pk_add_f32 v[56:57], v[56:57], v[154:155]
	v_pk_add_f32 v[54:55], v[54:55], v[152:153]
	global_store_dwordx4 v[76:77], v[54:57], off offset:128
	v_pk_mul_f32 v[60:61], v[54:55], v[54:55]
	v_pk_mul_f32 v[58:59], v[56:57], v[56:57]
	v_cvt_pk_bf16_f32 v54, v54, v55
	v_cvt_pk_bf16_f32 v55, v56, v57
	global_store_dwordx2 v[74:75], v[54:55], off offset:64
	s_nop 0
	v_add_f32_e32 v60, v60, v61
	v_add_f32_e32 v58, v58, v60
	v_add_f32_e32 v58, v59, v58
	v_add_f32_e32 v58, v62, v58
	s_waitcnt vmcnt(6)
	v_pk_add_f32 v[52:53], v[52:53], v[158:159]
	v_pk_add_f32 v[50:51], v[50:51], v[156:157]
	global_store_dwordx4 v[76:77], v[50:53], off offset:192
	v_pk_mul_f32 v[56:57], v[50:51], v[50:51]
	v_pk_mul_f32 v[54:55], v[52:53], v[52:53]
	v_cvt_pk_bf16_f32 v50, v50, v51
	v_cvt_pk_bf16_f32 v51, v52, v53
	v_add_f32_e32 v56, v56, v57
	global_store_dwordx2 v[74:75], v[50:51], off offset:96
	v_mov_b32_e32 v50, v229
	v_add_f32_e32 v54, v54, v56
	v_add_f32_e32 v54, v55, v54
	v_lshlrev_b32_e32 v50, 2, v50
	v_add_f32_e32 v54, v58, v54
	v_xor_b32_e32 v50, 64, v50
	ds_bpermute_b32 v50, v50, v54
	v_mov_b32_e32 v51, v229
	s_waitcnt lgkmcnt(0)
	v_add_f32_e32 v50, v54, v50
	v_lshlrev_b32_e32 v51, 2, v51
	v_xor_b32_e32 v51, 0x80, v51
	ds_bpermute_b32 v51, v51, v50
	s_and_saveexec_b64 s[10:11], vcc
	s_cbranch_execz .LBB0_993
	v_ashrrev_i32_e32 v115, 31, v114
	v_lshl_add_u64 v[52:53], v[114:115], 2, v[66:67]
	s_waitcnt lgkmcnt(0)
	v_add_f32_e32 v50, v50, v51
	global_store_dword v[52:53], v50, off
; DI u32 pack2(float a, float b) { f2_t v = {a, b}; bf2_t r = __builtin_convertvector(v, bf2_t); return __builtin_bit_cast(u32, r); }
; DI float shx(float v, int k) { return __int_as_float(__builtin_amdgcn_ds_bpermute((lane_id_l() ^ k) << 2, __float_as_int(v))); }
; DI void resid_store8(const f32x4v (&acc)[2][2][4][2], const float* xin, float* xout, u16* xb, float* ssp, int m0, int n0, bool wr_norm = true) {
;     ...
; #pragma unroll
;   for (int bj = 0; bj < 2; ++bj)
; #pragma unroll
;     for (int n = 0; n < 2; ++n) {
;       const int row = m0 + bj * 128 + wc * 32 + n * 16 + fr;
; #pragma unroll
;       for (int ai = 0; ai < 2; ++ai) {
;         float ss = 0.f;
;         const int cb = n0 + ai * 128 + wr * 64;
; #pragma unroll
;         for (int m = 0; m < 4; ++m) {
;           const size_t off = (size_t)row * 1024 + cb + m * 16 + fq * 4;
;           f32x4 v = *(const f32x4*)(xin + off);
;           f32x4v a = acc[ai][bj][m][n];
;           v.x += a.x; v.y += a.y; v.z += a.z; v.w += a.w;
;           *(f32x4*)(xout + off) = v;
;           ss += v.x * v.x + v.y * v.y + v.z * v.z + v.w * v.w;
;           if (wr_norm) { u32x2 o2; o2.x = pack2(v.x, v.y); o2.y = pack2(v.z, v.w); *(u32x2*)(xb + off) = o2; }
;         }
;         ss += shx(ss, 16);
;         ss += shx(ss, 32);
;         if (wr_norm && fq == 0) ssp[(size_t)row * 16 + (cb >> 6)] = ss;
;       }
.LBB0_993:
	s_or_b64 exec, exec, s[10:11]
	v_readlane_b32 s10, v254, 60
	v_lshl_add_u64 v[54:55], v[68:69], 0, v[116:117]
	v_readlane_b32 s11, v254, 61
	s_nop 1
	v_lshl_add_u64 v[56:57], v[54:55], 2, s[10:11]
	s_waitcnt lgkmcnt(0)
	global_load_dwordx4 v[50:53], v[56:57], off
	global_load_dwordx4 v[148:151], v[56:57], off offset:64
	global_load_dwordx4 v[152:155], v[56:57], off offset:128
	global_load_dwordx4 v[156:159], v[56:57], off offset:192
	v_lshl_add_u64 v[54:55], v[54:55], 1, s[6:7]
	s_waitcnt vmcnt(3)
	v_pk_add_f32 v[48:49], v[48:49], v[52:53]
	v_pk_add_f32 v[46:47], v[46:47], v[50:51]
	global_store_dwordx4 v[56:57], v[46:49], off
	v_pk_mul_f32 v[52:53], v[46:47], v[46:47]
	v_pk_mul_f32 v[50:51], v[48:49], v[48:49]
	v_cvt_pk_bf16_f32 v46, v46, v47
	v_cvt_pk_bf16_f32 v47, v48, v49
	global_store_dwordx2 v[54:55], v[46:47], off
	s_nop 0
	v_add_f32_e32 v52, v52, v53
	v_add_f32_e32 v50, v50, v52
	v_add_f32_e32 v50, v51, v50
	s_waitcnt vmcnt(4)
	v_pk_add_f32 v[44:45], v[44:45], v[150:151]
	v_pk_add_f32 v[42:43], v[42:43], v[148:149]
	global_store_dwordx4 v[56:57], v[42:45], off offset:64
	v_pk_mul_f32 v[48:49], v[42:43], v[42:43]
	v_pk_mul_f32 v[46:47], v[44:45], v[44:45]
	v_cvt_pk_bf16_f32 v42, v42, v43
	v_cvt_pk_bf16_f32 v43, v44, v45
	global_store_dwordx2 v[54:55], v[42:43], off offset:32
	s_nop 0
	v_add_f32_e32 v48, v48, v49
	v_add_f32_e32 v46, v46, v48
	v_add_f32_e32 v46, v47, v46
	v_add_f32_e32 v46, v50, v46
	s_waitcnt vmcnt(5)
	v_pk_add_f32 v[40:41], v[40:41], v[154:155]
	v_pk_add_f32 v[38:39], v[38:39], v[152:153]
	global_store_dwordx4 v[56:57], v[38:41], off offset:128
	v_pk_mul_f32 v[44:45], v[38:39], v[38:39]
	v_pk_mul_f32 v[42:43], v[40:41], v[40:41]
	v_cvt_pk_bf16_f32 v38, v38, v39
	v_cvt_pk_bf16_f32 v39, v40, v41
	global_store_dwordx2 v[54:55], v[38:39], off offset:64
	s_nop 0
	v_add_f32_e32 v44, v44, v45
	v_add_f32_e32 v42, v42, v44
	v_add_f32_e32 v42, v43, v42
	v_add_f32_e32 v42, v46, v42
	s_waitcnt vmcnt(6)
	v_pk_add_f32 v[36:37], v[36:37], v[158:159]
	v_pk_add_f32 v[34:35], v[34:35], v[156:157]
	global_store_dwordx4 v[56:57], v[34:37], off offset:192
	v_pk_mul_f32 v[40:41], v[34:35], v[34:35]
	v_pk_mul_f32 v[38:39], v[36:37], v[36:37]
	v_cvt_pk_bf16_f32 v34, v34, v35
	v_cvt_pk_bf16_f32 v35, v36, v37
	v_add_f32_e32 v40, v40, v41
	global_store_dwordx2 v[54:55], v[34:35], off offset:96
	v_mov_b32_e32 v34, v229
	v_add_f32_e32 v38, v38, v40
	v_add_f32_e32 v38, v39, v38
	v_lshlrev_b32_e32 v34, 2, v34
	v_add_f32_e32 v38, v42, v38
	v_xor_b32_e32 v34, 64, v34
	ds_bpermute_b32 v34, v34, v38
	v_mov_b32_e32 v35, v229
	s_waitcnt lgkmcnt(0)
	v_add_f32_e32 v34, v38, v34
	v_lshlrev_b32_e32 v35, 2, v35
	v_xor_b32_e32 v35, 0x80, v35
	ds_bpermute_b32 v35, v35, v34
	s_and_saveexec_b64 s[10:11], vcc
	s_cbranch_execz .LBB0_995
	v_ashrrev_i32_e32 v99, 31, v98
	v_lshl_add_u64 v[36:37], v[98:99], 2, v[66:67]
	s_waitcnt lgkmcnt(0)
	v_add_f32_e32 v34, v34, v35
	global_store_dword v[36:37], v34, off
; DI u32 pack2(float a, float b) { f2_t v = {a, b}; bf2_t r = __builtin_convertvector(v, bf2_t); return __builtin_bit_cast(u32, r); }
; DI float shx(float v, int k) { return __int_as_float(__builtin_amdgcn_ds_bpermute((lane_id_l() ^ k) << 2, __float_as_int(v))); }
; DI void resid_store8(const f32x4v (&acc)[2][2][4][2], const float* xin, float* xout, u16* xb, float* ssp, int m0, int n0, bool wr_norm = true) {
;     ...
; #pragma unroll
;   for (int bj = 0; bj < 2; ++bj)
; #pragma unroll
;     for (int n = 0; n < 2; ++n) {
;       const int row = m0 + bj * 128 + wc * 32 + n * 16 + fr;
; #pragma unroll
;       for (int ai = 0; ai < 2; ++ai) {
;         float ss = 0.f;
;         const int cb = n0 + ai * 128 + wr * 64;
; #pragma unroll
;         for (int m = 0; m < 4; ++m) {
;           const size_t off = (size_t)row * 1024 + cb + m * 16 + fq * 4;
;           f32x4 v = *(const f32x4*)(xin + off);
;           f32x4v a = acc[ai][bj][m][n];
;           v.x += a.x; v.y += a.y; v.z += a.z; v.w += a.w;
;           *(f32x4*)(xout + off) = v;
;           ss += v.x * v.x + v.y * v.y + v.z * v.z + v.w * v.w;
;           if (wr_norm) { u32x2 o2; o2.x = pack2(v.x, v.y); o2.y = pack2(v.z, v.w); *(u32x2*)(xb + off) = o2; }
;         }
;         ss += shx(ss, 16);
;         ss += shx(ss, 32);
;         if (wr_norm && fq == 0) ssp[(size_t)row * 16 + (cb >> 6)] = ss;
;       }
.LBB0_995:
	s_or_b64 exec, exec, s[10:11]
	v_or_b32_e32 v34, 0x90, v132
	s_waitcnt lgkmcnt(0)
	v_ashrrev_i32_e32 v35, 31, v34
	v_lshlrev_b64 v[36:37], 10, v[34:35]
	v_lshlrev_b64 v[34:35], 6, v[34:35]
	v_or_b32_e32 v36, v36, v0
	v_lshl_add_u64 v[34:35], s[8:9], 0, v[34:35]
	v_readlane_b32 s8, v254, 60
	v_lshl_add_u64 v[42:43], v[36:37], 0, v[130:131]
	v_readlane_b32 s9, v254, 61
	s_nop 1
	v_lshl_add_u64 v[44:45], v[42:43], 2, s[8:9]
	global_load_dwordx4 v[38:41], v[44:45], off
	global_load_dwordx4 v[148:151], v[44:45], off offset:64
	global_load_dwordx4 v[152:155], v[44:45], off offset:128
	global_load_dwordx4 v[156:159], v[44:45], off offset:192
	v_lshl_add_u64 v[42:43], v[42:43], 1, s[6:7]
	s_waitcnt vmcnt(3)
	v_pk_add_f32 v[32:33], v[32:33], v[40:41]
	v_pk_add_f32 v[30:31], v[30:31], v[38:39]
	global_store_dwordx4 v[44:45], v[30:33], off
	v_pk_mul_f32 v[40:41], v[30:31], v[30:31]
	v_pk_mul_f32 v[38:39], v[32:33], v[32:33]
	v_cvt_pk_bf16_f32 v30, v30, v31
	v_cvt_pk_bf16_f32 v31, v32, v33
	global_store_dwordx2 v[42:43], v[30:31], off
	s_nop 0
	v_add_f32_e32 v0, v40, v41
	v_add_f32_e32 v0, v38, v0
	v_add_f32_e32 v0, v39, v0
	s_waitcnt vmcnt(4)
	v_pk_add_f32 v[28:29], v[28:29], v[150:151]
	v_pk_add_f32 v[26:27], v[26:27], v[148:149]
	global_store_dwordx4 v[44:45], v[26:29], off offset:64
	v_pk_mul_f32 v[32:33], v[26:27], v[26:27]
	v_pk_mul_f32 v[30:31], v[28:29], v[28:29]
	v_cvt_pk_bf16_f32 v26, v26, v27
	v_cvt_pk_bf16_f32 v27, v28, v29
	global_store_dwordx2 v[42:43], v[26:27], off offset:32
	s_nop 0
	v_add_f32_e32 v32, v32, v33
	v_add_f32_e32 v30, v30, v32
	v_add_f32_e32 v30, v31, v30
	v_add_f32_e32 v0, v0, v30
	s_waitcnt vmcnt(5)
	v_pk_add_f32 v[24:25], v[24:25], v[154:155]
	v_pk_add_f32 v[22:23], v[22:23], v[152:153]
	global_store_dwordx4 v[44:45], v[22:25], off offset:128
	v_pk_mul_f32 v[28:29], v[22:23], v[22:23]
	v_pk_mul_f32 v[26:27], v[24:25], v[24:25]
	v_cvt_pk_bf16_f32 v22, v22, v23
	v_cvt_pk_bf16_f32 v23, v24, v25
	global_store_dwordx2 v[42:43], v[22:23], off offset:64
	s_nop 0
	v_add_f32_e32 v28, v28, v29
	v_add_f32_e32 v26, v26, v28
	v_add_f32_e32 v26, v27, v26
	v_add_f32_e32 v0, v0, v26
	s_waitcnt vmcnt(6)
	v_pk_add_f32 v[20:21], v[20:21], v[158:159]
	v_pk_add_f32 v[18:19], v[18:19], v[156:157]
	global_store_dwordx4 v[44:45], v[18:21], off offset:192
	v_pk_mul_f32 v[24:25], v[18:19], v[18:19]
	v_pk_mul_f32 v[22:23], v[20:21], v[20:21]
	v_cvt_pk_bf16_f32 v18, v18, v19
	v_cvt_pk_bf16_f32 v19, v20, v21
	v_add_f32_e32 v24, v24, v25
	global_store_dwordx2 v[42:43], v[18:19], off offset:96
	v_mov_b32_e32 v18, v229
	v_add_f32_e32 v22, v22, v24
	v_add_f32_e32 v22, v23, v22
	v_lshlrev_b32_e32 v18, 2, v18
	v_add_f32_e32 v0, v0, v22
	v_xor_b32_e32 v18, 64, v18
	ds_bpermute_b32 v18, v18, v0
	s_waitcnt lgkmcnt(0)
	v_add_f32_e32 v0, v0, v18
	v_mov_b32_e32 v18, v229
	s_nop 0
	v_lshlrev_b32_e32 v18, 2, v18
	v_xor_b32_e32 v18, 0x80, v18
	ds_bpermute_b32 v18, v18, v0
	s_and_saveexec_b64 s[8:9], vcc
	s_cbranch_execz .LBB0_997
	v_ashrrev_i32_e32 v115, 31, v114
	v_lshl_add_u64 v[20:21], v[114:115], 2, v[34:35]
	s_waitcnt lgkmcnt(0)
	v_add_f32_e32 v0, v0, v18
	global_store_dword v[20:21], v0, off
.LBB0_997:
	s_or_b64 exec, exec, s[8:9]
	v_readlane_b32 s8, v254, 60
	v_lshl_add_u64 v[22:23], v[36:37], 0, v[116:117]
	v_readlane_b32 s9, v254, 61
	s_nop 1
	v_lshl_add_u64 v[24:25], v[22:23], 2, s[8:9]
	s_waitcnt lgkmcnt(0)
	global_load_dwordx4 v[18:21], v[24:25], off
	global_load_dwordx4 v[148:151], v[24:25], off offset:64
	global_load_dwordx4 v[152:155], v[24:25], off offset:128
	global_load_dwordx4 v[156:159], v[24:25], off offset:192
	v_lshl_add_u64 v[22:23], v[22:23], 1, s[6:7]
	s_waitcnt vmcnt(3)
	v_pk_add_f32 v[16:17], v[16:17], v[20:21]
	v_pk_add_f32 v[14:15], v[14:15], v[18:19]
	global_store_dwordx4 v[24:25], v[14:17], off
	v_pk_mul_f32 v[20:21], v[14:15], v[14:15]
	v_pk_mul_f32 v[18:19], v[16:17], v[16:17]
	v_cvt_pk_bf16_f32 v14, v14, v15
	v_cvt_pk_bf16_f32 v15, v16, v17
	global_store_dwordx2 v[22:23], v[14:15], off
	s_nop 0
	v_add_f32_e32 v0, v20, v21
	v_add_f32_e32 v0, v18, v0
	v_add_f32_e32 v0, v19, v0
	s_waitcnt vmcnt(4)
	v_pk_add_f32 v[12:13], v[12:13], v[150:151]
	v_pk_add_f32 v[10:11], v[10:11], v[148:149]
	global_store_dwordx4 v[24:25], v[10:13], off offset:64
	v_pk_mul_f32 v[16:17], v[10:11], v[10:11]
	v_pk_mul_f32 v[14:15], v[12:13], v[12:13]
	v_cvt_pk_bf16_f32 v10, v10, v11
	v_cvt_pk_bf16_f32 v11, v12, v13
	global_store_dwordx2 v[22:23], v[10:11], off offset:32
	s_nop 0
	v_add_f32_e32 v16, v16, v17
	v_add_f32_e32 v14, v14, v16
	v_add_f32_e32 v14, v15, v14
	v_add_f32_e32 v0, v0, v14
	s_waitcnt vmcnt(5)
	v_pk_add_f32 v[8:9], v[8:9], v[154:155]
	v_pk_add_f32 v[6:7], v[6:7], v[152:153]
	global_store_dwordx4 v[24:25], v[6:9], off offset:128
	v_pk_mul_f32 v[12:13], v[6:7], v[6:7]
	v_pk_mul_f32 v[10:11], v[8:9], v[8:9]
	v_cvt_pk_bf16_f32 v6, v6, v7
	v_cvt_pk_bf16_f32 v7, v8, v9
	global_store_dwordx2 v[22:23], v[6:7], off offset:64
	s_nop 0
	v_add_f32_e32 v12, v12, v13
	v_add_f32_e32 v10, v10, v12
	v_add_f32_e32 v10, v11, v10
	v_add_f32_e32 v0, v0, v10
	s_waitcnt vmcnt(6)
	v_pk_add_f32 v[4:5], v[4:5], v[158:159]
	v_pk_add_f32 v[2:3], v[2:3], v[156:157]
	global_store_dwordx4 v[24:25], v[2:5], off offset:192
	v_pk_mul_f32 v[8:9], v[2:3], v[2:3]
	v_pk_mul_f32 v[6:7], v[4:5], v[4:5]
	v_cvt_pk_bf16_f32 v2, v2, v3
	v_cvt_pk_bf16_f32 v3, v4, v5
	v_add_f32_e32 v8, v8, v9
	global_store_dwordx2 v[22:23], v[2:3], off offset:96
	v_mov_b32_e32 v2, v229
	v_add_f32_e32 v6, v6, v8
	v_add_f32_e32 v6, v7, v6
	v_lshlrev_b32_e32 v2, 2, v2
	v_add_f32_e32 v0, v0, v6
	v_xor_b32_e32 v2, 64, v2
	ds_bpermute_b32 v2, v2, v0
	s_waitcnt lgkmcnt(0)
	v_add_f32_e32 v0, v0, v2
	v_mov_b32_e32 v2, v229
	s_nop 0
	v_lshlrev_b32_e32 v2, 2, v2
	v_xor_b32_e32 v2, 0x80, v2
	ds_bpermute_b32 v2, v2, v0
	s_and_saveexec_b64 s[6:7], vcc
	s_cbranch_execz .LBB0_976
	v_ashrrev_i32_e32 v99, 31, v98
	v_lshl_add_u64 v[4:5], v[98:99], 2, v[34:35]
	s_waitcnt lgkmcnt(0)
	v_add_f32_e32 v0, v0, v2
	global_store_dword v[4:5], v0, off
	s_branch .LBB0_976

; DI u32 pack2(float a, float b) { f2_t v = {a, b}; bf2_t r = __builtin_convertvector(v, bf2_t); return __builtin_bit_cast(u32, r); }
; DI float bflo(u32 v) { return __uint_as_float(v << 16); }
; DI float bfhi(u32 v) { return __uint_as_float(v & 0xffff0000u); }
; DI float sigmoidf_(float x) { return __builtin_amdgcn_rcpf(1.f + __builtin_amdgcn_exp2f(-LOG2E * x)); }
; DI void resid_store8(const f32x4v (&acc)[2][2][4][2], const float* xin, float* xout, u16* xb, float* ssp, int m0, int n0, bool wr_norm = true) {
;     ...
; #pragma unroll
;   for (int bj = 0; bj < 2; ++bj)
; #pragma unroll
;     for (int n = 0; n < 2; ++n) {
;       const int row = m0 + bj * 128 + wc * 32 + n * 16 + fr;
; #pragma unroll
;       for (int ai = 0; ai < 2; ++ai) {
;         float ss = 0.f;
;         const int cb = n0 + ai * 128 + wr * 64;
; #pragma unroll
;         for (int m = 0; m < 4; ++m) {
;           const size_t off = (size_t)row * 1024 + cb + m * 16 + fq * 4;
;           f32x4 v = *(const f32x4*)(xin + off);
;           f32x4v a = acc[ai][bj][m][n];
;           v.x += a.x; v.y += a.y; v.z += a.z; v.w += a.w;
;           *(f32x4*)(xout + off) = v;
;           ss += v.x * v.x + v.y * v.y + v.z * v.z + v.w * v.w;
;           if (wr_norm) { u32x2 o2; o2.x = pack2(v.x, v.y); o2.y = pack2(v.z, v.w); *(u32x2*)(xb + off) = o2; }
; DI void ple_tile8(const WsPtrs& W, int layer, float* x, int mt, int nt, unsigned char* smem, bool feed_next) {
;     ...
;         const int tl = bj * 128 + wc * 32 + n * 16 + fr;
;         const float rv = rs[tl];
;         const u16* pp = W.MERGED + (size_t)(m0 + tl) * 1024 + n0 + wr * 64 + fq * 4;
; #pragma unroll
;         for (int ai = 0; ai < 2; ++ai)
; #pragma unroll
;           for (int m = 0; m < 4; ++m) {
;             const u32x2 pv = *(const u32x2*)(pp + ai * 128 + m * 16);
;             f32x4v a = acc[ai][bj][m][n];
;             a.x = sigmoidf_(a.x * rv) * bflo(pv.x); a.y = sigmoidf_(a.y * rv) * bfhi(pv.x);
;             a.z = sigmoidf_(a.z * rv) * bflo(pv.y); a.w = sigmoidf_(a.w * rv) * bfhi(pv.y);
;             acc[ai][bj][m][n] = a;
;           }
;       }
;   }
;   resid_store8(acc, x, x, W.XB, W.SSA, m0, n0, feed_next);
.LBB0_1069:
	s_or_b64 exec, exec, s[12:13]
	v_mov_b32_e32 v0, v250
	s_movk_i32 s5, 0x60
	v_and_b32_e32 v130, 15, v0
	v_lshrrev_b32_e32 v132, 1, v0
	s_lshl_b64 s[12:13], s[10:11], 1
	v_ashrrev_i32_e32 v0, 2, v0
	v_and_or_b32 v134, v132, s5, v130
	s_add_u32 s12, s25, s12
	v_and_b32_e32 v130, 0xffffffc0, v0
	s_addc_u32 s13, s26, s13
	v_ashrrev_i32_e32 v131, 31, v130
	v_and_b32_e32 v0, 24, v132
	v_or_b32_e32 v132, s4, v134
	v_lshl_add_u64 v[130:131], v[130:131], 1, s[12:13]
	s_add_i32 s5, 64, 0x24000
	v_ashrrev_i32_e32 v133, 31, v132
	v_lshl_add_u64 v[130:131], v[130:131], 0, v[0:1]
	v_lshl_add_u32 v0, v134, 2, s5
	v_lshlrev_b64 v[132:133], 11, v[132:133]
	ds_read_b32 v205, v0
	v_lshl_add_u64 v[132:133], v[130:131], 0, v[132:133]
	v_or_b32_e32 v0, 16, v134
	global_load_dwordx2 v[198:199], v[132:133], off
	global_load_dwordx2 v[200:201], v[132:133], off offset:32
	global_load_dwordx2 v[196:197], v[132:133], off offset:64
	global_load_dwordx2 v[192:193], v[132:133], off offset:96
	global_load_dwordx2 v[188:189], v[132:133], off offset:256
	global_load_dwordx2 v[186:187], v[132:133], off offset:288
	global_load_dwordx2 v[184:185], v[132:133], off offset:320
	global_load_dwordx2 v[182:183], v[132:133], off offset:352
	v_lshl_add_u32 v132, v0, 2, s5
	ds_read_b32 v204, v132
	v_or_b32_e32 v132, s4, v0
	v_ashrrev_i32_e32 v133, 31, v132
	v_lshlrev_b64 v[132:133], 11, v[132:133]
	v_lshl_add_u64 v[132:133], v[130:131], 0, v[132:133]
	v_or_b32_e32 v0, 0x80, v134
	global_load_dwordx2 v[180:181], v[132:133], off
	global_load_dwordx2 v[178:179], v[132:133], off offset:32
	global_load_dwordx2 v[176:177], v[132:133], off offset:64
	global_load_dwordx2 v[174:175], v[132:133], off offset:96
	global_load_dwordx2 v[172:173], v[132:133], off offset:256
	global_load_dwordx2 v[170:171], v[132:133], off offset:288
	global_load_dwordx2 v[168:169], v[132:133], off offset:320
	global_load_dwordx2 v[166:167], v[132:133], off offset:352
	v_lshl_add_u32 v132, v0, 2, s5
	ds_read_b32 v203, v132
	v_or_b32_e32 v132, s4, v0
	v_ashrrev_i32_e32 v133, 31, v132
	v_lshlrev_b64 v[132:133], 11, v[132:133]
	v_lshl_add_u64 v[132:133], v[130:131], 0, v[132:133]
	global_load_dwordx2 v[164:165], v[132:133], off
	global_load_dwordx2 v[162:163], v[132:133], off offset:32
	global_load_dwordx2 v[160:161], v[132:133], off offset:64
	global_load_dwordx2 v[158:159], v[132:133], off offset:96
	global_load_dwordx2 v[156:157], v[132:133], off offset:256
	global_load_dwordx2 v[154:155], v[132:133], off offset:288
	global_load_dwordx2 v[152:153], v[132:133], off offset:320
	global_load_dwordx2 v[150:151], v[132:133], off offset:352
	v_or_b32_e32 v132, 0x90, v134
	v_lshl_add_u32 v0, v132, 2, s5
	v_or_b32_e32 v132, s4, v132
	v_ashrrev_i32_e32 v133, 31, v132
	v_lshlrev_b64 v[132:133], 11, v[132:133]
	v_lshl_add_u64 v[130:131], v[130:131], 0, v[132:133]
	v_mov_b32_e32 v146, v250
	ds_read_b32 v0, v0
	global_load_dwordx2 v[144:145], v[130:131], off
	global_load_dwordx2 v[142:143], v[130:131], off offset:32
	global_load_dwordx2 v[140:141], v[130:131], off offset:64
	global_load_dwordx2 v[138:139], v[130:131], off offset:96
	global_load_dwordx2 v[136:137], v[130:131], off offset:256
	global_load_dwordx2 v[134:135], v[130:131], off offset:288
	global_load_dwordx2 v[132:133], v[130:131], off offset:320
	s_nop 0
	global_load_dwordx2 v[130:131], v[130:131], off offset:352
	s_waitcnt lgkmcnt(0)
	v_mul_f32_e32 v128, v128, v205
	v_lshrrev_b32_e32 v148, 1, v146
	v_and_b32_e32 v147, 15, v146
	v_and_b32_e32 v148, 0x60, v148
	v_bfe_u32 v206, v146, 4, 2
	v_or3_b32 v148, v147, v148, s4
	v_ashrrev_i32_e32 v146, 2, v146
	v_and_b32_e32 v146, 0xffffffc0, v146
	v_ashrrev_i32_e32 v149, 31, v148
	v_add_u32_e32 v146, s10, v146
	v_lshlrev_b32_e32 v202, 2, v206
	v_lshlrev_b64 v[190:191], 10, v[148:149]
	v_or_b32_e32 v190, v190, v202
	v_ashrrev_i32_e32 v147, 31, v146
	v_readlane_b32 s4, v254, 60
	v_lshl_add_u64 v[212:213], v[190:191], 0, v[146:147]
	v_readlane_b32 s5, v254, 61
	v_mul_f32_e32 v129, v129, v205
	v_mul_f32_e32 v126, v126, v205
	v_lshl_add_u64 v[194:195], v[212:213], 2, s[4:5]
	global_load_dwordx4 v[208:211], v[194:195], off
	global_load_dwordx4 v[216:219], v[194:195], off offset:64
	global_load_dwordx4 v[220:223], v[194:195], off offset:128
	global_load_dwordx4 v[224:227], v[194:195], off offset:192
	v_mul_f32_e32 v127, v127, v205
	v_mul_f32_e32 v128, 0xbfb8aa3b, v128
	v_mul_f32_e32 v129, 0xbfb8aa3b, v129
	v_mul_f32_e32 v126, 0xbfb8aa3b, v126
	v_mul_f32_e32 v127, 0xbfb8aa3b, v127
	v_exp_f32_e32 v128, v128
	v_exp_f32_e32 v129, v129
	v_exp_f32_e32 v126, v126
	v_exp_f32_e32 v127, v127
	v_add_f32_e32 v128, 1.0, v128
	v_add_f32_e32 v129, 1.0, v129
	v_add_f32_e32 v126, 1.0, v126
	v_add_f32_e32 v127, 1.0, v127
	v_rcp_f32_e32 v128, v128
	v_rcp_f32_e32 v129, v129
	v_rcp_f32_e32 v126, v126
	v_rcp_f32_e32 v127, v127
	v_readlane_b32 s10, v255, 9
	v_readlane_b32 s11, v255, 10
	s_andn2_b64 vcc, exec, s[10:11]
	s_waitcnt vmcnt(3)
	v_lshlrev_b32_e32 v214, 16, v198
	v_and_b32_e32 v215, 0xffff0000, v198
	v_lshlrev_b32_e32 v198, 16, v199
	v_and_b32_e32 v199, 0xffff0000, v199
	v_pk_fma_f32 v[128:129], v[128:129], v[198:199], v[210:211]
	v_cndmask_b32_e64 v198, 0, 1, s[10:11]
	v_pk_fma_f32 v[126:127], v[126:127], v[214:215], v[208:209]
	v_cmp_ne_u32_e64 s[4:5], 1, v198
	v_lshl_add_u64 v[198:199], v[212:213], 1, s[6:7]
	global_store_dwordx4 v[194:195], v[126:129], off
	s_cbranch_vccnz .LBB0_1071
	v_cvt_pk_bf16_f32 v208, v126, v127
	v_cvt_pk_bf16_f32 v209, v128, v129
	global_store_dwordx2 v[198:199], v[208:209], off
; DI u32 pack2(float a, float b) { f2_t v = {a, b}; bf2_t r = __builtin_convertvector(v, bf2_t); return __builtin_bit_cast(u32, r); }
; DI float bflo(u32 v) { return __uint_as_float(v << 16); }
; DI float bfhi(u32 v) { return __uint_as_float(v & 0xffff0000u); }
; DI float sigmoidf_(float x) { return __builtin_amdgcn_rcpf(1.f + __builtin_amdgcn_exp2f(-LOG2E * x)); }
; DI void resid_store8(const f32x4v (&acc)[2][2][4][2], const float* xin, float* xout, u16* xb, float* ssp, int m0, int n0, bool wr_norm = true) {
;     ...
;         for (int m = 0; m < 4; ++m) {
;           const size_t off = (size_t)row * 1024 + cb + m * 16 + fq * 4;
;           f32x4 v = *(const f32x4*)(xin + off);
;           f32x4v a = acc[ai][bj][m][n];
;           v.x += a.x; v.y += a.y; v.z += a.z; v.w += a.w;
;           *(f32x4*)(xout + off) = v;
;           ss += v.x * v.x + v.y * v.y + v.z * v.z + v.w * v.w;
;           if (wr_norm) { u32x2 o2; o2.x = pack2(v.x, v.y); o2.y = pack2(v.z, v.w); *(u32x2*)(xb + off) = o2; }
; DI void ple_tile8(const WsPtrs& W, int layer, float* x, int mt, int nt, unsigned char* smem, bool feed_next) {
;     ...
;         for (int ai = 0; ai < 2; ++ai)
; #pragma unroll
;           for (int m = 0; m < 4; ++m) {
;             const u32x2 pv = *(const u32x2*)(pp + ai * 128 + m * 16);
;             f32x4v a = acc[ai][bj][m][n];
;             a.x = sigmoidf_(a.x * rv) * bflo(pv.x); a.y = sigmoidf_(a.y * rv) * bfhi(pv.x);
;             a.z = sigmoidf_(a.z * rv) * bflo(pv.y); a.w = sigmoidf_(a.w * rv) * bfhi(pv.y);
;             acc[ai][bj][m][n] = a;
;           }
;       }
;   }
;   resid_store8(acc, x, x, W.XB, W.SSA, m0, n0, feed_next);
.LBB0_1071:
	s_nop 0
	v_mul_f32_e32 v207, v122, v205
	v_mul_f32_e32 v212, v123, v205
	v_mul_f32_e32 v124, v124, v205
	v_mul_f32_e32 v125, v125, v205
	v_lshlrev_b32_e32 v122, 16, v200
	v_and_b32_e32 v123, 0xffff0000, v200
	v_mul_f32_e32 v200, 0xbfb8aa3b, v207
	v_mul_f32_e32 v207, 0xbfb8aa3b, v212
	v_mul_f32_e32 v124, 0xbfb8aa3b, v124
	v_mul_f32_e32 v125, 0xbfb8aa3b, v125
	v_exp_f32_e32 v200, v200
	v_exp_f32_e32 v207, v207
	v_exp_f32_e32 v124, v124
	v_exp_f32_e32 v125, v125
	v_add_f32_e32 v200, 1.0, v200
	v_add_f32_e32 v207, 1.0, v207
	v_add_f32_e32 v212, 1.0, v124
	v_add_f32_e32 v213, 1.0, v125
	v_rcp_f32_e32 v124, v200
	v_rcp_f32_e32 v125, v207
	v_rcp_f32_e32 v212, v212
	v_rcp_f32_e32 v213, v213
	v_lshlrev_b32_e32 v200, 16, v201
	v_and_b32_e32 v201, 0xffff0000, v201
	s_and_b64 vcc, exec, s[4:5]
	s_waitcnt vmcnt(3)
	v_pk_fma_f32 v[122:123], v[124:125], v[122:123], v[216:217]
	v_pk_fma_f32 v[124:125], v[212:213], v[200:201], v[218:219]
	global_store_dwordx4 v[194:195], v[122:125], off offset:64
	s_cbranch_vccnz .LBB0_1073
	v_cvt_pk_bf16_f32 v200, v122, v123
	v_cvt_pk_bf16_f32 v201, v124, v125
	global_store_dwordx2 v[198:199], v[200:201], off offset:32
.LBB0_1073:
	s_nop 0
	v_mul_f32_e32 v200, v118, v205
	v_mul_f32_e32 v201, v119, v205
	v_mul_f32_e32 v120, v120, v205
	v_mul_f32_e32 v121, v121, v205
	v_lshlrev_b32_e32 v118, 16, v196
	v_and_b32_e32 v119, 0xffff0000, v196
	v_mul_f32_e32 v196, 0xbfb8aa3b, v200
	v_mul_f32_e32 v200, 0xbfb8aa3b, v201
	v_mul_f32_e32 v120, 0xbfb8aa3b, v120
	v_mul_f32_e32 v121, 0xbfb8aa3b, v121
	v_exp_f32_e32 v196, v196
	v_exp_f32_e32 v200, v200
	v_exp_f32_e32 v120, v120
	v_exp_f32_e32 v121, v121
	v_add_f32_e32 v196, 1.0, v196
	v_add_f32_e32 v200, 1.0, v200
	v_add_f32_e32 v201, 1.0, v120
	v_add_f32_e32 v207, 1.0, v121
	v_rcp_f32_e32 v120, v196
	v_rcp_f32_e32 v121, v200
	v_rcp_f32_e32 v200, v201
	v_rcp_f32_e32 v201, v207
	v_lshlrev_b32_e32 v196, 16, v197
	v_and_b32_e32 v197, 0xffff0000, v197
	s_and_b64 vcc, exec, s[4:5]
	s_waitcnt vmcnt(3)
	v_pk_fma_f32 v[118:119], v[120:121], v[118:119], v[220:221]
	v_pk_fma_f32 v[120:121], v[200:201], v[196:197], v[222:223]
	global_store_dwordx4 v[194:195], v[118:121], off offset:128
	s_cbranch_vccnz .LBB0_1075
	v_cvt_pk_bf16_f32 v196, v118, v119
	v_cvt_pk_bf16_f32 v197, v120, v121
	global_store_dwordx2 v[198:199], v[196:197], off offset:64
.LBB0_1075:
	s_nop 0
	v_mul_f32_e32 v196, v114, v205
	v_mul_f32_e32 v197, v115, v205
	v_mul_f32_e32 v116, v116, v205
	v_mul_f32_e32 v117, v117, v205
	v_lshlrev_b32_e32 v114, 16, v192
	v_and_b32_e32 v115, 0xffff0000, v192
	v_mul_f32_e32 v192, 0xbfb8aa3b, v196
	v_mul_f32_e32 v196, 0xbfb8aa3b, v197
	v_mul_f32_e32 v116, 0xbfb8aa3b, v116
	v_mul_f32_e32 v117, 0xbfb8aa3b, v117
	v_exp_f32_e32 v192, v192
	v_exp_f32_e32 v196, v196
	v_exp_f32_e32 v116, v116
	v_exp_f32_e32 v117, v117
	v_add_f32_e32 v192, 1.0, v192
	v_add_f32_e32 v196, 1.0, v196
	v_add_f32_e32 v197, 1.0, v116
	v_add_f32_e32 v200, 1.0, v117
	v_rcp_f32_e32 v116, v192
	v_rcp_f32_e32 v117, v196
	v_rcp_f32_e32 v196, v197
	v_rcp_f32_e32 v197, v200
	v_lshlrev_b32_e32 v192, 16, v193
	v_and_b32_e32 v193, 0xffff0000, v193
	s_and_b64 vcc, exec, s[4:5]
	s_waitcnt vmcnt(3)
	v_pk_fma_f32 v[114:115], v[116:117], v[114:115], v[224:225]
	v_pk_fma_f32 v[116:117], v[196:197], v[192:193], v[226:227]
	global_store_dwordx4 v[194:195], v[114:117], off offset:192
	s_cbranch_vccnz .LBB0_1077
	v_cvt_pk_bf16_f32 v192, v114, v115
	v_cvt_pk_bf16_f32 v193, v116, v117
	global_store_dwordx2 v[198:199], v[192:193], off offset:96

; DI u32 pack2(float a, float b) { f2_t v = {a, b}; bf2_t r = __builtin_convertvector(v, bf2_t); return __builtin_bit_cast(u32, r); }
; DI float bflo(u32 v) { return __uint_as_float(v << 16); }
; DI float bfhi(u32 v) { return __uint_as_float(v & 0xffff0000u); }
; DI float sigmoidf_(float x) { return __builtin_amdgcn_rcpf(1.f + __builtin_amdgcn_exp2f(-LOG2E * x)); }
; DI void resid_store8(const f32x4v (&acc)[2][2][4][2], const float* xin, float* xout, u16* xb, float* ssp, int m0, int n0, bool wr_norm = true) {
;     ...
;         for (int m = 0; m < 4; ++m) {
;           const size_t off = (size_t)row * 1024 + cb + m * 16 + fq * 4;
;           f32x4 v = *(const f32x4*)(xin + off);
;           f32x4v a = acc[ai][bj][m][n];
;           v.x += a.x; v.y += a.y; v.z += a.z; v.w += a.w;
;           *(f32x4*)(xout + off) = v;
;           ss += v.x * v.x + v.y * v.y + v.z * v.z + v.w * v.w;
;           if (wr_norm) { u32x2 o2; o2.x = pack2(v.x, v.y); o2.y = pack2(v.z, v.w); *(u32x2*)(xb + off) = o2; }
; DI void ple_tile8(const WsPtrs& W, int layer, float* x, int mt, int nt, unsigned char* smem, bool feed_next) {
;     ...
;         for (int ai = 0; ai < 2; ++ai)
; #pragma unroll
;           for (int m = 0; m < 4; ++m) {
;             const u32x2 pv = *(const u32x2*)(pp + ai * 128 + m * 16);
;             f32x4v a = acc[ai][bj][m][n];
;             a.x = sigmoidf_(a.x * rv) * bflo(pv.x); a.y = sigmoidf_(a.y * rv) * bfhi(pv.x);
;             a.z = sigmoidf_(a.z * rv) * bflo(pv.y); a.w = sigmoidf_(a.w * rv) * bfhi(pv.y);
;             acc[ai][bj][m][n] = a;
;           }
;       }
;   }
;   resid_store8(acc, x, x, W.XB, W.SSA, m0, n0, feed_next);
.LBB0_1079:
	s_or_b64 exec, exec, s[12:13]
	v_add_u32_e32 v116, 0x80, v146
	s_waitcnt lgkmcnt(0)
	v_ashrrev_i32_e32 v117, 31, v116
	v_readlane_b32 s12, v254, 60
	v_lshl_add_u64 v[126:127], v[190:191], 0, v[116:117]
	v_readlane_b32 s13, v254, 61
	v_mul_f32_e32 v115, v110, v205
	v_mul_f32_e32 v128, v111, v205
	v_lshl_add_u64 v[120:121], v[126:127], 2, s[12:13]
	global_load_dwordx4 v[122:125], v[120:121], off
	global_load_dwordx4 v[216:219], v[120:121], off offset:64
	global_load_dwordx4 v[220:223], v[120:121], off offset:128
	global_load_dwordx4 v[224:227], v[120:121], off offset:192
	v_mul_f32_e32 v129, v112, v205
	v_mul_f32_e32 v113, v113, v205
	v_mul_f32_e32 v115, 0xbfb8aa3b, v115
	v_mul_f32_e32 v128, 0xbfb8aa3b, v128
	v_mul_f32_e32 v129, 0xbfb8aa3b, v129
	v_mul_f32_e32 v113, 0xbfb8aa3b, v113
	v_exp_f32_e32 v115, v115
	v_exp_f32_e32 v128, v128
	v_exp_f32_e32 v129, v129
	v_exp_f32_e32 v113, v113
	v_lshlrev_b32_e32 v110, 16, v188
	v_and_b32_e32 v111, 0xffff0000, v188
	v_add_f32_e32 v115, 1.0, v115
	v_add_f32_e32 v149, 1.0, v128
	v_add_f32_e32 v188, 1.0, v129
	v_add_f32_e32 v113, 1.0, v113
	v_rcp_f32_e32 v128, v115
	v_rcp_f32_e32 v129, v149
	v_rcp_f32_e32 v190, v188
	v_rcp_f32_e32 v191, v113
	v_lshlrev_b32_e32 v112, 16, v189
	v_and_b32_e32 v113, 0xffff0000, v189
	s_and_b64 vcc, exec, s[4:5]
	s_waitcnt vmcnt(3)
	v_pk_fma_f32 v[110:111], v[128:129], v[110:111], v[122:123]
	v_pk_fma_f32 v[112:113], v[190:191], v[112:113], v[124:125]
	v_lshl_add_u64 v[122:123], v[126:127], 1, s[6:7]
	global_store_dwordx4 v[120:121], v[110:113], off
	s_cbranch_vccnz .LBB0_1081
	v_cvt_pk_bf16_f32 v124, v110, v111
	v_cvt_pk_bf16_f32 v125, v112, v113
	global_store_dwordx2 v[122:123], v[124:125], off
.LBB0_1081:
	s_nop 0
	v_mul_f32_e32 v115, v106, v205
	v_mul_f32_e32 v128, v107, v205
	v_mul_f32_e32 v108, v108, v205
	v_mul_f32_e32 v109, v109, v205
	v_mul_f32_e32 v115, 0xbfb8aa3b, v115
	v_mul_f32_e32 v128, 0xbfb8aa3b, v128
	v_mul_f32_e32 v108, 0xbfb8aa3b, v108
	v_mul_f32_e32 v109, 0xbfb8aa3b, v109
	v_exp_f32_e32 v115, v115
	v_exp_f32_e32 v128, v128
	v_exp_f32_e32 v108, v108
	v_exp_f32_e32 v109, v109
	v_add_f32_e32 v115, 1.0, v115
	v_add_f32_e32 v128, 1.0, v128
	v_add_f32_e32 v129, 1.0, v108
	v_add_f32_e32 v149, 1.0, v109
	v_rcp_f32_e32 v108, v115
	v_rcp_f32_e32 v109, v128
	v_rcp_f32_e32 v128, v129
	v_rcp_f32_e32 v129, v149
	v_lshlrev_b32_e32 v106, 16, v186
	v_and_b32_e32 v107, 0xffff0000, v186
	v_lshlrev_b32_e32 v186, 16, v187
	v_and_b32_e32 v187, 0xffff0000, v187
	s_and_b64 vcc, exec, s[4:5]
	s_waitcnt vmcnt(3)
	v_pk_fma_f32 v[106:107], v[108:109], v[106:107], v[216:217]
	v_pk_fma_f32 v[108:109], v[128:129], v[186:187], v[218:219]
	global_store_dwordx4 v[120:121], v[106:109], off offset:64
	s_cbranch_vccnz .LBB0_1083
	v_cvt_pk_bf16_f32 v124, v106, v107
	v_cvt_pk_bf16_f32 v125, v108, v109
	global_store_dwordx2 v[122:123], v[124:125], off offset:32
.LBB0_1083:
	s_nop 0
	v_mul_f32_e32 v115, v102, v205
	v_mul_f32_e32 v128, v103, v205
	v_mul_f32_e32 v104, v104, v205
	v_mul_f32_e32 v105, v105, v205
	v_mul_f32_e32 v115, 0xbfb8aa3b, v115
	v_mul_f32_e32 v128, 0xbfb8aa3b, v128
	v_mul_f32_e32 v104, 0xbfb8aa3b, v104
	v_mul_f32_e32 v105, 0xbfb8aa3b, v105
	v_exp_f32_e32 v115, v115
	v_exp_f32_e32 v128, v128
	v_exp_f32_e32 v104, v104
	v_exp_f32_e32 v105, v105
	v_add_f32_e32 v115, 1.0, v115
	v_add_f32_e32 v128, 1.0, v128
	v_add_f32_e32 v129, 1.0, v104
	v_add_f32_e32 v149, 1.0, v105
	v_rcp_f32_e32 v104, v115
	v_rcp_f32_e32 v105, v128
	v_rcp_f32_e32 v128, v129
	v_rcp_f32_e32 v129, v149
	v_lshlrev_b32_e32 v102, 16, v184
	v_and_b32_e32 v103, 0xffff0000, v184
	v_lshlrev_b32_e32 v184, 16, v185
	v_and_b32_e32 v185, 0xffff0000, v185
	s_and_b64 vcc, exec, s[4:5]
	s_waitcnt vmcnt(3)
	v_pk_fma_f32 v[102:103], v[104:105], v[102:103], v[220:221]
	v_pk_fma_f32 v[104:105], v[128:129], v[184:185], v[222:223]
	global_store_dwordx4 v[120:121], v[102:105], off offset:128
	s_cbranch_vccnz .LBB0_1085
	v_cvt_pk_bf16_f32 v124, v102, v103
	v_cvt_pk_bf16_f32 v125, v104, v105
	global_store_dwordx2 v[122:123], v[124:125], off offset:64
.LBB0_1085:
	s_nop 0
	v_mul_f32_e32 v115, v98, v205
	v_mul_f32_e32 v128, v99, v205
	v_mul_f32_e32 v100, v100, v205
	v_mul_f32_e32 v101, v101, v205
	v_mul_f32_e32 v115, 0xbfb8aa3b, v115
	v_mul_f32_e32 v128, 0xbfb8aa3b, v128
	v_mul_f32_e32 v100, 0xbfb8aa3b, v100
	v_mul_f32_e32 v101, 0xbfb8aa3b, v101
	v_exp_f32_e32 v115, v115
	v_exp_f32_e32 v128, v128
	v_exp_f32_e32 v100, v100
	v_exp_f32_e32 v101, v101
	v_add_f32_e32 v115, 1.0, v115
	v_add_f32_e32 v128, 1.0, v128
	v_add_f32_e32 v129, 1.0, v100
	v_add_f32_e32 v149, 1.0, v101
	v_rcp_f32_e32 v100, v115
	v_rcp_f32_e32 v101, v128
	v_rcp_f32_e32 v128, v129
	v_rcp_f32_e32 v129, v149
	v_lshlrev_b32_e32 v98, 16, v182
	v_and_b32_e32 v99, 0xffff0000, v182
	v_lshlrev_b32_e32 v182, 16, v183
	v_and_b32_e32 v183, 0xffff0000, v183
	s_and_b64 vcc, exec, s[4:5]
	s_waitcnt vmcnt(3)
	v_pk_fma_f32 v[98:99], v[100:101], v[98:99], v[224:225]
	v_pk_fma_f32 v[100:101], v[128:129], v[182:183], v[226:227]
	global_store_dwordx4 v[120:121], v[98:101], off offset:192
	s_cbranch_vccnz .LBB0_1087
	v_cvt_pk_bf16_f32 v120, v98, v99
	v_cvt_pk_bf16_f32 v121, v100, v101
	global_store_dwordx2 v[122:123], v[120:121], off offset:96

; DI u32 pack2(float a, float b) { f2_t v = {a, b}; bf2_t r = __builtin_convertvector(v, bf2_t); return __builtin_bit_cast(u32, r); }
; DI float bflo(u32 v) { return __uint_as_float(v << 16); }
; DI float bfhi(u32 v) { return __uint_as_float(v & 0xffff0000u); }
; DI float sigmoidf_(float x) { return __builtin_amdgcn_rcpf(1.f + __builtin_amdgcn_exp2f(-LOG2E * x)); }
; DI void resid_store8(const f32x4v (&acc)[2][2][4][2], const float* xin, float* xout, u16* xb, float* ssp, int m0, int n0, bool wr_norm = true) {
;     ...
;         for (int m = 0; m < 4; ++m) {
;           const size_t off = (size_t)row * 1024 + cb + m * 16 + fq * 4;
;           f32x4 v = *(const f32x4*)(xin + off);
;           f32x4v a = acc[ai][bj][m][n];
;           v.x += a.x; v.y += a.y; v.z += a.z; v.w += a.w;
;           *(f32x4*)(xout + off) = v;
;           ss += v.x * v.x + v.y * v.y + v.z * v.z + v.w * v.w;
;           if (wr_norm) { u32x2 o2; o2.x = pack2(v.x, v.y); o2.y = pack2(v.z, v.w); *(u32x2*)(xb + off) = o2; }
; DI void ple_tile8(const WsPtrs& W, int layer, float* x, int mt, int nt, unsigned char* smem, bool feed_next) {
;     ...
;         for (int ai = 0; ai < 2; ++ai)
; #pragma unroll
;           for (int m = 0; m < 4; ++m) {
;             const u32x2 pv = *(const u32x2*)(pp + ai * 128 + m * 16);
;             f32x4v a = acc[ai][bj][m][n];
;             a.x = sigmoidf_(a.x * rv) * bflo(pv.x); a.y = sigmoidf_(a.y * rv) * bfhi(pv.x);
;             a.z = sigmoidf_(a.z * rv) * bflo(pv.y); a.w = sigmoidf_(a.w * rv) * bfhi(pv.y);
;             acc[ai][bj][m][n] = a;
;           }
;       }
;   }
;   resid_store8(acc, x, x, W.XB, W.SSA, m0, n0, feed_next);
.LBB0_1089:
	s_or_b64 exec, exec, s[12:13]
	v_or_b32_e32 v102, 16, v148
	v_ashrrev_i32_e32 v103, 31, v102
	s_waitcnt lgkmcnt(0)
	v_lshlrev_b64 v[100:101], 10, v[102:103]
	v_or_b32_e32 v100, v100, v202
	v_readlane_b32 s12, v254, 60
	v_lshl_add_u64 v[110:111], v[100:101], 0, v[146:147]
	v_readlane_b32 s13, v254, 61
	v_mul_f32_e32 v99, v94, v204
	v_mul_f32_e32 v112, v95, v204
	v_lshl_add_u64 v[104:105], v[110:111], 2, s[12:13]
	global_load_dwordx4 v[106:109], v[104:105], off
	global_load_dwordx4 v[216:219], v[104:105], off offset:64
	global_load_dwordx4 v[220:223], v[104:105], off offset:128
	global_load_dwordx4 v[224:227], v[104:105], off offset:192
	v_mul_f32_e32 v113, v96, v204
	v_mul_f32_e32 v97, v97, v204
	v_mul_f32_e32 v99, 0xbfb8aa3b, v99
	v_mul_f32_e32 v112, 0xbfb8aa3b, v112
	v_mul_f32_e32 v113, 0xbfb8aa3b, v113
	v_mul_f32_e32 v97, 0xbfb8aa3b, v97
	v_exp_f32_e32 v99, v99
	v_exp_f32_e32 v112, v112
	v_exp_f32_e32 v113, v113
	v_exp_f32_e32 v97, v97
	v_add_f32_e32 v99, 1.0, v99
	v_add_f32_e32 v115, 1.0, v112
	v_add_f32_e32 v118, 1.0, v113
	v_add_f32_e32 v97, 1.0, v97
	v_rcp_f32_e32 v112, v99
	v_rcp_f32_e32 v113, v115
	v_rcp_f32_e32 v118, v118
	v_rcp_f32_e32 v119, v97
	v_lshlrev_b32_e32 v94, 16, v180
	v_and_b32_e32 v95, 0xffff0000, v180
	v_lshlrev_b32_e32 v96, 16, v181
	v_and_b32_e32 v97, 0xffff0000, v181
	s_and_b64 vcc, exec, s[4:5]
	s_waitcnt vmcnt(3)
	v_pk_fma_f32 v[94:95], v[112:113], v[94:95], v[106:107]
	v_pk_fma_f32 v[96:97], v[118:119], v[96:97], v[108:109]
	v_lshl_add_u64 v[106:107], v[110:111], 1, s[6:7]
	global_store_dwordx4 v[104:105], v[94:97], off
	s_cbranch_vccnz .LBB0_1091
	v_cvt_pk_bf16_f32 v108, v94, v95
	v_cvt_pk_bf16_f32 v109, v96, v97
	global_store_dwordx2 v[106:107], v[108:109], off
.LBB0_1091:
	s_nop 0
	v_mul_f32_e32 v99, v90, v204
	v_mul_f32_e32 v112, v91, v204
	v_mul_f32_e32 v92, v92, v204
	v_mul_f32_e32 v93, v93, v204
	v_mul_f32_e32 v99, 0xbfb8aa3b, v99
	v_mul_f32_e32 v112, 0xbfb8aa3b, v112
	v_mul_f32_e32 v92, 0xbfb8aa3b, v92
	v_mul_f32_e32 v93, 0xbfb8aa3b, v93
	v_exp_f32_e32 v99, v99
	v_exp_f32_e32 v112, v112
	v_exp_f32_e32 v92, v92
	v_exp_f32_e32 v93, v93
	v_add_f32_e32 v99, 1.0, v99
	v_add_f32_e32 v112, 1.0, v112
	v_add_f32_e32 v113, 1.0, v92
	v_add_f32_e32 v115, 1.0, v93
	v_rcp_f32_e32 v92, v99
	v_rcp_f32_e32 v93, v112
	v_rcp_f32_e32 v112, v113
	v_rcp_f32_e32 v113, v115
	v_lshlrev_b32_e32 v90, 16, v178
	v_and_b32_e32 v91, 0xffff0000, v178
	v_lshlrev_b32_e32 v118, 16, v179
	v_and_b32_e32 v119, 0xffff0000, v179
	s_and_b64 vcc, exec, s[4:5]
	s_waitcnt vmcnt(3)
	v_pk_fma_f32 v[90:91], v[92:93], v[90:91], v[216:217]
	v_pk_fma_f32 v[92:93], v[112:113], v[118:119], v[218:219]
	global_store_dwordx4 v[104:105], v[90:93], off offset:64
	s_cbranch_vccnz .LBB0_1093
	v_cvt_pk_bf16_f32 v108, v90, v91
	v_cvt_pk_bf16_f32 v109, v92, v93
	global_store_dwordx2 v[106:107], v[108:109], off offset:32
.LBB0_1093:
	s_nop 0
	v_mul_f32_e32 v99, v86, v204
	v_mul_f32_e32 v112, v87, v204
	v_mul_f32_e32 v88, v88, v204
	v_mul_f32_e32 v89, v89, v204
	v_mul_f32_e32 v99, 0xbfb8aa3b, v99
	v_mul_f32_e32 v112, 0xbfb8aa3b, v112
	v_mul_f32_e32 v88, 0xbfb8aa3b, v88
	v_mul_f32_e32 v89, 0xbfb8aa3b, v89
	v_exp_f32_e32 v99, v99
	v_exp_f32_e32 v112, v112
	v_exp_f32_e32 v88, v88
	v_exp_f32_e32 v89, v89
	v_add_f32_e32 v99, 1.0, v99
	v_add_f32_e32 v112, 1.0, v112
	v_add_f32_e32 v113, 1.0, v88
	v_add_f32_e32 v115, 1.0, v89
	v_rcp_f32_e32 v88, v99
	v_rcp_f32_e32 v89, v112
	v_rcp_f32_e32 v112, v113
	v_rcp_f32_e32 v113, v115
	v_lshlrev_b32_e32 v86, 16, v176
	v_and_b32_e32 v87, 0xffff0000, v176
	v_lshlrev_b32_e32 v118, 16, v177
	v_and_b32_e32 v119, 0xffff0000, v177
	s_and_b64 vcc, exec, s[4:5]
	s_waitcnt vmcnt(3)
	v_pk_fma_f32 v[86:87], v[88:89], v[86:87], v[220:221]
	v_pk_fma_f32 v[88:89], v[112:113], v[118:119], v[222:223]
	global_store_dwordx4 v[104:105], v[86:89], off offset:128
	s_cbranch_vccnz .LBB0_1095
	v_cvt_pk_bf16_f32 v108, v86, v87
	v_cvt_pk_bf16_f32 v109, v88, v89
	global_store_dwordx2 v[106:107], v[108:109], off offset:64
.LBB0_1095:
	s_nop 0
	v_mul_f32_e32 v99, v82, v204
	v_mul_f32_e32 v112, v83, v204
	v_mul_f32_e32 v84, v84, v204
	v_mul_f32_e32 v85, v85, v204
	v_mul_f32_e32 v99, 0xbfb8aa3b, v99
	v_mul_f32_e32 v112, 0xbfb8aa3b, v112
	v_mul_f32_e32 v84, 0xbfb8aa3b, v84
	v_mul_f32_e32 v85, 0xbfb8aa3b, v85
	v_exp_f32_e32 v99, v99
	v_exp_f32_e32 v112, v112
	v_exp_f32_e32 v84, v84
	v_exp_f32_e32 v85, v85
	v_add_f32_e32 v99, 1.0, v99
	v_add_f32_e32 v112, 1.0, v112
	v_add_f32_e32 v113, 1.0, v84
	v_add_f32_e32 v115, 1.0, v85
	v_rcp_f32_e32 v84, v99
	v_rcp_f32_e32 v85, v112
	v_rcp_f32_e32 v112, v113
	v_rcp_f32_e32 v113, v115
	v_lshlrev_b32_e32 v82, 16, v174
	v_and_b32_e32 v83, 0xffff0000, v174
	v_lshlrev_b32_e32 v118, 16, v175
	v_and_b32_e32 v119, 0xffff0000, v175
	s_and_b64 vcc, exec, s[4:5]
	s_waitcnt vmcnt(3)
	v_pk_fma_f32 v[82:83], v[84:85], v[82:83], v[224:225]
	v_pk_fma_f32 v[84:85], v[112:113], v[118:119], v[226:227]
	global_store_dwordx4 v[104:105], v[82:85], off offset:192
	s_cbranch_vccnz .LBB0_1097
	v_cvt_pk_bf16_f32 v104, v82, v83
	v_cvt_pk_bf16_f32 v105, v84, v85
	global_store_dwordx2 v[106:107], v[104:105], off offset:96

; DI u32 pack2(float a, float b) { f2_t v = {a, b}; bf2_t r = __builtin_convertvector(v, bf2_t); return __builtin_bit_cast(u32, r); }
; DI float bflo(u32 v) { return __uint_as_float(v << 16); }
; DI float bfhi(u32 v) { return __uint_as_float(v & 0xffff0000u); }
; DI float sigmoidf_(float x) { return __builtin_amdgcn_rcpf(1.f + __builtin_amdgcn_exp2f(-LOG2E * x)); }
; DI void resid_store8(const f32x4v (&acc)[2][2][4][2], const float* xin, float* xout, u16* xb, float* ssp, int m0, int n0, bool wr_norm = true) {
;     ...
;         for (int m = 0; m < 4; ++m) {
;           const size_t off = (size_t)row * 1024 + cb + m * 16 + fq * 4;
;           f32x4 v = *(const f32x4*)(xin + off);
;           f32x4v a = acc[ai][bj][m][n];
;           v.x += a.x; v.y += a.y; v.z += a.z; v.w += a.w;
;           *(f32x4*)(xout + off) = v;
;           ss += v.x * v.x + v.y * v.y + v.z * v.z + v.w * v.w;
;           if (wr_norm) { u32x2 o2; o2.x = pack2(v.x, v.y); o2.y = pack2(v.z, v.w); *(u32x2*)(xb + off) = o2; }
; DI void ple_tile8(const WsPtrs& W, int layer, float* x, int mt, int nt, unsigned char* smem, bool feed_next) {
;     ...
;           for (int m = 0; m < 4; ++m) {
;             const u32x2 pv = *(const u32x2*)(pp + ai * 128 + m * 16);
;             f32x4v a = acc[ai][bj][m][n];
;             a.x = sigmoidf_(a.x * rv) * bflo(pv.x); a.y = sigmoidf_(a.y * rv) * bfhi(pv.x);
;             a.z = sigmoidf_(a.z * rv) * bflo(pv.y); a.w = sigmoidf_(a.w * rv) * bfhi(pv.y);
;             acc[ai][bj][m][n] = a;
.LBB0_1099:
	s_or_b64 exec, exec, s[12:13]
	v_readlane_b32 s12, v254, 60
	v_lshl_add_u64 v[90:91], v[100:101], 0, v[116:117]
	v_readlane_b32 s13, v254, 61
	v_mul_f32_e32 v92, v78, v204
	v_mul_f32_e32 v93, v79, v204
	s_waitcnt lgkmcnt(0)
	v_lshl_add_u64 v[84:85], v[90:91], 2, s[12:13]
	global_load_dwordx4 v[86:89], v[84:85], off
	global_load_dwordx4 v[216:219], v[84:85], off offset:64
	global_load_dwordx4 v[220:223], v[84:85], off offset:128
	global_load_dwordx4 v[224:227], v[84:85], off offset:192
	v_mul_f32_e32 v94, v80, v204
	v_mul_f32_e32 v81, v81, v204
	v_mul_f32_e32 v92, 0xbfb8aa3b, v92
	v_mul_f32_e32 v93, 0xbfb8aa3b, v93
	v_mul_f32_e32 v94, 0xbfb8aa3b, v94
	v_mul_f32_e32 v81, 0xbfb8aa3b, v81
	v_exp_f32_e32 v92, v92
	v_exp_f32_e32 v93, v93
	v_exp_f32_e32 v94, v94
	v_exp_f32_e32 v81, v81
	v_add_f32_e32 v92, 1.0, v92
	v_add_f32_e32 v93, 1.0, v93
	v_add_f32_e32 v94, 1.0, v94
	v_add_f32_e32 v81, 1.0, v81
	v_rcp_f32_e32 v92, v92
	v_rcp_f32_e32 v93, v93
	v_rcp_f32_e32 v94, v94
	v_rcp_f32_e32 v95, v81
	v_lshlrev_b32_e32 v78, 16, v172
	v_and_b32_e32 v79, 0xffff0000, v172
	v_lshlrev_b32_e32 v80, 16, v173
	v_and_b32_e32 v81, 0xffff0000, v173
	s_and_b64 vcc, exec, s[4:5]
	s_waitcnt vmcnt(3)
	v_pk_fma_f32 v[78:79], v[92:93], v[78:79], v[86:87]
	v_pk_fma_f32 v[80:81], v[94:95], v[80:81], v[88:89]
	v_lshl_add_u64 v[86:87], v[90:91], 1, s[6:7]
	global_store_dwordx4 v[84:85], v[78:81], off
	s_cbranch_vccnz .LBB0_1101
	v_cvt_pk_bf16_f32 v88, v78, v79
	v_cvt_pk_bf16_f32 v89, v80, v81
	global_store_dwordx2 v[86:87], v[88:89], off
.LBB0_1101:
	s_nop 0
	v_mul_f32_e32 v92, v74, v204
	v_mul_f32_e32 v93, v75, v204
	v_mul_f32_e32 v76, v76, v204
	v_mul_f32_e32 v77, v77, v204
	v_mul_f32_e32 v92, 0xbfb8aa3b, v92
	v_mul_f32_e32 v93, 0xbfb8aa3b, v93
	v_mul_f32_e32 v76, 0xbfb8aa3b, v76
	v_mul_f32_e32 v77, 0xbfb8aa3b, v77
	v_exp_f32_e32 v92, v92
	v_exp_f32_e32 v93, v93
	v_exp_f32_e32 v76, v76
	v_exp_f32_e32 v77, v77
	v_add_f32_e32 v92, 1.0, v92
	v_add_f32_e32 v93, 1.0, v93
	v_add_f32_e32 v94, 1.0, v76
	v_add_f32_e32 v95, 1.0, v77
	v_rcp_f32_e32 v76, v92
	v_rcp_f32_e32 v77, v93
	v_rcp_f32_e32 v92, v94
	v_rcp_f32_e32 v93, v95
	v_lshlrev_b32_e32 v74, 16, v170
	v_and_b32_e32 v75, 0xffff0000, v170
	v_lshlrev_b32_e32 v94, 16, v171
	v_and_b32_e32 v95, 0xffff0000, v171
	s_and_b64 vcc, exec, s[4:5]
	s_waitcnt vmcnt(3)
	v_pk_fma_f32 v[74:75], v[76:77], v[74:75], v[216:217]
	v_pk_fma_f32 v[76:77], v[92:93], v[94:95], v[218:219]
	global_store_dwordx4 v[84:85], v[74:77], off offset:64
	s_cbranch_vccnz .LBB0_1103
	v_cvt_pk_bf16_f32 v88, v74, v75
	v_cvt_pk_bf16_f32 v89, v76, v77
	global_store_dwordx2 v[86:87], v[88:89], off offset:32
.LBB0_1103:
	s_nop 0
	v_mul_f32_e32 v92, v70, v204
	v_mul_f32_e32 v93, v71, v204
	v_mul_f32_e32 v72, v72, v204
	v_mul_f32_e32 v73, v73, v204
	v_mul_f32_e32 v92, 0xbfb8aa3b, v92
	v_mul_f32_e32 v93, 0xbfb8aa3b, v93
	v_mul_f32_e32 v72, 0xbfb8aa3b, v72
	v_mul_f32_e32 v73, 0xbfb8aa3b, v73
	v_exp_f32_e32 v92, v92
	v_exp_f32_e32 v93, v93
	v_exp_f32_e32 v72, v72
	v_exp_f32_e32 v73, v73
	v_add_f32_e32 v92, 1.0, v92
	v_add_f32_e32 v93, 1.0, v93
	v_add_f32_e32 v94, 1.0, v72
	v_add_f32_e32 v95, 1.0, v73
	v_rcp_f32_e32 v72, v92
	v_rcp_f32_e32 v73, v93
	v_rcp_f32_e32 v92, v94
	v_rcp_f32_e32 v93, v95
	v_lshlrev_b32_e32 v70, 16, v168
	v_and_b32_e32 v71, 0xffff0000, v168
	v_lshlrev_b32_e32 v94, 16, v169
	v_and_b32_e32 v95, 0xffff0000, v169
	s_and_b64 vcc, exec, s[4:5]
	s_waitcnt vmcnt(3)
	v_pk_fma_f32 v[70:71], v[72:73], v[70:71], v[220:221]
	v_pk_fma_f32 v[72:73], v[92:93], v[94:95], v[222:223]
	global_store_dwordx4 v[84:85], v[70:73], off offset:128
	s_cbranch_vccnz .LBB0_1105
	v_cvt_pk_bf16_f32 v88, v70, v71
	v_cvt_pk_bf16_f32 v89, v72, v73
	global_store_dwordx2 v[86:87], v[88:89], off offset:64
.LBB0_1105:
	s_nop 0
	v_mul_f32_e32 v92, v66, v204
	v_mul_f32_e32 v93, v67, v204
	v_mul_f32_e32 v68, v68, v204
	v_mul_f32_e32 v69, v69, v204
	v_mul_f32_e32 v92, 0xbfb8aa3b, v92
	v_mul_f32_e32 v93, 0xbfb8aa3b, v93
	v_mul_f32_e32 v68, 0xbfb8aa3b, v68
	v_mul_f32_e32 v69, 0xbfb8aa3b, v69
	v_exp_f32_e32 v92, v92
	v_exp_f32_e32 v93, v93
	v_exp_f32_e32 v68, v68
	v_exp_f32_e32 v69, v69
	v_add_f32_e32 v92, 1.0, v92
	v_add_f32_e32 v93, 1.0, v93
	v_add_f32_e32 v94, 1.0, v68
	v_add_f32_e32 v95, 1.0, v69
	v_rcp_f32_e32 v68, v92
	v_rcp_f32_e32 v69, v93
	v_rcp_f32_e32 v92, v94
	v_rcp_f32_e32 v93, v95
	v_lshlrev_b32_e32 v66, 16, v166
	v_and_b32_e32 v67, 0xffff0000, v166
	v_lshlrev_b32_e32 v94, 16, v167
	v_and_b32_e32 v95, 0xffff0000, v167
	s_and_b64 vcc, exec, s[4:5]
	s_waitcnt vmcnt(3)
	v_pk_fma_f32 v[66:67], v[68:69], v[66:67], v[224:225]
	v_pk_fma_f32 v[68:69], v[92:93], v[94:95], v[226:227]
	global_store_dwordx4 v[84:85], v[66:69], off offset:192
	s_cbranch_vccnz .LBB0_1107
	v_cvt_pk_bf16_f32 v84, v66, v67
	v_cvt_pk_bf16_f32 v85, v68, v69
	global_store_dwordx2 v[86:87], v[84:85], off offset:96

; DI u32 pack2(float a, float b) { f2_t v = {a, b}; bf2_t r = __builtin_convertvector(v, bf2_t); return __builtin_bit_cast(u32, r); }
; DI float bflo(u32 v) { return __uint_as_float(v << 16); }
; DI float bfhi(u32 v) { return __uint_as_float(v & 0xffff0000u); }
; DI float sigmoidf_(float x) { return __builtin_amdgcn_rcpf(1.f + __builtin_amdgcn_exp2f(-LOG2E * x)); }
; DI void resid_store8(const f32x4v (&acc)[2][2][4][2], const float* xin, float* xout, u16* xb, float* ssp, int m0, int n0, bool wr_norm = true) {
;     ...
;         for (int m = 0; m < 4; ++m) {
;           const size_t off = (size_t)row * 1024 + cb + m * 16 + fq * 4;
;           f32x4 v = *(const f32x4*)(xin + off);
;           f32x4v a = acc[ai][bj][m][n];
;           v.x += a.x; v.y += a.y; v.z += a.z; v.w += a.w;
;           *(f32x4*)(xout + off) = v;
;           ss += v.x * v.x + v.y * v.y + v.z * v.z + v.w * v.w;
;           if (wr_norm) { u32x2 o2; o2.x = pack2(v.x, v.y); o2.y = pack2(v.z, v.w); *(u32x2*)(xb + off) = o2; }
; DI void ple_tile8(const WsPtrs& W, int layer, float* x, int mt, int nt, unsigned char* smem, bool feed_next) {
;     ...
;           for (int m = 0; m < 4; ++m) {
;             const u32x2 pv = *(const u32x2*)(pp + ai * 128 + m * 16);
;             f32x4v a = acc[ai][bj][m][n];
;             a.x = sigmoidf_(a.x * rv) * bflo(pv.x); a.y = sigmoidf_(a.y * rv) * bfhi(pv.x);
;             a.z = sigmoidf_(a.z * rv) * bflo(pv.y); a.w = sigmoidf_(a.w * rv) * bfhi(pv.y);
;             acc[ai][bj][m][n] = a;
.LBB0_1109:
	s_or_b64 exec, exec, s[12:13]
	v_or_b32_e32 v68, 0x80, v148
	v_ashrrev_i32_e32 v69, 31, v68
	s_waitcnt lgkmcnt(0)
	v_lshlrev_b64 v[66:67], 10, v[68:69]
	v_or_b32_e32 v66, v66, v202
	v_readlane_b32 s12, v254, 60
	v_lshl_add_u64 v[76:77], v[66:67], 0, v[146:147]
	v_readlane_b32 s13, v254, 61
	v_mul_f32_e32 v78, v62, v203
	v_mul_f32_e32 v79, v63, v203
	v_lshl_add_u64 v[70:71], v[76:77], 2, s[12:13]
	global_load_dwordx4 v[72:75], v[70:71], off
	global_load_dwordx4 v[216:219], v[70:71], off offset:64
	global_load_dwordx4 v[220:223], v[70:71], off offset:128
	global_load_dwordx4 v[224:227], v[70:71], off offset:192
	v_mul_f32_e32 v80, v64, v203
	v_mul_f32_e32 v65, v65, v203
	v_mul_f32_e32 v78, 0xbfb8aa3b, v78
	v_mul_f32_e32 v79, 0xbfb8aa3b, v79
	v_mul_f32_e32 v80, 0xbfb8aa3b, v80
	v_mul_f32_e32 v65, 0xbfb8aa3b, v65
	v_exp_f32_e32 v78, v78
	v_exp_f32_e32 v79, v79
	v_exp_f32_e32 v80, v80
	v_exp_f32_e32 v65, v65
	v_add_f32_e32 v78, 1.0, v78
	v_add_f32_e32 v79, 1.0, v79
	v_add_f32_e32 v80, 1.0, v80
	v_add_f32_e32 v65, 1.0, v65
	v_rcp_f32_e32 v78, v78
	v_rcp_f32_e32 v79, v79
	v_rcp_f32_e32 v80, v80
	v_rcp_f32_e32 v81, v65
	v_lshlrev_b32_e32 v62, 16, v164
	v_and_b32_e32 v63, 0xffff0000, v164
	v_lshlrev_b32_e32 v64, 16, v165
	v_and_b32_e32 v65, 0xffff0000, v165
	s_and_b64 vcc, exec, s[4:5]
	s_waitcnt vmcnt(3)
	v_pk_fma_f32 v[62:63], v[78:79], v[62:63], v[72:73]
	v_pk_fma_f32 v[64:65], v[80:81], v[64:65], v[74:75]
	v_lshl_add_u64 v[72:73], v[76:77], 1, s[6:7]
	global_store_dwordx4 v[70:71], v[62:65], off
	s_cbranch_vccnz .LBB0_1111
	v_cvt_pk_bf16_f32 v74, v62, v63
	v_cvt_pk_bf16_f32 v75, v64, v65
	global_store_dwordx2 v[72:73], v[74:75], off
.LBB0_1111:
	s_nop 0
	v_mul_f32_e32 v78, v58, v203
	v_mul_f32_e32 v79, v59, v203
	v_mul_f32_e32 v60, v60, v203
	v_mul_f32_e32 v61, v61, v203
	v_mul_f32_e32 v78, 0xbfb8aa3b, v78
	v_mul_f32_e32 v79, 0xbfb8aa3b, v79
	v_mul_f32_e32 v60, 0xbfb8aa3b, v60
	v_mul_f32_e32 v61, 0xbfb8aa3b, v61
	v_exp_f32_e32 v78, v78
	v_exp_f32_e32 v79, v79
	v_exp_f32_e32 v60, v60
	v_exp_f32_e32 v61, v61
	v_add_f32_e32 v78, 1.0, v78
	v_add_f32_e32 v79, 1.0, v79
	v_add_f32_e32 v80, 1.0, v60
	v_add_f32_e32 v81, 1.0, v61
	v_rcp_f32_e32 v60, v78
	v_rcp_f32_e32 v61, v79
	v_rcp_f32_e32 v78, v80
	v_rcp_f32_e32 v79, v81
	v_lshlrev_b32_e32 v58, 16, v162
	v_and_b32_e32 v59, 0xffff0000, v162
	v_lshlrev_b32_e32 v80, 16, v163
	v_and_b32_e32 v81, 0xffff0000, v163
	s_and_b64 vcc, exec, s[4:5]
	s_waitcnt vmcnt(3)
	v_pk_fma_f32 v[58:59], v[60:61], v[58:59], v[216:217]
	v_pk_fma_f32 v[60:61], v[78:79], v[80:81], v[218:219]
	global_store_dwordx4 v[70:71], v[58:61], off offset:64
	s_cbranch_vccnz .LBB0_1113
	v_cvt_pk_bf16_f32 v74, v58, v59
	v_cvt_pk_bf16_f32 v75, v60, v61
	global_store_dwordx2 v[72:73], v[74:75], off offset:32
.LBB0_1113:
	s_nop 0
	v_mul_f32_e32 v78, v54, v203
	v_mul_f32_e32 v79, v55, v203
	v_mul_f32_e32 v56, v56, v203
	v_mul_f32_e32 v57, v57, v203
	v_mul_f32_e32 v78, 0xbfb8aa3b, v78
	v_mul_f32_e32 v79, 0xbfb8aa3b, v79
	v_mul_f32_e32 v56, 0xbfb8aa3b, v56
	v_mul_f32_e32 v57, 0xbfb8aa3b, v57
	v_exp_f32_e32 v78, v78
	v_exp_f32_e32 v79, v79
	v_exp_f32_e32 v56, v56
	v_exp_f32_e32 v57, v57
	v_add_f32_e32 v78, 1.0, v78
	v_add_f32_e32 v79, 1.0, v79
	v_add_f32_e32 v80, 1.0, v56
	v_add_f32_e32 v81, 1.0, v57
	v_rcp_f32_e32 v56, v78
	v_rcp_f32_e32 v57, v79
	v_rcp_f32_e32 v78, v80
	v_rcp_f32_e32 v79, v81
	v_lshlrev_b32_e32 v54, 16, v160
	v_and_b32_e32 v55, 0xffff0000, v160
	v_lshlrev_b32_e32 v80, 16, v161
	v_and_b32_e32 v81, 0xffff0000, v161
	s_and_b64 vcc, exec, s[4:5]
	s_waitcnt vmcnt(3)
	v_pk_fma_f32 v[54:55], v[56:57], v[54:55], v[220:221]
	v_pk_fma_f32 v[56:57], v[78:79], v[80:81], v[222:223]
	global_store_dwordx4 v[70:71], v[54:57], off offset:128
	s_cbranch_vccnz .LBB0_1115
	v_cvt_pk_bf16_f32 v74, v54, v55
	v_cvt_pk_bf16_f32 v75, v56, v57
	global_store_dwordx2 v[72:73], v[74:75], off offset:64
.LBB0_1115:
	s_nop 0
	v_mul_f32_e32 v78, v50, v203
	v_mul_f32_e32 v79, v51, v203
	v_mul_f32_e32 v52, v52, v203
	v_mul_f32_e32 v53, v53, v203
	v_mul_f32_e32 v78, 0xbfb8aa3b, v78
	v_mul_f32_e32 v79, 0xbfb8aa3b, v79
	v_mul_f32_e32 v52, 0xbfb8aa3b, v52
	v_mul_f32_e32 v53, 0xbfb8aa3b, v53
	v_exp_f32_e32 v78, v78
	v_exp_f32_e32 v79, v79
	v_exp_f32_e32 v52, v52
	v_exp_f32_e32 v53, v53
	v_add_f32_e32 v78, 1.0, v78
	v_add_f32_e32 v79, 1.0, v79
	v_add_f32_e32 v80, 1.0, v52
	v_add_f32_e32 v81, 1.0, v53
	v_rcp_f32_e32 v52, v78
	v_rcp_f32_e32 v53, v79
	v_rcp_f32_e32 v78, v80
	v_rcp_f32_e32 v79, v81
	v_lshlrev_b32_e32 v50, 16, v158
	v_and_b32_e32 v51, 0xffff0000, v158
	v_lshlrev_b32_e32 v80, 16, v159
	v_and_b32_e32 v81, 0xffff0000, v159
	s_and_b64 vcc, exec, s[4:5]
	s_waitcnt vmcnt(3)
	v_pk_fma_f32 v[50:51], v[52:53], v[50:51], v[224:225]
	v_pk_fma_f32 v[52:53], v[78:79], v[80:81], v[226:227]
	global_store_dwordx4 v[70:71], v[50:53], off offset:192
	s_cbranch_vccnz .LBB0_1117
	v_cvt_pk_bf16_f32 v70, v50, v51
	v_cvt_pk_bf16_f32 v71, v52, v53
	global_store_dwordx2 v[72:73], v[70:71], off offset:96

; DI u32 pack2(float a, float b) { f2_t v = {a, b}; bf2_t r = __builtin_convertvector(v, bf2_t); return __builtin_bit_cast(u32, r); }
; DI float bflo(u32 v) { return __uint_as_float(v << 16); }
; DI float bfhi(u32 v) { return __uint_as_float(v & 0xffff0000u); }
; DI float sigmoidf_(float x) { return __builtin_amdgcn_rcpf(1.f + __builtin_amdgcn_exp2f(-LOG2E * x)); }
; DI void resid_store8(const f32x4v (&acc)[2][2][4][2], const float* xin, float* xout, u16* xb, float* ssp, int m0, int n0, bool wr_norm = true) {
;     ...
;         for (int m = 0; m < 4; ++m) {
;           const size_t off = (size_t)row * 1024 + cb + m * 16 + fq * 4;
;           f32x4 v = *(const f32x4*)(xin + off);
;           f32x4v a = acc[ai][bj][m][n];
;           v.x += a.x; v.y += a.y; v.z += a.z; v.w += a.w;
;           *(f32x4*)(xout + off) = v;
;           ss += v.x * v.x + v.y * v.y + v.z * v.z + v.w * v.w;
;           if (wr_norm) { u32x2 o2; o2.x = pack2(v.x, v.y); o2.y = pack2(v.z, v.w); *(u32x2*)(xb + off) = o2; }
; DI void ple_tile8(const WsPtrs& W, int layer, float* x, int mt, int nt, unsigned char* smem, bool feed_next) {
;     ...
;           for (int m = 0; m < 4; ++m) {
;             const u32x2 pv = *(const u32x2*)(pp + ai * 128 + m * 16);
;             f32x4v a = acc[ai][bj][m][n];
;             a.x = sigmoidf_(a.x * rv) * bflo(pv.x); a.y = sigmoidf_(a.y * rv) * bfhi(pv.x);
;             a.z = sigmoidf_(a.z * rv) * bflo(pv.y); a.w = sigmoidf_(a.w * rv) * bfhi(pv.y);
;             acc[ai][bj][m][n] = a;
.LBB0_1119:
	s_or_b64 exec, exec, s[12:13]
	v_readlane_b32 s12, v254, 60
	v_lshl_add_u64 v[58:59], v[66:67], 0, v[116:117]
	v_readlane_b32 s13, v254, 61
	v_mul_f32_e32 v60, v46, v203
	v_mul_f32_e32 v61, v47, v203
	s_waitcnt lgkmcnt(0)
	v_lshl_add_u64 v[52:53], v[58:59], 2, s[12:13]
	global_load_dwordx4 v[54:57], v[52:53], off
	global_load_dwordx4 v[216:219], v[52:53], off offset:64
	global_load_dwordx4 v[220:223], v[52:53], off offset:128
	global_load_dwordx4 v[224:227], v[52:53], off offset:192
	v_mul_f32_e32 v62, v48, v203
	v_mul_f32_e32 v49, v49, v203
	v_mul_f32_e32 v60, 0xbfb8aa3b, v60
	v_mul_f32_e32 v61, 0xbfb8aa3b, v61
	v_mul_f32_e32 v62, 0xbfb8aa3b, v62
	v_mul_f32_e32 v49, 0xbfb8aa3b, v49
	v_exp_f32_e32 v60, v60
	v_exp_f32_e32 v61, v61
	v_exp_f32_e32 v62, v62
	v_exp_f32_e32 v49, v49
	v_add_f32_e32 v60, 1.0, v60
	v_add_f32_e32 v61, 1.0, v61
	v_add_f32_e32 v62, 1.0, v62
	v_add_f32_e32 v49, 1.0, v49
	v_rcp_f32_e32 v60, v60
	v_rcp_f32_e32 v61, v61
	v_rcp_f32_e32 v62, v62
	v_rcp_f32_e32 v63, v49
	v_lshlrev_b32_e32 v46, 16, v156
	v_and_b32_e32 v47, 0xffff0000, v156
	v_lshlrev_b32_e32 v48, 16, v157
	v_and_b32_e32 v49, 0xffff0000, v157
	s_and_b64 vcc, exec, s[4:5]
	s_waitcnt vmcnt(3)
	v_pk_fma_f32 v[46:47], v[60:61], v[46:47], v[54:55]
	v_pk_fma_f32 v[48:49], v[62:63], v[48:49], v[56:57]
	v_lshl_add_u64 v[54:55], v[58:59], 1, s[6:7]
	global_store_dwordx4 v[52:53], v[46:49], off
	s_cbranch_vccnz .LBB0_1121
	v_cvt_pk_bf16_f32 v56, v46, v47
	v_cvt_pk_bf16_f32 v57, v48, v49
	global_store_dwordx2 v[54:55], v[56:57], off
.LBB0_1121:
	s_nop 0
	v_mul_f32_e32 v60, v42, v203
	v_mul_f32_e32 v61, v43, v203
	v_mul_f32_e32 v44, v44, v203
	v_mul_f32_e32 v45, v45, v203
	v_mul_f32_e32 v60, 0xbfb8aa3b, v60
	v_mul_f32_e32 v61, 0xbfb8aa3b, v61
	v_mul_f32_e32 v44, 0xbfb8aa3b, v44
	v_mul_f32_e32 v45, 0xbfb8aa3b, v45
	v_exp_f32_e32 v60, v60
	v_exp_f32_e32 v61, v61
	v_exp_f32_e32 v44, v44
	v_exp_f32_e32 v45, v45
	v_add_f32_e32 v60, 1.0, v60
	v_add_f32_e32 v61, 1.0, v61
	v_add_f32_e32 v62, 1.0, v44
	v_add_f32_e32 v63, 1.0, v45
	v_rcp_f32_e32 v44, v60
	v_rcp_f32_e32 v45, v61
	v_rcp_f32_e32 v60, v62
	v_rcp_f32_e32 v61, v63
	v_lshlrev_b32_e32 v42, 16, v154
	v_and_b32_e32 v43, 0xffff0000, v154
	v_lshlrev_b32_e32 v62, 16, v155
	v_and_b32_e32 v63, 0xffff0000, v155
	s_and_b64 vcc, exec, s[4:5]
	s_waitcnt vmcnt(3)
	v_pk_fma_f32 v[42:43], v[44:45], v[42:43], v[216:217]
	v_pk_fma_f32 v[44:45], v[60:61], v[62:63], v[218:219]
	global_store_dwordx4 v[52:53], v[42:45], off offset:64
	s_cbranch_vccnz .LBB0_1123
	v_cvt_pk_bf16_f32 v56, v42, v43
	v_cvt_pk_bf16_f32 v57, v44, v45
	global_store_dwordx2 v[54:55], v[56:57], off offset:32
.LBB0_1123:
	s_nop 0
	v_mul_f32_e32 v60, v38, v203
	v_mul_f32_e32 v61, v39, v203
	v_mul_f32_e32 v40, v40, v203
	v_mul_f32_e32 v41, v41, v203
	v_mul_f32_e32 v60, 0xbfb8aa3b, v60
	v_mul_f32_e32 v61, 0xbfb8aa3b, v61
	v_mul_f32_e32 v40, 0xbfb8aa3b, v40
	v_mul_f32_e32 v41, 0xbfb8aa3b, v41
	v_exp_f32_e32 v60, v60
	v_exp_f32_e32 v61, v61
	v_exp_f32_e32 v40, v40
	v_exp_f32_e32 v41, v41
	v_add_f32_e32 v60, 1.0, v60
	v_add_f32_e32 v61, 1.0, v61
	v_add_f32_e32 v62, 1.0, v40
	v_add_f32_e32 v63, 1.0, v41
	v_rcp_f32_e32 v40, v60
	v_rcp_f32_e32 v41, v61
	v_rcp_f32_e32 v60, v62
	v_rcp_f32_e32 v61, v63
	v_lshlrev_b32_e32 v38, 16, v152
	v_and_b32_e32 v39, 0xffff0000, v152
	v_lshlrev_b32_e32 v62, 16, v153
	v_and_b32_e32 v63, 0xffff0000, v153
	s_and_b64 vcc, exec, s[4:5]
	s_waitcnt vmcnt(3)
	v_pk_fma_f32 v[38:39], v[40:41], v[38:39], v[220:221]
	v_pk_fma_f32 v[40:41], v[60:61], v[62:63], v[222:223]
	global_store_dwordx4 v[52:53], v[38:41], off offset:128
	s_cbranch_vccnz .LBB0_1125
	v_cvt_pk_bf16_f32 v56, v38, v39
	v_cvt_pk_bf16_f32 v57, v40, v41
	global_store_dwordx2 v[54:55], v[56:57], off offset:64
.LBB0_1125:
	s_nop 0
	v_mul_f32_e32 v60, v34, v203
	v_mul_f32_e32 v61, v35, v203
	v_mul_f32_e32 v36, v36, v203
	v_mul_f32_e32 v37, v37, v203
	v_mul_f32_e32 v60, 0xbfb8aa3b, v60
	v_mul_f32_e32 v61, 0xbfb8aa3b, v61
	v_mul_f32_e32 v36, 0xbfb8aa3b, v36
	v_mul_f32_e32 v37, 0xbfb8aa3b, v37
	v_exp_f32_e32 v60, v60
	v_exp_f32_e32 v61, v61
	v_exp_f32_e32 v36, v36
	v_exp_f32_e32 v37, v37
	v_add_f32_e32 v60, 1.0, v60
	v_add_f32_e32 v61, 1.0, v61
	v_add_f32_e32 v62, 1.0, v36
	v_add_f32_e32 v63, 1.0, v37
	v_rcp_f32_e32 v36, v60
	v_rcp_f32_e32 v37, v61
	v_rcp_f32_e32 v60, v62
	v_rcp_f32_e32 v61, v63
	v_lshlrev_b32_e32 v34, 16, v150
	v_and_b32_e32 v35, 0xffff0000, v150
	v_lshlrev_b32_e32 v62, 16, v151
	v_and_b32_e32 v63, 0xffff0000, v151
	s_and_b64 vcc, exec, s[4:5]
	s_waitcnt vmcnt(3)
	v_pk_fma_f32 v[34:35], v[36:37], v[34:35], v[224:225]
	v_pk_fma_f32 v[36:37], v[60:61], v[62:63], v[226:227]
	global_store_dwordx4 v[52:53], v[34:37], off offset:192
	s_cbranch_vccnz .LBB0_1127
	v_cvt_pk_bf16_f32 v52, v34, v35
	v_cvt_pk_bf16_f32 v53, v36, v37
	global_store_dwordx2 v[54:55], v[52:53], off offset:96

; DI u32 pack2(float a, float b) { f2_t v = {a, b}; bf2_t r = __builtin_convertvector(v, bf2_t); return __builtin_bit_cast(u32, r); }
; DI float bflo(u32 v) { return __uint_as_float(v << 16); }
; DI float bfhi(u32 v) { return __uint_as_float(v & 0xffff0000u); }
; DI float sigmoidf_(float x) { return __builtin_amdgcn_rcpf(1.f + __builtin_amdgcn_exp2f(-LOG2E * x)); }
; DI void resid_store8(const f32x4v (&acc)[2][2][4][2], const float* xin, float* xout, u16* xb, float* ssp, int m0, int n0, bool wr_norm = true) {
;     ...
;         for (int m = 0; m < 4; ++m) {
;           const size_t off = (size_t)row * 1024 + cb + m * 16 + fq * 4;
;           f32x4 v = *(const f32x4*)(xin + off);
;           f32x4v a = acc[ai][bj][m][n];
;           v.x += a.x; v.y += a.y; v.z += a.z; v.w += a.w;
;           *(f32x4*)(xout + off) = v;
;           ss += v.x * v.x + v.y * v.y + v.z * v.z + v.w * v.w;
;           if (wr_norm) { u32x2 o2; o2.x = pack2(v.x, v.y); o2.y = pack2(v.z, v.w); *(u32x2*)(xb + off) = o2; }
; DI void ple_tile8(const WsPtrs& W, int layer, float* x, int mt, int nt, unsigned char* smem, bool feed_next) {
;     ...
;           for (int m = 0; m < 4; ++m) {
;             const u32x2 pv = *(const u32x2*)(pp + ai * 128 + m * 16);
;             f32x4v a = acc[ai][bj][m][n];
;             a.x = sigmoidf_(a.x * rv) * bflo(pv.x); a.y = sigmoidf_(a.y * rv) * bfhi(pv.x);
;             a.z = sigmoidf_(a.z * rv) * bflo(pv.y); a.w = sigmoidf_(a.w * rv) * bfhi(pv.y);
;             acc[ai][bj][m][n] = a;
.LBB0_1129:
	s_or_b64 exec, exec, s[12:13]
	v_or_b32_e32 v36, 0x90, v148
	v_ashrrev_i32_e32 v37, 31, v36
	s_waitcnt lgkmcnt(0)
	v_lshlrev_b64 v[34:35], 10, v[36:37]
	v_or_b32_e32 v34, v34, v202
	v_readlane_b32 s12, v254, 60
	v_lshl_add_u64 v[44:45], v[34:35], 0, v[146:147]
	v_readlane_b32 s13, v254, 61
	v_mul_f32_e32 v46, v30, v0
	v_mul_f32_e32 v47, v31, v0
	v_lshl_add_u64 v[38:39], v[44:45], 2, s[12:13]
	global_load_dwordx4 v[40:43], v[38:39], off
	global_load_dwordx4 v[216:219], v[38:39], off offset:64
	global_load_dwordx4 v[220:223], v[38:39], off offset:128
	global_load_dwordx4 v[224:227], v[38:39], off offset:192
	v_mul_f32_e32 v48, v32, v0
	v_mul_f32_e32 v33, v33, v0
	v_mul_f32_e32 v46, 0xbfb8aa3b, v46
	v_mul_f32_e32 v47, 0xbfb8aa3b, v47
	v_mul_f32_e32 v48, 0xbfb8aa3b, v48
	v_mul_f32_e32 v33, 0xbfb8aa3b, v33
	v_exp_f32_e32 v46, v46
	v_exp_f32_e32 v47, v47
	v_exp_f32_e32 v48, v48
	v_exp_f32_e32 v33, v33
	v_add_f32_e32 v46, 1.0, v46
	v_add_f32_e32 v47, 1.0, v47
	v_add_f32_e32 v48, 1.0, v48
	v_add_f32_e32 v33, 1.0, v33
	v_rcp_f32_e32 v46, v46
	v_rcp_f32_e32 v47, v47
	v_rcp_f32_e32 v48, v48
	v_rcp_f32_e32 v49, v33
	v_lshlrev_b32_e32 v30, 16, v144
	v_and_b32_e32 v31, 0xffff0000, v144
	v_lshlrev_b32_e32 v32, 16, v145
	v_and_b32_e32 v33, 0xffff0000, v145
	s_and_b64 vcc, exec, s[4:5]
	s_waitcnt vmcnt(3)
	v_pk_fma_f32 v[30:31], v[46:47], v[30:31], v[40:41]
	v_pk_fma_f32 v[32:33], v[48:49], v[32:33], v[42:43]
	v_lshl_add_u64 v[40:41], v[44:45], 1, s[6:7]
	global_store_dwordx4 v[38:39], v[30:33], off
	s_cbranch_vccnz .LBB0_1131
	v_cvt_pk_bf16_f32 v42, v30, v31
	v_cvt_pk_bf16_f32 v43, v32, v33
	global_store_dwordx2 v[40:41], v[42:43], off
.LBB0_1131:
	s_nop 0
	v_mul_f32_e32 v46, v26, v0
	v_mul_f32_e32 v47, v27, v0
	v_mul_f32_e32 v28, v28, v0
	v_mul_f32_e32 v29, v29, v0
	v_mul_f32_e32 v46, 0xbfb8aa3b, v46
	v_mul_f32_e32 v47, 0xbfb8aa3b, v47
	v_mul_f32_e32 v28, 0xbfb8aa3b, v28
	v_mul_f32_e32 v29, 0xbfb8aa3b, v29
	v_exp_f32_e32 v46, v46
	v_exp_f32_e32 v47, v47
	v_exp_f32_e32 v28, v28
	v_exp_f32_e32 v29, v29
	v_add_f32_e32 v46, 1.0, v46
	v_add_f32_e32 v47, 1.0, v47
	v_add_f32_e32 v48, 1.0, v28
	v_add_f32_e32 v49, 1.0, v29
	v_rcp_f32_e32 v28, v46
	v_rcp_f32_e32 v29, v47
	v_rcp_f32_e32 v46, v48
	v_rcp_f32_e32 v47, v49
	v_lshlrev_b32_e32 v26, 16, v142
	v_and_b32_e32 v27, 0xffff0000, v142
	v_lshlrev_b32_e32 v48, 16, v143
	v_and_b32_e32 v49, 0xffff0000, v143
	s_and_b64 vcc, exec, s[4:5]
	s_waitcnt vmcnt(3)
	v_pk_fma_f32 v[26:27], v[28:29], v[26:27], v[216:217]
	v_pk_fma_f32 v[28:29], v[46:47], v[48:49], v[218:219]
	global_store_dwordx4 v[38:39], v[26:29], off offset:64
	s_cbranch_vccnz .LBB0_1133
	v_cvt_pk_bf16_f32 v42, v26, v27
	v_cvt_pk_bf16_f32 v43, v28, v29
	global_store_dwordx2 v[40:41], v[42:43], off offset:32
.LBB0_1133:
	s_nop 0
	v_mul_f32_e32 v46, v22, v0
	v_mul_f32_e32 v47, v23, v0
	v_mul_f32_e32 v24, v24, v0
	v_mul_f32_e32 v25, v25, v0
	v_mul_f32_e32 v46, 0xbfb8aa3b, v46
	v_mul_f32_e32 v47, 0xbfb8aa3b, v47
	v_mul_f32_e32 v24, 0xbfb8aa3b, v24
	v_mul_f32_e32 v25, 0xbfb8aa3b, v25
	v_exp_f32_e32 v46, v46
	v_exp_f32_e32 v47, v47
	v_exp_f32_e32 v24, v24
	v_exp_f32_e32 v25, v25
	v_add_f32_e32 v46, 1.0, v46
	v_add_f32_e32 v47, 1.0, v47
	v_add_f32_e32 v48, 1.0, v24
	v_add_f32_e32 v49, 1.0, v25
	v_rcp_f32_e32 v24, v46
	v_rcp_f32_e32 v25, v47
	v_rcp_f32_e32 v46, v48
	v_rcp_f32_e32 v47, v49
	v_lshlrev_b32_e32 v22, 16, v140
	v_and_b32_e32 v23, 0xffff0000, v140
	v_lshlrev_b32_e32 v48, 16, v141
	v_and_b32_e32 v49, 0xffff0000, v141
	s_and_b64 vcc, exec, s[4:5]
	s_waitcnt vmcnt(3)
	v_pk_fma_f32 v[22:23], v[24:25], v[22:23], v[220:221]
	v_pk_fma_f32 v[24:25], v[46:47], v[48:49], v[222:223]
	global_store_dwordx4 v[38:39], v[22:25], off offset:128
	s_cbranch_vccnz .LBB0_1135
	v_cvt_pk_bf16_f32 v42, v22, v23
	v_cvt_pk_bf16_f32 v43, v24, v25
	global_store_dwordx2 v[40:41], v[42:43], off offset:64
.LBB0_1135:
	s_nop 0
	v_mul_f32_e32 v46, v18, v0
	v_mul_f32_e32 v47, v19, v0
	v_mul_f32_e32 v20, v20, v0
	v_mul_f32_e32 v21, v21, v0
	v_mul_f32_e32 v46, 0xbfb8aa3b, v46
	v_mul_f32_e32 v47, 0xbfb8aa3b, v47
	v_mul_f32_e32 v20, 0xbfb8aa3b, v20
	v_mul_f32_e32 v21, 0xbfb8aa3b, v21
	v_exp_f32_e32 v46, v46
	v_exp_f32_e32 v47, v47
	v_exp_f32_e32 v20, v20
	v_exp_f32_e32 v21, v21
	v_add_f32_e32 v46, 1.0, v46
	v_add_f32_e32 v47, 1.0, v47
	v_add_f32_e32 v48, 1.0, v20
	v_add_f32_e32 v49, 1.0, v21
	v_rcp_f32_e32 v20, v46
	v_rcp_f32_e32 v21, v47
	v_rcp_f32_e32 v46, v48
	v_rcp_f32_e32 v47, v49
	v_lshlrev_b32_e32 v18, 16, v138
	v_and_b32_e32 v19, 0xffff0000, v138
	v_lshlrev_b32_e32 v48, 16, v139
	v_and_b32_e32 v49, 0xffff0000, v139
	s_and_b64 vcc, exec, s[4:5]
	s_waitcnt vmcnt(3)
	v_pk_fma_f32 v[18:19], v[20:21], v[18:19], v[224:225]
	v_pk_fma_f32 v[20:21], v[46:47], v[48:49], v[226:227]
	global_store_dwordx4 v[38:39], v[18:21], off offset:192
	s_cbranch_vccnz .LBB0_1137
	v_cvt_pk_bf16_f32 v38, v18, v19
	v_cvt_pk_bf16_f32 v39, v20, v21
	global_store_dwordx2 v[40:41], v[38:39], off offset:96

; DI u32 pack2(float a, float b) { f2_t v = {a, b}; bf2_t r = __builtin_convertvector(v, bf2_t); return __builtin_bit_cast(u32, r); }
; DI float bflo(u32 v) { return __uint_as_float(v << 16); }
; DI float bfhi(u32 v) { return __uint_as_float(v & 0xffff0000u); }
; DI float sigmoidf_(float x) { return __builtin_amdgcn_rcpf(1.f + __builtin_amdgcn_exp2f(-LOG2E * x)); }
; DI void resid_store8(const f32x4v (&acc)[2][2][4][2], const float* xin, float* xout, u16* xb, float* ssp, int m0, int n0, bool wr_norm = true) {
;     ...
;         for (int m = 0; m < 4; ++m) {
;           const size_t off = (size_t)row * 1024 + cb + m * 16 + fq * 4;
;           f32x4 v = *(const f32x4*)(xin + off);
;           f32x4v a = acc[ai][bj][m][n];
;           v.x += a.x; v.y += a.y; v.z += a.z; v.w += a.w;
;           *(f32x4*)(xout + off) = v;
;           ss += v.x * v.x + v.y * v.y + v.z * v.z + v.w * v.w;
;           if (wr_norm) { u32x2 o2; o2.x = pack2(v.x, v.y); o2.y = pack2(v.z, v.w); *(u32x2*)(xb + off) = o2; }
; DI void ple_tile8(const WsPtrs& W, int layer, float* x, int mt, int nt, unsigned char* smem, bool feed_next) {
;     ...
;           for (int m = 0; m < 4; ++m) {
;             const u32x2 pv = *(const u32x2*)(pp + ai * 128 + m * 16);
;             f32x4v a = acc[ai][bj][m][n];
;             a.x = sigmoidf_(a.x * rv) * bflo(pv.x); a.y = sigmoidf_(a.y * rv) * bfhi(pv.x);
;             a.z = sigmoidf_(a.z * rv) * bflo(pv.y); a.w = sigmoidf_(a.w * rv) * bfhi(pv.y);
;             acc[ai][bj][m][n] = a;
.LBB0_1139:
	s_or_b64 exec, exec, s[8:9]
	v_readlane_b32 s8, v254, 60
	v_lshl_add_u64 v[26:27], v[34:35], 0, v[116:117]
	v_readlane_b32 s9, v254, 61
	v_mul_f32_e32 v28, v14, v0
	v_mul_f32_e32 v29, v15, v0
	s_waitcnt lgkmcnt(0)
	v_lshl_add_u64 v[20:21], v[26:27], 2, s[8:9]
	global_load_dwordx4 v[22:25], v[20:21], off
	global_load_dwordx4 v[216:219], v[20:21], off offset:64
	global_load_dwordx4 v[220:223], v[20:21], off offset:128
	global_load_dwordx4 v[224:227], v[20:21], off offset:192
	v_mul_f32_e32 v30, v16, v0
	v_mul_f32_e32 v17, v17, v0
	v_mul_f32_e32 v28, 0xbfb8aa3b, v28
	v_mul_f32_e32 v29, 0xbfb8aa3b, v29
	v_mul_f32_e32 v30, 0xbfb8aa3b, v30
	v_mul_f32_e32 v17, 0xbfb8aa3b, v17
	v_exp_f32_e32 v28, v28
	v_exp_f32_e32 v29, v29
	v_exp_f32_e32 v30, v30
	v_exp_f32_e32 v17, v17
	v_add_f32_e32 v28, 1.0, v28
	v_add_f32_e32 v29, 1.0, v29
	v_add_f32_e32 v30, 1.0, v30
	v_add_f32_e32 v17, 1.0, v17
	v_rcp_f32_e32 v28, v28
	v_rcp_f32_e32 v29, v29
	v_rcp_f32_e32 v30, v30
	v_rcp_f32_e32 v31, v17
	v_lshlrev_b32_e32 v14, 16, v136
	v_and_b32_e32 v15, 0xffff0000, v136
	v_lshlrev_b32_e32 v16, 16, v137
	v_and_b32_e32 v17, 0xffff0000, v137
	s_and_b64 vcc, exec, s[4:5]
	s_waitcnt vmcnt(3)
	v_pk_fma_f32 v[14:15], v[28:29], v[14:15], v[22:23]
	v_pk_fma_f32 v[16:17], v[30:31], v[16:17], v[24:25]
	v_lshl_add_u64 v[22:23], v[26:27], 1, s[6:7]
	global_store_dwordx4 v[20:21], v[14:17], off
	s_cbranch_vccnz .LBB0_1141
	v_cvt_pk_bf16_f32 v24, v14, v15
	v_cvt_pk_bf16_f32 v25, v16, v17
	global_store_dwordx2 v[22:23], v[24:25], off
.LBB0_1141:
	s_nop 0
	v_mul_f32_e32 v28, v10, v0
	v_mul_f32_e32 v29, v11, v0
	v_mul_f32_e32 v12, v12, v0
	v_mul_f32_e32 v13, v13, v0
	v_mul_f32_e32 v28, 0xbfb8aa3b, v28
	v_mul_f32_e32 v29, 0xbfb8aa3b, v29
	v_mul_f32_e32 v12, 0xbfb8aa3b, v12
	v_mul_f32_e32 v13, 0xbfb8aa3b, v13
	v_exp_f32_e32 v28, v28
	v_exp_f32_e32 v29, v29
	v_exp_f32_e32 v12, v12
	v_exp_f32_e32 v13, v13
	v_add_f32_e32 v28, 1.0, v28
	v_add_f32_e32 v29, 1.0, v29
	v_add_f32_e32 v30, 1.0, v12
	v_add_f32_e32 v31, 1.0, v13
	v_rcp_f32_e32 v12, v28
	v_rcp_f32_e32 v13, v29
	v_rcp_f32_e32 v28, v30
	v_rcp_f32_e32 v29, v31
	v_lshlrev_b32_e32 v10, 16, v134
	v_and_b32_e32 v11, 0xffff0000, v134
	v_lshlrev_b32_e32 v30, 16, v135
	v_and_b32_e32 v31, 0xffff0000, v135
	s_and_b64 vcc, exec, s[4:5]
	s_waitcnt vmcnt(3)
	v_pk_fma_f32 v[10:11], v[12:13], v[10:11], v[216:217]
	v_pk_fma_f32 v[12:13], v[28:29], v[30:31], v[218:219]
	global_store_dwordx4 v[20:21], v[10:13], off offset:64
	s_cbranch_vccnz .LBB0_1143
	v_cvt_pk_bf16_f32 v24, v10, v11
	v_cvt_pk_bf16_f32 v25, v12, v13
	global_store_dwordx2 v[22:23], v[24:25], off offset:32
.LBB0_1143:
	s_nop 0
	v_mul_f32_e32 v28, v6, v0
	v_mul_f32_e32 v29, v7, v0
	v_mul_f32_e32 v8, v8, v0
	v_mul_f32_e32 v9, v9, v0
	v_mul_f32_e32 v28, 0xbfb8aa3b, v28
	v_mul_f32_e32 v29, 0xbfb8aa3b, v29
	v_mul_f32_e32 v8, 0xbfb8aa3b, v8
	v_mul_f32_e32 v9, 0xbfb8aa3b, v9
	v_exp_f32_e32 v28, v28
	v_exp_f32_e32 v29, v29
	v_exp_f32_e32 v8, v8
	v_exp_f32_e32 v9, v9
	v_add_f32_e32 v28, 1.0, v28
	v_add_f32_e32 v29, 1.0, v29
	v_add_f32_e32 v30, 1.0, v8
	v_add_f32_e32 v31, 1.0, v9
	v_rcp_f32_e32 v8, v28
	v_rcp_f32_e32 v9, v29
	v_rcp_f32_e32 v28, v30
	v_rcp_f32_e32 v29, v31
	v_lshlrev_b32_e32 v6, 16, v132
	v_and_b32_e32 v7, 0xffff0000, v132
	v_lshlrev_b32_e32 v30, 16, v133
	v_and_b32_e32 v31, 0xffff0000, v133
	s_and_b64 vcc, exec, s[4:5]
	s_waitcnt vmcnt(3)
	v_pk_fma_f32 v[6:7], v[8:9], v[6:7], v[220:221]
	v_pk_fma_f32 v[8:9], v[28:29], v[30:31], v[222:223]
	global_store_dwordx4 v[20:21], v[6:9], off offset:128
	s_cbranch_vccnz .LBB0_1145
	v_cvt_pk_bf16_f32 v24, v6, v7
	v_cvt_pk_bf16_f32 v25, v8, v9
	global_store_dwordx2 v[22:23], v[24:25], off offset:64
.LBB0_1145:
	s_nop 0
	v_mul_f32_e32 v28, v2, v0
	v_mul_f32_e32 v29, v3, v0
	v_mul_f32_e32 v4, v4, v0
	v_mul_f32_e32 v0, v5, v0
	v_mul_f32_e32 v5, 0xbfb8aa3b, v28
	v_mul_f32_e32 v28, 0xbfb8aa3b, v29
	v_mul_f32_e32 v4, 0xbfb8aa3b, v4
	v_mul_f32_e32 v0, 0xbfb8aa3b, v0
	v_exp_f32_e32 v5, v5
	v_exp_f32_e32 v28, v28
	v_exp_f32_e32 v4, v4
	v_exp_f32_e32 v0, v0
	v_add_f32_e32 v5, 1.0, v5
	v_add_f32_e32 v28, 1.0, v28
	v_add_f32_e32 v29, 1.0, v4
	v_add_f32_e32 v0, 1.0, v0
	v_rcp_f32_e32 v4, v5
	v_rcp_f32_e32 v5, v28
	v_rcp_f32_e32 v28, v29
	v_rcp_f32_e32 v29, v0
	v_lshlrev_b32_e32 v2, 16, v130
	v_and_b32_e32 v3, 0xffff0000, v130
	v_lshlrev_b32_e32 v30, 16, v131
	v_and_b32_e32 v31, 0xffff0000, v131
	s_and_b64 vcc, exec, s[4:5]
	s_waitcnt vmcnt(3)
	v_pk_fma_f32 v[2:3], v[4:5], v[2:3], v[224:225]
	v_pk_fma_f32 v[4:5], v[28:29], v[30:31], v[226:227]
	global_store_dwordx4 v[20:21], v[2:5], off offset:192
	s_cbranch_vccnz .LBB0_1147
	v_cvt_pk_bf16_f32 v20, v2, v3
	v_cvt_pk_bf16_f32 v21, v4, v5
	global_store_dwordx2 v[22:23], v[20:21], off offset:96
